# K-loop segment-tail rotation: post-MFMA scalar bookkeeping (next m0/address setup, loop counters, compare) moved after the closing barrier of each MFMA section
# baseline (speedup 1.0000x reference)
.LBB0_175:
	ds_read_b128 v[40:43], v234
	ds_read_b128 v[44:47], v234 offset:1024
	ds_read_b128 v[48:51], v234 offset:2048
	ds_read_b128 v[52:55], v234 offset:3072
	ds_read_b128 v[186:189], v234 offset:4096
	ds_read_b128 v[190:193], v234 offset:5120
	ds_read_b128 v[194:197], v234 offset:6144
	ds_read_b128 v[198:201], v234 offset:7168
	ds_read_b128 v[16:19], v233
	ds_read_b128 v[20:23], v233 offset:1024
	ds_read_b128 v[24:27], v233 offset:2048
	ds_read_b128 v[28:31], v233 offset:3072
	s_add_u32 s6, s4, 0xfffc0080
	s_addc_u32 s7, s5, -1
	s_cmp_eq_u32 s34, 12
	s_cselect_b32 s9, s10, s7
	s_cselect_b32 s8, s11, s6
	s_cselect_b32 s7, s25, s31
	s_cselect_b32 s6, s29, s30
	v_lshl_add_u64 v[202:203], s[4:5], 0, v[182:183]
	s_add_i32 m0, s92, 0xc000
	s_nop 0
	global_load_lds_dwordx4 v[202:203], off
	v_lshl_add_u64 v[202:203], s[4:5], 0, v[184:185]
	s_add_i32 m0, s92, 0xe000
	s_nop 0
	global_load_lds_dwordx4 v[202:203], off
	s_waitcnt lgkmcnt(0)
	s_barrier
	v_mfma_f32_16x16x32_bf16 v[156:159], v[16:19], v[40:43], v[156:159]
	v_mfma_f32_16x16x32_bf16 v[152:155], v[24:27], v[40:43], v[152:155]
	v_mfma_f32_16x16x32_bf16 v[140:143], v[16:19], v[48:51], v[140:143]
	v_mfma_f32_16x16x32_bf16 v[136:139], v[24:27], v[48:51], v[136:139]
	v_mfma_f32_16x16x32_bf16 v[124:127], v[16:19], v[186:189], v[124:127]
	v_mfma_f32_16x16x32_bf16 v[120:123], v[24:27], v[186:189], v[120:123]
	v_mfma_f32_16x16x32_bf16 v[108:111], v[16:19], v[194:197], v[108:111]
	v_mfma_f32_16x16x32_bf16 v[104:107], v[24:27], v[194:197], v[104:107]
	v_mfma_f32_16x16x32_bf16 v[156:159], v[20:23], v[44:47], v[156:159]
	v_mfma_f32_16x16x32_bf16 v[152:155], v[28:31], v[44:47], v[152:155]
	v_mfma_f32_16x16x32_bf16 v[140:143], v[20:23], v[52:55], v[140:143]
	v_mfma_f32_16x16x32_bf16 v[136:139], v[28:31], v[52:55], v[136:139]
	v_mfma_f32_16x16x32_bf16 v[124:127], v[20:23], v[190:193], v[124:127]
	v_mfma_f32_16x16x32_bf16 v[120:123], v[28:31], v[190:193], v[120:123]
	v_mfma_f32_16x16x32_bf16 v[108:111], v[20:23], v[198:201], v[108:111]
	v_mfma_f32_16x16x32_bf16 v[104:107], v[28:31], v[198:201], v[104:107]
	s_barrier
	s_add_i32 s35, s1, s33
	v_lshl_add_u64 v[218:219], s[6:7], 0, v[166:167]
	s_mov_b32 m0, s35
	ds_read_b128 v[202:205], v235
	ds_read_b128 v[206:209], v235 offset:1024
	ds_read_b128 v[210:213], v235 offset:2048
	ds_read_b128 v[214:217], v235 offset:3072
	global_load_lds_dwordx4 v[218:219], off
	v_lshl_add_u64 v[246:247], s[6:7], 0, v[162:163]
	s_add_i32 m0, s35, 0x2000
	s_nop 0
	global_load_lds_dwordx4 v[246:247], off
	s_barrier
	s_waitcnt lgkmcnt(0)
	v_mfma_f32_16x16x32_bf16 v[148:151], v[202:205], v[40:43], v[148:151]
	v_mfma_f32_16x16x32_bf16 v[40:43], v[210:213], v[40:43], v[144:147]
	v_mfma_f32_16x16x32_bf16 v[148:151], v[206:209], v[44:47], v[148:151]
	v_mfma_f32_16x16x32_bf16 v[40:43], v[214:217], v[44:47], v[40:43]
	v_mfma_f32_16x16x32_bf16 v[44:47], v[202:205], v[48:51], v[132:135]
	v_mfma_f32_16x16x32_bf16 v[48:51], v[210:213], v[48:51], v[128:131]
	v_mfma_f32_16x16x32_bf16 v[112:115], v[210:213], v[186:189], v[112:115]
	v_mfma_f32_16x16x32_bf16 v[100:103], v[202:205], v[194:197], v[100:103]
	v_mfma_f32_16x16x32_bf16 v[96:99], v[210:213], v[194:197], v[96:99]
	v_mfma_f32_16x16x32_bf16 v[44:47], v[206:209], v[52:55], v[44:47]
	v_mfma_f32_16x16x32_bf16 v[48:51], v[214:217], v[52:55], v[48:51]
	v_mfma_f32_16x16x32_bf16 v[52:55], v[202:205], v[186:189], v[116:119]
	v_mfma_f32_16x16x32_bf16 v[112:115], v[214:217], v[190:193], v[112:115]
	v_mfma_f32_16x16x32_bf16 v[100:103], v[206:209], v[198:201], v[100:103]
	v_mfma_f32_16x16x32_bf16 v[96:99], v[214:217], v[198:201], v[96:99]
	v_mfma_f32_16x16x32_bf16 v[52:55], v[206:209], v[190:193], v[52:55]
	s_barrier
	s_mov_b32 m0, s92
	v_lshl_add_u64 v[248:249], s[8:9], 0, v[168:169]
	ds_read_b128 v[116:119], v234 offset:16384
	ds_read_b128 v[128:131], v234 offset:17408
	ds_read_b128 v[132:135], v234 offset:18432
	ds_read_b128 v[144:147], v234 offset:19456
	ds_read_b128 v[186:189], v234 offset:20480
	ds_read_b128 v[190:193], v234 offset:21504
	ds_read_b128 v[194:197], v234 offset:22528
	ds_read_b128 v[198:201], v234 offset:23552
	global_load_lds_dwordx4 v[248:249], off
	v_lshl_add_u64 v[250:251], s[8:9], 0, v[164:165]
	s_mov_b32 m0, s93
	s_nop 0
	global_load_lds_dwordx4 v[250:251], off
	s_barrier
	s_waitcnt lgkmcnt(0)
	v_mfma_f32_16x16x32_bf16 v[92:95], v[16:19], v[116:119], v[92:95]
	v_mfma_f32_16x16x32_bf16 v[88:91], v[24:27], v[116:119], v[88:91]
	v_mfma_f32_16x16x32_bf16 v[76:79], v[16:19], v[132:135], v[76:79]
	v_mfma_f32_16x16x32_bf16 v[72:75], v[24:27], v[132:135], v[72:75]
	v_mfma_f32_16x16x32_bf16 v[60:63], v[16:19], v[186:189], v[60:63]
	v_mfma_f32_16x16x32_bf16 v[56:59], v[24:27], v[186:189], v[56:59]
	v_mfma_f32_16x16x32_bf16 v[12:15], v[16:19], v[194:197], v[12:15]
	v_mfma_f32_16x16x32_bf16 v[8:11], v[24:27], v[194:197], v[8:11]
	v_mfma_f32_16x16x32_bf16 v[92:95], v[20:23], v[128:131], v[92:95]
	v_mfma_f32_16x16x32_bf16 v[88:91], v[28:31], v[128:131], v[88:91]
	v_mfma_f32_16x16x32_bf16 v[76:79], v[20:23], v[144:147], v[76:79]
	v_mfma_f32_16x16x32_bf16 v[72:75], v[28:31], v[144:147], v[72:75]
	v_mfma_f32_16x16x32_bf16 v[60:63], v[20:23], v[190:193], v[60:63]
	v_mfma_f32_16x16x32_bf16 v[56:59], v[28:31], v[190:193], v[56:59]
	v_mfma_f32_16x16x32_bf16 v[12:15], v[20:23], v[198:201], v[12:15]
	v_mfma_f32_16x16x32_bf16 v[8:11], v[28:31], v[198:201], v[8:11]
	s_barrier
	s_add_u32 s56, s6, 0x40000
	s_addc_u32 s57, s7, 0
	s_add_i32 s35, s18, s33
	v_lshl_add_u64 v[16:17], s[56:57], 0, v[166:167]
	s_mov_b32 m0, s35
	s_nop 0
	global_load_lds_dwordx4 v[16:17], off
	v_lshl_add_u64 v[16:17], s[56:57], 0, v[162:163]
	s_add_i32 m0, s35, 0x2000
	s_nop 0
	global_load_lds_dwordx4 v[16:17], off
	s_waitcnt vmcnt(6)
	s_barrier
	v_mfma_f32_16x16x32_bf16 v[36:39], v[202:205], v[186:189], v[36:39]
	v_mfma_f32_16x16x32_bf16 v[32:35], v[210:213], v[186:189], v[32:35]
	v_mfma_f32_16x16x32_bf16 v[4:7], v[202:205], v[194:197], v[4:7]
	v_mfma_f32_16x16x32_bf16 v[0:3], v[210:213], v[194:197], v[0:3]
	v_mfma_f32_16x16x32_bf16 v[16:19], v[202:205], v[116:119], v[84:87]
	v_mfma_f32_16x16x32_bf16 v[20:23], v[210:213], v[116:119], v[80:83]
	v_mfma_f32_16x16x32_bf16 v[24:27], v[202:205], v[132:135], v[68:71]
	v_mfma_f32_16x16x32_bf16 v[28:31], v[210:213], v[132:135], v[64:67]
	v_mfma_f32_16x16x32_bf16 v[36:39], v[206:209], v[190:193], v[36:39]
	v_mfma_f32_16x16x32_bf16 v[32:35], v[214:217], v[190:193], v[32:35]
	v_mfma_f32_16x16x32_bf16 v[4:7], v[206:209], v[198:201], v[4:7]
	v_mfma_f32_16x16x32_bf16 v[0:3], v[214:217], v[198:201], v[0:3]
	v_mfma_f32_16x16x32_bf16 v[16:19], v[206:209], v[128:131], v[16:19]
	v_mfma_f32_16x16x32_bf16 v[20:23], v[214:217], v[128:131], v[20:23]
	v_mfma_f32_16x16x32_bf16 v[24:27], v[206:209], v[144:147], v[24:27]
	v_mfma_f32_16x16x32_bf16 v[28:31], v[214:217], v[144:147], v[28:31]
	s_barrier
	s_add_i32 s35, 0, 0x18000
	v_add_u32_e32 v84, s35, v232
	ds_read_b128 v[116:119], v234 offset:32768
	ds_read_b128 v[128:131], v234 offset:33792
	ds_read_b128 v[186:189], v234 offset:34816
	ds_read_b128 v[190:193], v234 offset:35840
	ds_read_b128 v[194:197], v234 offset:36864
	ds_read_b128 v[198:201], v234 offset:37888
	ds_read_b128 v[202:205], v234 offset:38912
	ds_read_b128 v[206:209], v234 offset:39936
	ds_read_b128 v[64:67], v84
	ds_read_b128 v[68:71], v84 offset:1024
	ds_read_b128 v[80:83], v84 offset:2048
	ds_read_b128 v[84:87], v84 offset:3072
	s_add_u32 s8, s8, 0x40000
	s_addc_u32 s9, s9, 0
	s_mov_b32 m0, s96
	v_lshl_add_u64 v[132:133], s[8:9], 0, v[168:169]
	global_load_lds_dwordx4 v[132:133], off
	v_lshl_add_u64 v[132:133], s[8:9], 0, v[164:165]
	s_mov_b32 m0, s97
	s_nop 0
	global_load_lds_dwordx4 v[132:133], off
	s_waitcnt lgkmcnt(0)
	s_barrier
	v_mfma_f32_16x16x32_bf16 v[132:135], v[64:67], v[116:119], v[156:159]
	v_mfma_f32_16x16x32_bf16 v[156:159], v[68:71], v[128:131], v[132:135]
	v_mfma_f32_16x16x32_bf16 v[132:135], v[80:83], v[116:119], v[152:155]
	v_mfma_f32_16x16x32_bf16 v[152:155], v[84:87], v[128:131], v[132:135]
	v_mfma_f32_16x16x32_bf16 v[132:135], v[64:67], v[186:189], v[140:143]
	v_mfma_f32_16x16x32_bf16 v[140:143], v[68:71], v[190:193], v[132:135]
	v_mfma_f32_16x16x32_bf16 v[132:135], v[80:83], v[186:189], v[136:139]
	v_mfma_f32_16x16x32_bf16 v[124:127], v[64:67], v[194:197], v[124:127]
	v_mfma_f32_16x16x32_bf16 v[120:123], v[80:83], v[194:197], v[120:123]
	v_mfma_f32_16x16x32_bf16 v[108:111], v[64:67], v[202:205], v[108:111]
	v_mfma_f32_16x16x32_bf16 v[104:107], v[80:83], v[202:205], v[104:107]
	v_mfma_f32_16x16x32_bf16 v[136:139], v[84:87], v[190:193], v[132:135]
	v_mfma_f32_16x16x32_bf16 v[124:127], v[68:71], v[198:201], v[124:127]
	v_mfma_f32_16x16x32_bf16 v[120:123], v[84:87], v[198:201], v[120:123]
	v_mfma_f32_16x16x32_bf16 v[108:111], v[68:71], v[206:209], v[108:111]
	v_mfma_f32_16x16x32_bf16 v[104:107], v[84:87], v[206:209], v[104:107]
	s_barrier
	s_add_i32 s8, 0, 0x1c000
	v_add_u32_e32 v132, s8, v232
	s_add_i32 s9, s35, s33
	ds_read_b128 v[210:213], v132
	ds_read_b128 v[214:217], v132 offset:1024
	ds_read_b128 v[238:241], v132 offset:2048
	ds_read_b128 v[242:245], v132 offset:3072
	v_lshl_add_u64 v[132:133], v[218:219], 0, s[14:15]
	s_mov_b32 m0, s9
	s_nop 0
	global_load_lds_dwordx4 v[132:133], off
	v_lshl_add_u64 v[132:133], v[246:247], 0, s[14:15]
	s_add_i32 m0, s9, 0x2000
	s_nop 0
	global_load_lds_dwordx4 v[132:133], off
	s_barrier
	s_waitcnt lgkmcnt(0)
	v_mfma_f32_16x16x32_bf16 v[40:43], v[238:241], v[116:119], v[40:43]
	v_mfma_f32_16x16x32_bf16 v[132:135], v[210:213], v[116:119], v[148:151]
	v_mfma_f32_16x16x32_bf16 v[144:147], v[242:245], v[128:131], v[40:43]
	v_mfma_f32_16x16x32_bf16 v[40:43], v[210:213], v[186:189], v[44:47]
	v_mfma_f32_16x16x32_bf16 v[148:151], v[214:217], v[128:131], v[132:135]
	v_mfma_f32_16x16x32_bf16 v[132:135], v[214:217], v[190:193], v[40:43]
	v_mfma_f32_16x16x32_bf16 v[40:43], v[238:241], v[186:189], v[48:51]
	v_mfma_f32_16x16x32_bf16 v[128:131], v[242:245], v[190:193], v[40:43]
	v_mfma_f32_16x16x32_bf16 v[40:43], v[210:213], v[194:197], v[52:55]
	v_mfma_f32_16x16x32_bf16 v[116:119], v[214:217], v[198:201], v[40:43]
	v_mfma_f32_16x16x32_bf16 v[40:43], v[238:241], v[194:197], v[112:115]
	v_mfma_f32_16x16x32_bf16 v[112:115], v[242:245], v[198:201], v[40:43]
	v_mfma_f32_16x16x32_bf16 v[40:43], v[210:213], v[202:205], v[100:103]
	v_mfma_f32_16x16x32_bf16 v[100:103], v[214:217], v[206:209], v[40:43]
	v_mfma_f32_16x16x32_bf16 v[40:43], v[238:241], v[202:205], v[96:99]
	v_mfma_f32_16x16x32_bf16 v[96:99], v[242:245], v[206:209], v[40:43]
	s_barrier
	s_mov_b32 m0, s53
	v_lshl_add_u64 v[202:203], v[248:249], 0, s[14:15]
	s_nop 2
	ds_read_b128 v[40:43], v234 offset:49152
	ds_read_b128 v[44:47], v234 offset:50176
	ds_read_b128 v[48:51], v234 offset:51200
	ds_read_b128 v[52:55], v234 offset:52224
	ds_read_b128 v[186:189], v234 offset:53248
	ds_read_b128 v[190:193], v234 offset:54272
	ds_read_b128 v[194:197], v234 offset:55296
	ds_read_b128 v[198:201], v234 offset:56320
	global_load_lds_dwordx4 v[202:203], off
	v_lshl_add_u64 v[202:203], v[250:251], 0, s[14:15]
	s_mov_b32 m0, s23
	s_nop 0
	global_load_lds_dwordx4 v[202:203], off
	s_barrier
	s_waitcnt lgkmcnt(0)
	v_mfma_f32_16x16x32_bf16 v[92:95], v[64:67], v[40:43], v[92:95]
	v_mfma_f32_16x16x32_bf16 v[88:91], v[80:83], v[40:43], v[88:91]
	v_mfma_f32_16x16x32_bf16 v[76:79], v[64:67], v[48:51], v[76:79]
	v_mfma_f32_16x16x32_bf16 v[72:75], v[80:83], v[48:51], v[72:75]
	v_mfma_f32_16x16x32_bf16 v[60:63], v[64:67], v[186:189], v[60:63]
	v_mfma_f32_16x16x32_bf16 v[56:59], v[80:83], v[186:189], v[56:59]
	v_mfma_f32_16x16x32_bf16 v[12:15], v[64:67], v[194:197], v[12:15]
	v_mfma_f32_16x16x32_bf16 v[8:11], v[80:83], v[194:197], v[8:11]
	v_mfma_f32_16x16x32_bf16 v[92:95], v[68:71], v[44:47], v[92:95]
	v_mfma_f32_16x16x32_bf16 v[88:91], v[84:87], v[44:47], v[88:91]
	v_mfma_f32_16x16x32_bf16 v[76:79], v[68:71], v[52:55], v[76:79]
	v_mfma_f32_16x16x32_bf16 v[72:75], v[84:87], v[52:55], v[72:75]
	v_mfma_f32_16x16x32_bf16 v[60:63], v[68:71], v[190:193], v[60:63]
	v_mfma_f32_16x16x32_bf16 v[56:59], v[84:87], v[190:193], v[56:59]
	v_mfma_f32_16x16x32_bf16 v[12:15], v[68:71], v[198:201], v[12:15]
	v_mfma_f32_16x16x32_bf16 v[8:11], v[84:87], v[198:201], v[8:11]
	s_barrier
	s_add_u32 s6, s6, 0x40080
	s_addc_u32 s7, s7, 0
	s_add_i32 s8, s8, s33
	v_lshl_add_u64 v[64:65], s[6:7], 0, v[166:167]
	s_mov_b32 m0, s8
	s_nop 0
	global_load_lds_dwordx4 v[64:65], off
	v_lshl_add_u64 v[64:65], s[6:7], 0, v[162:163]
	s_add_i32 m0, s8, 0x2000
	s_nop 0
	global_load_lds_dwordx4 v[64:65], off
	s_waitcnt vmcnt(6)
	s_barrier
	v_mfma_f32_16x16x32_bf16 v[16:19], v[210:213], v[40:43], v[16:19]
	v_mfma_f32_16x16x32_bf16 v[84:87], v[214:217], v[44:47], v[16:19]
	v_mfma_f32_16x16x32_bf16 v[16:19], v[238:241], v[40:43], v[20:23]
	v_mfma_f32_16x16x32_bf16 v[80:83], v[242:245], v[44:47], v[16:19]
	v_mfma_f32_16x16x32_bf16 v[16:19], v[210:213], v[48:51], v[24:27]
	v_mfma_f32_16x16x32_bf16 v[68:71], v[214:217], v[52:55], v[16:19]
	v_mfma_f32_16x16x32_bf16 v[16:19], v[238:241], v[48:51], v[28:31]
	v_mfma_f32_16x16x32_bf16 v[64:67], v[242:245], v[52:55], v[16:19]
	v_mfma_f32_16x16x32_bf16 v[16:19], v[210:213], v[186:189], v[36:39]
	v_mfma_f32_16x16x32_bf16 v[36:39], v[214:217], v[190:193], v[16:19]
	v_mfma_f32_16x16x32_bf16 v[16:19], v[238:241], v[186:189], v[32:35]
	v_mfma_f32_16x16x32_bf16 v[4:7], v[210:213], v[194:197], v[4:7]
	v_mfma_f32_16x16x32_bf16 v[0:3], v[238:241], v[194:197], v[0:3]
	v_mfma_f32_16x16x32_bf16 v[32:35], v[242:245], v[190:193], v[16:19]
	v_mfma_f32_16x16x32_bf16 v[4:7], v[214:217], v[198:201], v[4:7]
	v_mfma_f32_16x16x32_bf16 v[0:3], v[242:245], v[198:201], v[0:3]
	s_barrier
	s_add_i32 s34, s34, 2
	s_add_u32 s4, s4, 0x100
	s_addc_u32 s5, s5, 0
	s_add_u32 s30, s30, 0x100
	s_addc_u32 s31, s31, 0
	s_cmp_gt_u32 s34, 13
	s_cbranch_scc0 .LBB0_175
	s_cmp_gt_i32 s28, 1
	s_cselect_b64 s[6:7], -1, 0
	s_cmp_lt_i32 s28, 2
	s_cselect_b64 s[4:5], -1, 0
	s_add_i32 s8, s28, -3
	s_cmp_lt_u32 s8, 2
	s_cselect_b64 s[8:9], -1, 0
	s_lshl_b32 s29, s12, 8
	s_add_i32 s29, s29, s52
	v_or_b32_e32 v196, s29, v179
	s_nop 0
	v_ashrrev_i32_e32 v197, 31, v196
	v_readlane_b32 s72, v253, 63
	v_readlane_b32 s73, v252, 0
	s_or_b64 s[4:5], s[4:5], s[8:9]
	s_and_b32 s8, s29, 0xfc0
	v_lshl_add_u64 v[16:17], v[196:197], 2, s[72:73]
	global_load_dword v204, v[16:17], off
	global_load_dword v200, v[16:17], off offset:64
	global_load_dword v198, v[16:17], off offset:128
	global_load_dword v194, v[16:17], off offset:192
	global_load_dword v192, v[16:17], off offset:512
	global_load_dword v190, v[16:17], off offset:576
	global_load_dword v188, v[16:17], off offset:640
	global_load_dword v186, v[16:17], off offset:704
	v_or_b32_e32 v16, s8, v179
	v_readlane_b32 s8, v252, 45
	v_readlane_b32 s9, v252, 46
	s_and_b64 s[62:63], s[8:9], s[4:5]
	v_cndmask_b32_e64 v17, 0, 1, s[62:63]
	v_readlane_b32 s68, v253, 59
	v_readlane_b32 s69, v253, 60
	v_readlane_b32 s76, v252, 3
	v_readlane_b32 s77, v252, 4
	v_readlane_b32 s78, v252, 5
	v_readlane_b32 s79, v252, 6
	v_cmp_ne_u32_e64 s[4:5], 1, v17
	s_andn2_b64 vcc, exec, s[62:63]
	v_lshlrev_b32_e32 v187, 6, v16
	s_nop 6
	s_cbranch_vccnz .LBB0_178
	global_load_dwordx4 v[40:43], v187, s[76:77] offset:48
	global_load_dwordx4 v[44:47], v187, s[76:77] offset:32
	global_load_dwordx4 v[48:51], v187, s[76:77] offset:16
	global_load_dwordx4 v[52:55], v187, s[76:77]
	global_load_dwordx4 v[16:19], v187, s[76:77] offset:1072
	global_load_dwordx4 v[20:23], v187, s[76:77] offset:1056
	global_load_dwordx4 v[24:27], v187, s[76:77] offset:1040
	global_load_dwordx4 v[28:31], v187, s[76:77] offset:1024

.LBB0_612:
	ds_read_b128 v[188:191], v162
	ds_read_b128 v[192:195], v162 offset:1024
	ds_read_b128 v[196:199], v162 offset:2048
	ds_read_b128 v[200:203], v162 offset:3072
	ds_read_b128 v[204:207], v162 offset:4096
	ds_read_b128 v[208:211], v162 offset:5120
	ds_read_b128 v[212:215], v162 offset:6144
	ds_read_b128 v[216:219], v162 offset:7168
	ds_read_b128 v[164:167], v159
	ds_read_b128 v[168:171], v159 offset:1024
	ds_read_b128 v[180:183], v159 offset:2048
	ds_read_b128 v[184:187], v159 offset:3072
	s_add_u32 s24, s22, 0xfffc0080
	s_addc_u32 s25, s23, -1
	s_cmp_eq_u32 s45, 4
	s_cselect_b32 s35, s9, s25
	s_cselect_b32 s34, s41, s24
	s_cselect_b32 s25, s7, s44
	s_cselect_b32 s24, s42, s43
	v_lshl_add_u64 v[172:173], s[22:23], 0, v[154:155]
	s_add_i32 m0, s3, 0xc000
	s_nop 0
	global_load_lds_dwordx4 v[172:173], off
	v_lshl_add_u64 v[172:173], s[22:23], 0, v[156:157]
	s_add_i32 m0, s3, 0xe000
	s_nop 0
	global_load_lds_dwordx4 v[172:173], off
	s_waitcnt lgkmcnt(0)
	s_barrier
	v_mfma_f32_16x16x32_bf16 v[124:127], v[164:167], v[188:191], v[124:127]
	v_mfma_f32_16x16x32_bf16 v[120:123], v[180:183], v[188:191], v[120:123]
	v_mfma_f32_16x16x32_bf16 v[116:119], v[164:167], v[196:199], v[116:119]
	v_mfma_f32_16x16x32_bf16 v[112:115], v[180:183], v[196:199], v[112:115]
	v_mfma_f32_16x16x32_bf16 v[108:111], v[164:167], v[204:207], v[108:111]
	v_mfma_f32_16x16x32_bf16 v[100:103], v[180:183], v[204:207], v[100:103]
	v_mfma_f32_16x16x32_bf16 v[92:95], v[164:167], v[212:215], v[92:95]
	v_mfma_f32_16x16x32_bf16 v[84:87], v[180:183], v[212:215], v[84:87]
	v_mfma_f32_16x16x32_bf16 v[124:127], v[168:171], v[192:195], v[124:127]
	v_mfma_f32_16x16x32_bf16 v[120:123], v[184:187], v[192:195], v[120:123]
	v_mfma_f32_16x16x32_bf16 v[116:119], v[168:171], v[200:203], v[116:119]
	v_mfma_f32_16x16x32_bf16 v[112:115], v[184:187], v[200:203], v[112:115]
	v_mfma_f32_16x16x32_bf16 v[108:111], v[168:171], v[208:211], v[108:111]
	v_mfma_f32_16x16x32_bf16 v[100:103], v[184:187], v[208:211], v[100:103]
	v_mfma_f32_16x16x32_bf16 v[92:95], v[168:171], v[216:219], v[92:95]
	v_mfma_f32_16x16x32_bf16 v[84:87], v[184:187], v[216:219], v[84:87]
	s_barrier
	s_add_i32 s52, s31, s19
	v_lshl_add_u64 v[172:173], s[24:25], 0, v[130:131]
	s_mov_b32 m0, s52
	ds_read_b128 v[232:235], v163
	ds_read_b128 v[236:239], v163 offset:1024
	ds_read_b128 v[240:243], v163 offset:2048
	ds_read_b128 v[244:247], v163 offset:3072
	global_load_lds_dwordx4 v[172:173], off
	v_lshl_add_u64 v[176:177], s[24:25], 0, v[134:135]
	s_add_i32 m0, s52, 0x2000
	s_nop 0
	global_load_lds_dwordx4 v[176:177], off
	s_barrier
	s_waitcnt lgkmcnt(0)
	v_mfma_f32_16x16x32_bf16 v[104:107], v[232:235], v[188:191], v[104:107]
	v_mfma_f32_16x16x32_bf16 v[96:99], v[240:243], v[188:191], v[96:99]
	v_mfma_f32_16x16x32_bf16 v[88:91], v[232:235], v[196:199], v[88:91]
	v_mfma_f32_16x16x32_bf16 v[80:83], v[240:243], v[196:199], v[80:83]
	v_mfma_f32_16x16x32_bf16 v[76:79], v[232:235], v[204:207], v[76:79]
	v_mfma_f32_16x16x32_bf16 v[72:75], v[240:243], v[204:207], v[72:75]
	v_mfma_f32_16x16x32_bf16 v[68:71], v[232:235], v[212:215], v[68:71]
	v_mfma_f32_16x16x32_bf16 v[64:67], v[240:243], v[212:215], v[64:67]
	v_mfma_f32_16x16x32_bf16 v[104:107], v[236:239], v[192:195], v[104:107]
	v_mfma_f32_16x16x32_bf16 v[96:99], v[244:247], v[192:195], v[96:99]
	v_mfma_f32_16x16x32_bf16 v[88:91], v[236:239], v[200:203], v[88:91]
	v_mfma_f32_16x16x32_bf16 v[80:83], v[244:247], v[200:203], v[80:83]
	v_mfma_f32_16x16x32_bf16 v[76:79], v[236:239], v[208:211], v[76:79]
	v_mfma_f32_16x16x32_bf16 v[72:75], v[244:247], v[208:211], v[72:75]
	v_mfma_f32_16x16x32_bf16 v[68:71], v[236:239], v[216:219], v[68:71]
	v_mfma_f32_16x16x32_bf16 v[64:67], v[244:247], v[216:219], v[64:67]
	s_barrier
	s_mov_b32 m0, s3
	v_lshl_add_u64 v[248:249], s[34:35], 0, v[128:129]
	ds_read_b128 v[188:191], v162 offset:16384
	ds_read_b128 v[192:195], v162 offset:17408
	ds_read_b128 v[196:199], v162 offset:18432
	ds_read_b128 v[200:203], v162 offset:19456
	ds_read_b128 v[204:207], v162 offset:20480
	ds_read_b128 v[208:211], v162 offset:21504
	ds_read_b128 v[212:215], v162 offset:22528
	ds_read_b128 v[216:219], v162 offset:23552
	global_load_lds_dwordx4 v[248:249], off
	v_lshl_add_u64 v[250:251], s[34:35], 0, v[132:133]
	s_mov_b32 m0, s20
	s_nop 0
	global_load_lds_dwordx4 v[250:251], off
	s_barrier
	s_waitcnt lgkmcnt(0)
	v_mfma_f32_16x16x32_bf16 v[60:63], v[164:167], v[188:191], v[60:63]
	v_mfma_f32_16x16x32_bf16 v[56:59], v[180:183], v[188:191], v[56:59]
	v_mfma_f32_16x16x32_bf16 v[52:55], v[164:167], v[196:199], v[52:55]
	v_mfma_f32_16x16x32_bf16 v[48:51], v[180:183], v[196:199], v[48:51]
	v_mfma_f32_16x16x32_bf16 v[44:47], v[164:167], v[204:207], v[44:47]
	v_mfma_f32_16x16x32_bf16 v[40:43], v[180:183], v[204:207], v[40:43]
	v_mfma_f32_16x16x32_bf16 v[28:31], v[164:167], v[212:215], v[28:31]
	v_mfma_f32_16x16x32_bf16 v[24:27], v[180:183], v[212:215], v[24:27]
	v_mfma_f32_16x16x32_bf16 v[60:63], v[168:171], v[192:195], v[60:63]
	v_mfma_f32_16x16x32_bf16 v[56:59], v[184:187], v[192:195], v[56:59]
	v_mfma_f32_16x16x32_bf16 v[52:55], v[168:171], v[200:203], v[52:55]
	v_mfma_f32_16x16x32_bf16 v[48:51], v[184:187], v[200:203], v[48:51]
	v_mfma_f32_16x16x32_bf16 v[44:47], v[168:171], v[208:211], v[44:47]
	v_mfma_f32_16x16x32_bf16 v[40:43], v[184:187], v[208:211], v[40:43]
	v_mfma_f32_16x16x32_bf16 v[28:31], v[168:171], v[216:219], v[28:31]
	v_mfma_f32_16x16x32_bf16 v[24:27], v[184:187], v[216:219], v[24:27]
	s_barrier
	s_add_u32 s52, s24, 0x80000
	s_addc_u32 s53, s25, 0
	s_add_i32 s54, s33, s19
	v_lshl_add_u64 v[164:165], s[52:53], 0, v[130:131]
	s_mov_b32 m0, s54
	s_nop 0
	global_load_lds_dwordx4 v[164:165], off
	v_lshl_add_u64 v[164:165], s[52:53], 0, v[134:135]
	s_add_i32 m0, s54, 0x2000
	s_nop 0
	global_load_lds_dwordx4 v[164:165], off
	s_waitcnt vmcnt(6)
	s_barrier
	v_mfma_f32_16x16x32_bf16 v[36:39], v[232:235], v[188:191], v[36:39]
	v_mfma_f32_16x16x32_bf16 v[32:35], v[240:243], v[188:191], v[32:35]
	v_mfma_f32_16x16x32_bf16 v[20:23], v[232:235], v[196:199], v[20:23]
	v_mfma_f32_16x16x32_bf16 v[16:19], v[240:243], v[196:199], v[16:19]
	v_mfma_f32_16x16x32_bf16 v[12:15], v[232:235], v[204:207], v[12:15]
	v_mfma_f32_16x16x32_bf16 v[8:11], v[240:243], v[204:207], v[8:11]
	v_mfma_f32_16x16x32_bf16 v[4:7], v[232:235], v[212:215], v[4:7]
	v_mfma_f32_16x16x32_bf16 v[0:3], v[240:243], v[212:215], v[0:3]
	v_mfma_f32_16x16x32_bf16 v[36:39], v[236:239], v[192:195], v[36:39]
	v_mfma_f32_16x16x32_bf16 v[32:35], v[244:247], v[192:195], v[32:35]
	v_mfma_f32_16x16x32_bf16 v[20:23], v[236:239], v[200:203], v[20:23]
	v_mfma_f32_16x16x32_bf16 v[16:19], v[244:247], v[200:203], v[16:19]
	v_mfma_f32_16x16x32_bf16 v[12:15], v[236:239], v[208:211], v[12:15]
	v_mfma_f32_16x16x32_bf16 v[8:11], v[244:247], v[208:211], v[8:11]
	v_mfma_f32_16x16x32_bf16 v[4:7], v[236:239], v[216:219], v[4:7]
	v_mfma_f32_16x16x32_bf16 v[0:3], v[244:247], v[216:219], v[0:3]
	s_barrier
	s_add_i32 s52, 0, 0x18000
	v_add_u32_e32 v174, s52, v158
	ds_read_b128 v[188:191], v162 offset:32768
	ds_read_b128 v[192:195], v162 offset:33792
	ds_read_b128 v[196:199], v162 offset:34816
	ds_read_b128 v[200:203], v162 offset:35840
	ds_read_b128 v[204:207], v162 offset:36864
	ds_read_b128 v[208:211], v162 offset:37888
	ds_read_b128 v[212:215], v162 offset:38912
	ds_read_b128 v[216:219], v162 offset:39936
	ds_read_b128 v[164:167], v174
	ds_read_b128 v[168:171], v174 offset:1024
	ds_read_b128 v[180:183], v174 offset:2048
	ds_read_b128 v[184:187], v174 offset:3072
	s_add_u32 s34, s34, 0x40000
	s_addc_u32 s35, s35, 0
	s_mov_b32 m0, s21
	v_lshl_add_u64 v[232:233], s[34:35], 0, v[128:129]
	global_load_lds_dwordx4 v[232:233], off
	v_lshl_add_u64 v[232:233], s[34:35], 0, v[132:133]
	s_mov_b32 m0, s27
	s_nop 0
	global_load_lds_dwordx4 v[232:233], off
	s_waitcnt lgkmcnt(0)
	s_barrier
	v_mfma_f32_16x16x32_bf16 v[124:127], v[164:167], v[188:191], v[124:127]
	v_mfma_f32_16x16x32_bf16 v[120:123], v[180:183], v[188:191], v[120:123]
	v_mfma_f32_16x16x32_bf16 v[116:119], v[164:167], v[196:199], v[116:119]
	v_mfma_f32_16x16x32_bf16 v[112:115], v[180:183], v[196:199], v[112:115]
	v_mfma_f32_16x16x32_bf16 v[108:111], v[164:167], v[204:207], v[108:111]
	v_mfma_f32_16x16x32_bf16 v[100:103], v[180:183], v[204:207], v[100:103]
	v_mfma_f32_16x16x32_bf16 v[92:95], v[164:167], v[212:215], v[92:95]
	v_mfma_f32_16x16x32_bf16 v[84:87], v[180:183], v[212:215], v[84:87]
	v_mfma_f32_16x16x32_bf16 v[124:127], v[168:171], v[192:195], v[124:127]
	v_mfma_f32_16x16x32_bf16 v[120:123], v[184:187], v[192:195], v[120:123]
	v_mfma_f32_16x16x32_bf16 v[116:119], v[168:171], v[200:203], v[116:119]
	v_mfma_f32_16x16x32_bf16 v[112:115], v[184:187], v[200:203], v[112:115]
	v_mfma_f32_16x16x32_bf16 v[108:111], v[168:171], v[208:211], v[108:111]
	v_mfma_f32_16x16x32_bf16 v[100:103], v[184:187], v[208:211], v[100:103]
	v_mfma_f32_16x16x32_bf16 v[92:95], v[168:171], v[216:219], v[92:95]
	v_mfma_f32_16x16x32_bf16 v[84:87], v[184:187], v[216:219], v[84:87]
	s_barrier
	s_add_i32 s34, 0, 0x1c000
	s_add_i32 s35, s52, s19
	v_add_u32_e32 v174, s34, v158
	v_lshl_add_u64 v[172:173], v[172:173], 0, s[4:5]
	s_mov_b32 m0, s35
	ds_read_b128 v[232:235], v174
	ds_read_b128 v[236:239], v174 offset:1024
	ds_read_b128 v[240:243], v174 offset:2048
	ds_read_b128 v[244:247], v174 offset:3072
	global_load_lds_dwordx4 v[172:173], off
	v_lshl_add_u64 v[172:173], v[176:177], 0, s[4:5]
	s_add_i32 m0, s35, 0x2000
	s_nop 0
	global_load_lds_dwordx4 v[172:173], off
	s_barrier
	s_waitcnt lgkmcnt(0)
	v_mfma_f32_16x16x32_bf16 v[104:107], v[232:235], v[188:191], v[104:107]
	v_mfma_f32_16x16x32_bf16 v[96:99], v[240:243], v[188:191], v[96:99]
	v_mfma_f32_16x16x32_bf16 v[88:91], v[232:235], v[196:199], v[88:91]
	v_mfma_f32_16x16x32_bf16 v[80:83], v[240:243], v[196:199], v[80:83]
	v_mfma_f32_16x16x32_bf16 v[76:79], v[232:235], v[204:207], v[76:79]
	v_mfma_f32_16x16x32_bf16 v[72:75], v[240:243], v[204:207], v[72:75]
	v_mfma_f32_16x16x32_bf16 v[68:71], v[232:235], v[212:215], v[68:71]
	v_mfma_f32_16x16x32_bf16 v[64:67], v[240:243], v[212:215], v[64:67]
	v_mfma_f32_16x16x32_bf16 v[104:107], v[236:239], v[192:195], v[104:107]
	v_mfma_f32_16x16x32_bf16 v[96:99], v[244:247], v[192:195], v[96:99]
	v_mfma_f32_16x16x32_bf16 v[88:91], v[236:239], v[200:203], v[88:91]
	v_mfma_f32_16x16x32_bf16 v[80:83], v[244:247], v[200:203], v[80:83]
	v_mfma_f32_16x16x32_bf16 v[76:79], v[236:239], v[208:211], v[76:79]
	v_mfma_f32_16x16x32_bf16 v[72:75], v[244:247], v[208:211], v[72:75]
	v_mfma_f32_16x16x32_bf16 v[68:71], v[236:239], v[216:219], v[68:71]
	v_mfma_f32_16x16x32_bf16 v[64:67], v[244:247], v[216:219], v[64:67]
	s_barrier
	s_mov_b32 m0, s29
	v_lshl_add_u64 v[172:173], v[248:249], 0, s[4:5]
	ds_read_b128 v[188:191], v162 offset:49152
	ds_read_b128 v[192:195], v162 offset:50176
	ds_read_b128 v[196:199], v162 offset:51200
	ds_read_b128 v[200:203], v162 offset:52224
	ds_read_b128 v[204:207], v162 offset:53248
	ds_read_b128 v[208:211], v162 offset:54272
	ds_read_b128 v[212:215], v162 offset:55296
	ds_read_b128 v[216:219], v162 offset:56320
	global_load_lds_dwordx4 v[172:173], off
	v_lshl_add_u64 v[172:173], v[250:251], 0, s[4:5]
	s_mov_b32 m0, s30
	s_nop 0
	global_load_lds_dwordx4 v[172:173], off
	s_barrier
	s_waitcnt lgkmcnt(0)
	v_mfma_f32_16x16x32_bf16 v[60:63], v[164:167], v[188:191], v[60:63]
	v_mfma_f32_16x16x32_bf16 v[56:59], v[180:183], v[188:191], v[56:59]
	v_mfma_f32_16x16x32_bf16 v[52:55], v[164:167], v[196:199], v[52:55]
	v_mfma_f32_16x16x32_bf16 v[48:51], v[180:183], v[196:199], v[48:51]
	v_mfma_f32_16x16x32_bf16 v[44:47], v[164:167], v[204:207], v[44:47]
	v_mfma_f32_16x16x32_bf16 v[40:43], v[180:183], v[204:207], v[40:43]
	v_mfma_f32_16x16x32_bf16 v[28:31], v[164:167], v[212:215], v[28:31]
	v_mfma_f32_16x16x32_bf16 v[24:27], v[180:183], v[212:215], v[24:27]
	v_mfma_f32_16x16x32_bf16 v[60:63], v[168:171], v[192:195], v[60:63]
	v_mfma_f32_16x16x32_bf16 v[56:59], v[184:187], v[192:195], v[56:59]
	v_mfma_f32_16x16x32_bf16 v[52:55], v[168:171], v[200:203], v[52:55]
	v_mfma_f32_16x16x32_bf16 v[48:51], v[184:187], v[200:203], v[48:51]
	v_mfma_f32_16x16x32_bf16 v[44:47], v[168:171], v[208:211], v[44:47]
	v_mfma_f32_16x16x32_bf16 v[40:43], v[184:187], v[208:211], v[40:43]
	v_mfma_f32_16x16x32_bf16 v[28:31], v[168:171], v[216:219], v[28:31]
	v_mfma_f32_16x16x32_bf16 v[24:27], v[184:187], v[216:219], v[24:27]
	s_barrier
	s_add_u32 s24, s24, 0x80080
	s_addc_u32 s25, s25, 0
	s_add_i32 s34, s34, s19
	v_lshl_add_u64 v[164:165], s[24:25], 0, v[130:131]
	s_mov_b32 m0, s34
	s_nop 0
	global_load_lds_dwordx4 v[164:165], off
	v_lshl_add_u64 v[164:165], s[24:25], 0, v[134:135]
	s_add_i32 m0, s34, 0x2000
	s_nop 0
	global_load_lds_dwordx4 v[164:165], off
	s_waitcnt vmcnt(6)
	s_barrier
	v_mfma_f32_16x16x32_bf16 v[36:39], v[232:235], v[188:191], v[36:39]
	v_mfma_f32_16x16x32_bf16 v[32:35], v[240:243], v[188:191], v[32:35]
	v_mfma_f32_16x16x32_bf16 v[20:23], v[232:235], v[196:199], v[20:23]
	v_mfma_f32_16x16x32_bf16 v[16:19], v[240:243], v[196:199], v[16:19]
	v_mfma_f32_16x16x32_bf16 v[12:15], v[232:235], v[204:207], v[12:15]
	v_mfma_f32_16x16x32_bf16 v[8:11], v[240:243], v[204:207], v[8:11]
	v_mfma_f32_16x16x32_bf16 v[4:7], v[232:235], v[212:215], v[4:7]
	v_mfma_f32_16x16x32_bf16 v[0:3], v[240:243], v[212:215], v[0:3]
	v_mfma_f32_16x16x32_bf16 v[36:39], v[236:239], v[192:195], v[36:39]
	v_mfma_f32_16x16x32_bf16 v[32:35], v[244:247], v[192:195], v[32:35]
	v_mfma_f32_16x16x32_bf16 v[20:23], v[236:239], v[200:203], v[20:23]
	v_mfma_f32_16x16x32_bf16 v[16:19], v[244:247], v[200:203], v[16:19]
	v_mfma_f32_16x16x32_bf16 v[12:15], v[236:239], v[208:211], v[12:15]
	v_mfma_f32_16x16x32_bf16 v[8:11], v[244:247], v[208:211], v[8:11]
	v_mfma_f32_16x16x32_bf16 v[4:7], v[236:239], v[216:219], v[4:7]
	v_mfma_f32_16x16x32_bf16 v[0:3], v[244:247], v[216:219], v[0:3]
	s_barrier
	s_add_i32 s45, s45, 2
	s_add_u32 s22, s22, 0x100
	s_addc_u32 s23, s23, 0
	s_add_u32 s43, s43, 0x100
	s_addc_u32 s44, s44, 0
	s_cmp_gt_u32 s45, 5
	s_cbranch_scc0 .LBB0_612
	s_lshl_b32 s7, s26, 2
	s_and_b32 s7, s7, 0x7fffffe0
	s_add_i32 s22, s7, s2
	s_ashr_i32 s23, s22, 31
	s_lshl_b64 s[22:23], s[22:23], 18
	s_add_u32 s22, s82, s22
	s_addc_u32 s23, s83, s23
	v_lshl_add_u64 v[164:165], s[22:23], 0, v[138:139]
	v_lshl_add_u64 v[164:165], v[164:165], 0, v[136:137]
	global_store_dwordx4 v[164:165], v[124:127], off
	global_store_dwordx4 v[164:165], v[120:123], off offset:16
	global_store_dwordx4 v[164:165], v[104:107], off offset:512
	global_store_dwordx4 v[164:165], v[96:99], off offset:528
	s_and_b64 vcc, exec, s[10:11]
	s_mov_b32 s26, s40
	v_lshl_add_u64 v[96:97], s[22:23], 0, v[140:141]
	v_lshl_add_u64 v[96:97], v[96:97], 0, v[136:137]
	global_store_dwordx4 v[96:97], v[116:119], off
	global_store_dwordx4 v[96:97], v[112:115], off offset:16
	global_store_dwordx4 v[96:97], v[88:91], off offset:512
	global_store_dwordx4 v[96:97], v[80:83], off offset:528
	s_mov_b32 s2, s8
	s_mov_b64 s[24:25], s[16:17]
	v_lshl_add_u64 v[80:81], s[22:23], 0, v[142:143]
	v_lshl_add_u64 v[80:81], v[80:81], 0, v[136:137]
	global_store_dwordx4 v[80:81], v[108:111], off
	global_store_dwordx4 v[80:81], v[100:103], off offset:16
	global_store_dwordx4 v[80:81], v[76:79], off offset:512
	global_store_dwordx4 v[80:81], v[72:75], off offset:528
	s_nop 1
	v_lshl_add_u64 v[72:73], s[22:23], 0, v[144:145]
	v_lshl_add_u64 v[72:73], v[72:73], 0, v[136:137]
	global_store_dwordx4 v[72:73], v[92:95], off
	global_store_dwordx4 v[72:73], v[84:87], off offset:16
	global_store_dwordx4 v[72:73], v[68:71], off offset:512
	global_store_dwordx4 v[72:73], v[64:67], off offset:528
	s_nop 1
	v_lshl_add_u64 v[64:65], s[22:23], 0, v[146:147]
	v_lshl_add_u64 v[64:65], v[64:65], 0, v[136:137]
	global_store_dwordx4 v[64:65], v[60:63], off
	global_store_dwordx4 v[64:65], v[56:59], off offset:16
	global_store_dwordx4 v[64:65], v[36:39], off offset:512
	global_store_dwordx4 v[64:65], v[32:35], off offset:528
	s_nop 1
	v_lshl_add_u64 v[32:33], s[22:23], 0, v[148:149]
	v_lshl_add_u64 v[32:33], v[32:33], 0, v[136:137]
	global_store_dwordx4 v[32:33], v[52:55], off
	global_store_dwordx4 v[32:33], v[48:51], off offset:16
	global_store_dwordx4 v[32:33], v[20:23], off offset:512
	global_store_dwordx4 v[32:33], v[16:19], off offset:528
	s_nop 1
	v_lshl_add_u64 v[16:17], s[22:23], 0, v[150:151]
	v_lshl_add_u64 v[16:17], v[16:17], 0, v[136:137]
	global_store_dwordx4 v[16:17], v[44:47], off
	global_store_dwordx4 v[16:17], v[40:43], off offset:16
	global_store_dwordx4 v[16:17], v[12:15], off offset:512
	global_store_dwordx4 v[16:17], v[8:11], off offset:528
	s_nop 1
	v_lshl_add_u64 v[8:9], s[22:23], 0, v[152:153]
	v_lshl_add_u64 v[8:9], v[8:9], 0, v[136:137]
	s_mov_b64 s[22:23], s[14:15]
	global_store_dwordx4 v[8:9], v[28:31], off
	global_store_dwordx4 v[8:9], v[24:27], off offset:16
	global_store_dwordx4 v[8:9], v[4:7], off offset:512
	global_store_dwordx4 v[8:9], v[0:3], off offset:528
	s_cbranch_vccz .LBB0_606
	s_waitcnt vmcnt(0)
	s_cmpk_gt_u32 s18, 0xff
	s_cbranch_scc1 .LBB0_616
	s_barrier

.LBB0_1268:
	ds_read_b128 v[164:167], v150
	ds_read_b128 v[168:171], v150 offset:1024
	ds_read_b128 v[172:175], v150 offset:2048
	ds_read_b128 v[180:183], v150 offset:3072
	ds_read_b128 v[184:187], v150 offset:4096
	ds_read_b128 v[188:191], v150 offset:5120
	ds_read_b128 v[192:195], v150 offset:6144
	ds_read_b128 v[196:199], v150 offset:7168
	ds_read_b128 v[140:143], v149
	ds_read_b128 v[152:155], v149 offset:1024
	ds_read_b128 v[156:159], v149 offset:2048
	ds_read_b128 v[160:163], v149 offset:3072
	s_add_u32 s22, s10, 0xfffe0080
	s_addc_u32 s23, s11, -1
	s_cmp_eq_u32 s44, 4
	s_cselect_b32 s25, s13, s23
	s_cselect_b32 s24, s40, s22
	s_cselect_b32 s23, s15, s43
	s_cselect_b32 s22, s41, s42
	v_lshl_add_u64 v[144:145], s[10:11], 0, v[136:137]
	s_add_i32 m0, s1, 0xc000
	s_nop 0
	global_load_lds_dwordx4 v[144:145], off
	v_lshl_add_u64 v[144:145], s[10:11], 0, v[138:139]
	s_add_i32 m0, s1, 0xe000
	s_nop 0
	global_load_lds_dwordx4 v[144:145], off
	s_waitcnt lgkmcnt(0)
	s_barrier
	v_mfma_f32_16x16x32_bf16 v[124:127], v[140:143], v[164:167], v[124:127]
	v_mfma_f32_16x16x32_bf16 v[120:123], v[156:159], v[164:167], v[120:123]
	v_mfma_f32_16x16x32_bf16 v[112:115], v[140:143], v[172:175], v[112:115]
	v_mfma_f32_16x16x32_bf16 v[104:107], v[156:159], v[172:175], v[104:107]
	v_mfma_f32_16x16x32_bf16 v[96:99], v[140:143], v[184:187], v[96:99]
	v_mfma_f32_16x16x32_bf16 v[88:91], v[156:159], v[184:187], v[88:91]
	v_mfma_f32_16x16x32_bf16 v[80:83], v[140:143], v[192:195], v[80:83]
	v_mfma_f32_16x16x32_bf16 v[72:75], v[156:159], v[192:195], v[72:75]
	v_mfma_f32_16x16x32_bf16 v[124:127], v[152:155], v[168:171], v[124:127]
	v_mfma_f32_16x16x32_bf16 v[120:123], v[160:163], v[168:171], v[120:123]
	v_mfma_f32_16x16x32_bf16 v[112:115], v[152:155], v[180:183], v[112:115]
	v_mfma_f32_16x16x32_bf16 v[104:107], v[160:163], v[180:183], v[104:107]
	v_mfma_f32_16x16x32_bf16 v[96:99], v[152:155], v[188:191], v[96:99]
	v_mfma_f32_16x16x32_bf16 v[88:91], v[160:163], v[188:191], v[88:91]
	v_mfma_f32_16x16x32_bf16 v[80:83], v[152:155], v[196:199], v[80:83]
	v_mfma_f32_16x16x32_bf16 v[72:75], v[160:163], v[196:199], v[72:75]
	s_barrier
	s_add_i32 s45, s35, s27
	v_lshl_add_u64 v[144:145], s[22:23], 0, v[132:133]
	s_mov_b32 m0, s45
	ds_read_b128 v[200:203], v151
	ds_read_b128 v[204:207], v151 offset:1024
	ds_read_b128 v[208:211], v151 offset:2048
	ds_read_b128 v[212:215], v151 offset:3072
	global_load_lds_dwordx4 v[144:145], off
	v_lshl_add_u64 v[176:177], s[22:23], 0, v[128:129]
	s_add_i32 m0, s45, 0x2000
	s_nop 0
	global_load_lds_dwordx4 v[176:177], off
	s_barrier
	s_waitcnt lgkmcnt(0)
	v_mfma_f32_16x16x32_bf16 v[116:119], v[200:203], v[164:167], v[116:119]
	v_mfma_f32_16x16x32_bf16 v[108:111], v[208:211], v[164:167], v[108:111]
	v_mfma_f32_16x16x32_bf16 v[100:103], v[200:203], v[172:175], v[100:103]
	v_mfma_f32_16x16x32_bf16 v[92:95], v[208:211], v[172:175], v[92:95]
	v_mfma_f32_16x16x32_bf16 v[84:87], v[200:203], v[184:187], v[84:87]
	v_mfma_f32_16x16x32_bf16 v[76:79], v[208:211], v[184:187], v[76:79]
	v_mfma_f32_16x16x32_bf16 v[68:71], v[200:203], v[192:195], v[68:71]
	v_mfma_f32_16x16x32_bf16 v[64:67], v[208:211], v[192:195], v[64:67]
	v_mfma_f32_16x16x32_bf16 v[116:119], v[204:207], v[168:171], v[116:119]
	v_mfma_f32_16x16x32_bf16 v[108:111], v[212:215], v[168:171], v[108:111]
	v_mfma_f32_16x16x32_bf16 v[100:103], v[204:207], v[180:183], v[100:103]
	v_mfma_f32_16x16x32_bf16 v[92:95], v[212:215], v[180:183], v[92:95]
	v_mfma_f32_16x16x32_bf16 v[84:87], v[204:207], v[188:191], v[84:87]
	v_mfma_f32_16x16x32_bf16 v[76:79], v[212:215], v[188:191], v[76:79]
	v_mfma_f32_16x16x32_bf16 v[68:71], v[204:207], v[196:199], v[68:71]
	v_mfma_f32_16x16x32_bf16 v[64:67], v[212:215], v[196:199], v[64:67]
	s_barrier
	s_mov_b32 m0, s1
	v_lshl_add_u64 v[216:217], s[24:25], 0, v[134:135]
	ds_read_b128 v[164:167], v150 offset:16384
	ds_read_b128 v[168:171], v150 offset:17408
	ds_read_b128 v[172:175], v150 offset:18432
	ds_read_b128 v[180:183], v150 offset:19456
	ds_read_b128 v[184:187], v150 offset:20480
	ds_read_b128 v[188:191], v150 offset:21504
	ds_read_b128 v[192:195], v150 offset:22528
	ds_read_b128 v[196:199], v150 offset:23552
	global_load_lds_dwordx4 v[216:217], off
	v_lshl_add_u64 v[218:219], s[24:25], 0, v[130:131]
	s_mov_b32 m0, s7
	s_nop 0
	global_load_lds_dwordx4 v[218:219], off
	s_barrier
	s_waitcnt lgkmcnt(0)
	v_mfma_f32_16x16x32_bf16 v[60:63], v[140:143], v[164:167], v[60:63]
	v_mfma_f32_16x16x32_bf16 v[56:59], v[156:159], v[164:167], v[56:59]
	v_mfma_f32_16x16x32_bf16 v[48:51], v[140:143], v[172:175], v[48:51]
	v_mfma_f32_16x16x32_bf16 v[40:43], v[156:159], v[172:175], v[40:43]
	v_mfma_f32_16x16x32_bf16 v[32:35], v[140:143], v[184:187], v[32:35]
	v_mfma_f32_16x16x32_bf16 v[24:27], v[156:159], v[184:187], v[24:27]
	v_mfma_f32_16x16x32_bf16 v[16:19], v[140:143], v[192:195], v[16:19]
	v_mfma_f32_16x16x32_bf16 v[8:11], v[156:159], v[192:195], v[8:11]
	v_mfma_f32_16x16x32_bf16 v[60:63], v[152:155], v[168:171], v[60:63]
	v_mfma_f32_16x16x32_bf16 v[56:59], v[160:163], v[168:171], v[56:59]
	v_mfma_f32_16x16x32_bf16 v[48:51], v[152:155], v[180:183], v[48:51]
	v_mfma_f32_16x16x32_bf16 v[40:43], v[160:163], v[180:183], v[40:43]
	v_mfma_f32_16x16x32_bf16 v[32:35], v[152:155], v[188:191], v[32:35]
	v_mfma_f32_16x16x32_bf16 v[24:27], v[160:163], v[188:191], v[24:27]
	v_mfma_f32_16x16x32_bf16 v[16:19], v[152:155], v[196:199], v[16:19]
	v_mfma_f32_16x16x32_bf16 v[8:11], v[160:163], v[196:199], v[8:11]
	s_barrier
	s_add_u32 s46, s22, 0x20000
	s_addc_u32 s47, s23, 0
	s_add_i32 s45, s36, s27
	v_lshl_add_u64 v[140:141], s[46:47], 0, v[132:133]
	s_mov_b32 m0, s45
	s_nop 0
	global_load_lds_dwordx4 v[140:141], off
	v_lshl_add_u64 v[140:141], s[46:47], 0, v[128:129]
	s_add_i32 m0, s45, 0x2000
	s_nop 0
	global_load_lds_dwordx4 v[140:141], off
	s_waitcnt vmcnt(6)
	s_barrier
	v_mfma_f32_16x16x32_bf16 v[52:55], v[200:203], v[164:167], v[52:55]
	v_mfma_f32_16x16x32_bf16 v[44:47], v[208:211], v[164:167], v[44:47]
	v_mfma_f32_16x16x32_bf16 v[36:39], v[200:203], v[172:175], v[36:39]
	v_mfma_f32_16x16x32_bf16 v[28:31], v[208:211], v[172:175], v[28:31]
	v_mfma_f32_16x16x32_bf16 v[20:23], v[200:203], v[184:187], v[20:23]
	v_mfma_f32_16x16x32_bf16 v[12:15], v[208:211], v[184:187], v[12:15]
	v_mfma_f32_16x16x32_bf16 v[4:7], v[200:203], v[192:195], v[4:7]
	v_mfma_f32_16x16x32_bf16 v[0:3], v[208:211], v[192:195], v[0:3]
	v_mfma_f32_16x16x32_bf16 v[52:55], v[204:207], v[168:171], v[52:55]
	v_mfma_f32_16x16x32_bf16 v[44:47], v[212:215], v[168:171], v[44:47]
	v_mfma_f32_16x16x32_bf16 v[36:39], v[204:207], v[180:183], v[36:39]
	v_mfma_f32_16x16x32_bf16 v[28:31], v[212:215], v[180:183], v[28:31]
	v_mfma_f32_16x16x32_bf16 v[20:23], v[204:207], v[188:191], v[20:23]
	v_mfma_f32_16x16x32_bf16 v[12:15], v[212:215], v[188:191], v[12:15]
	v_mfma_f32_16x16x32_bf16 v[4:7], v[204:207], v[196:199], v[4:7]
	v_mfma_f32_16x16x32_bf16 v[0:3], v[212:215], v[196:199], v[0:3]
	s_barrier
	s_add_i32 s45, 0, 0x18000
	v_add_u32_e32 v160, s45, v147
	ds_read_b128 v[164:167], v150 offset:32768
	ds_read_b128 v[168:171], v150 offset:33792
	ds_read_b128 v[172:175], v150 offset:34816
	ds_read_b128 v[180:183], v150 offset:35840
	ds_read_b128 v[184:187], v150 offset:36864
	ds_read_b128 v[188:191], v150 offset:37888
	ds_read_b128 v[192:195], v150 offset:38912
	ds_read_b128 v[196:199], v150 offset:39936
	ds_read_b128 v[140:143], v160
	ds_read_b128 v[152:155], v160 offset:1024
	ds_read_b128 v[156:159], v160 offset:2048
	ds_read_b128 v[160:163], v160 offset:3072
	s_add_u32 s24, s24, 0x20000
	s_addc_u32 s25, s25, 0
	s_mov_b32 m0, s28
	v_lshl_add_u64 v[200:201], s[24:25], 0, v[134:135]
	global_load_lds_dwordx4 v[200:201], off
	v_lshl_add_u64 v[200:201], s[24:25], 0, v[130:131]
	s_mov_b32 m0, s29
	s_nop 0
	global_load_lds_dwordx4 v[200:201], off
	s_waitcnt lgkmcnt(0)
	s_barrier
	v_mfma_f32_16x16x32_bf16 v[124:127], v[140:143], v[164:167], v[124:127]
	v_mfma_f32_16x16x32_bf16 v[120:123], v[156:159], v[164:167], v[120:123]
	v_mfma_f32_16x16x32_bf16 v[112:115], v[140:143], v[172:175], v[112:115]
	v_mfma_f32_16x16x32_bf16 v[104:107], v[156:159], v[172:175], v[104:107]
	v_mfma_f32_16x16x32_bf16 v[96:99], v[140:143], v[184:187], v[96:99]
	v_mfma_f32_16x16x32_bf16 v[88:91], v[156:159], v[184:187], v[88:91]
	v_mfma_f32_16x16x32_bf16 v[80:83], v[140:143], v[192:195], v[80:83]
	v_mfma_f32_16x16x32_bf16 v[72:75], v[156:159], v[192:195], v[72:75]
	v_mfma_f32_16x16x32_bf16 v[124:127], v[152:155], v[168:171], v[124:127]
	v_mfma_f32_16x16x32_bf16 v[120:123], v[160:163], v[168:171], v[120:123]
	v_mfma_f32_16x16x32_bf16 v[112:115], v[152:155], v[180:183], v[112:115]
	v_mfma_f32_16x16x32_bf16 v[104:107], v[160:163], v[180:183], v[104:107]
	v_mfma_f32_16x16x32_bf16 v[96:99], v[152:155], v[188:191], v[96:99]
	v_mfma_f32_16x16x32_bf16 v[88:91], v[160:163], v[188:191], v[88:91]
	v_mfma_f32_16x16x32_bf16 v[80:83], v[152:155], v[196:199], v[80:83]
	v_mfma_f32_16x16x32_bf16 v[72:75], v[160:163], v[196:199], v[72:75]
	s_barrier
	s_add_i32 s24, 0, 0x1c000
	s_add_i32 s25, s45, s27
	v_add_u32_e32 v179, s24, v147
	v_lshl_add_u64 v[144:145], v[144:145], 0, s[2:3]
	s_mov_b32 m0, s25
	ds_read_b128 v[200:203], v179
	ds_read_b128 v[204:207], v179 offset:1024
	ds_read_b128 v[208:211], v179 offset:2048
	ds_read_b128 v[212:215], v179 offset:3072
	global_load_lds_dwordx4 v[144:145], off
	v_lshl_add_u64 v[144:145], v[176:177], 0, s[2:3]
	s_add_i32 m0, s25, 0x2000
	s_nop 0
	global_load_lds_dwordx4 v[144:145], off
	s_barrier
	s_waitcnt lgkmcnt(0)
	v_mfma_f32_16x16x32_bf16 v[116:119], v[200:203], v[164:167], v[116:119]
	v_mfma_f32_16x16x32_bf16 v[108:111], v[208:211], v[164:167], v[108:111]
	v_mfma_f32_16x16x32_bf16 v[100:103], v[200:203], v[172:175], v[100:103]
	v_mfma_f32_16x16x32_bf16 v[92:95], v[208:211], v[172:175], v[92:95]
	v_mfma_f32_16x16x32_bf16 v[84:87], v[200:203], v[184:187], v[84:87]
	v_mfma_f32_16x16x32_bf16 v[76:79], v[208:211], v[184:187], v[76:79]
	v_mfma_f32_16x16x32_bf16 v[68:71], v[200:203], v[192:195], v[68:71]
	v_mfma_f32_16x16x32_bf16 v[64:67], v[208:211], v[192:195], v[64:67]
	v_mfma_f32_16x16x32_bf16 v[116:119], v[204:207], v[168:171], v[116:119]
	v_mfma_f32_16x16x32_bf16 v[108:111], v[212:215], v[168:171], v[108:111]
	v_mfma_f32_16x16x32_bf16 v[100:103], v[204:207], v[180:183], v[100:103]
	v_mfma_f32_16x16x32_bf16 v[92:95], v[212:215], v[180:183], v[92:95]
	v_mfma_f32_16x16x32_bf16 v[84:87], v[204:207], v[188:191], v[84:87]
	v_mfma_f32_16x16x32_bf16 v[76:79], v[212:215], v[188:191], v[76:79]
	v_mfma_f32_16x16x32_bf16 v[68:71], v[204:207], v[196:199], v[68:71]
	v_mfma_f32_16x16x32_bf16 v[64:67], v[212:215], v[196:199], v[64:67]
	s_barrier
	s_mov_b32 m0, s31
	v_lshl_add_u64 v[144:145], v[216:217], 0, s[2:3]
	ds_read_b128 v[164:167], v150 offset:49152
	ds_read_b128 v[168:171], v150 offset:50176
	ds_read_b128 v[172:175], v150 offset:51200
	ds_read_b128 v[180:183], v150 offset:52224
	ds_read_b128 v[184:187], v150 offset:53248
	ds_read_b128 v[188:191], v150 offset:54272
	ds_read_b128 v[192:195], v150 offset:55296
	ds_read_b128 v[196:199], v150 offset:56320
	global_load_lds_dwordx4 v[144:145], off
	v_lshl_add_u64 v[144:145], v[218:219], 0, s[2:3]
	s_mov_b32 m0, s33
	s_nop 0
	global_load_lds_dwordx4 v[144:145], off
	s_barrier
	s_waitcnt lgkmcnt(0)
	v_mfma_f32_16x16x32_bf16 v[60:63], v[140:143], v[164:167], v[60:63]
	v_mfma_f32_16x16x32_bf16 v[56:59], v[156:159], v[164:167], v[56:59]
	v_mfma_f32_16x16x32_bf16 v[48:51], v[140:143], v[172:175], v[48:51]
	v_mfma_f32_16x16x32_bf16 v[40:43], v[156:159], v[172:175], v[40:43]
	v_mfma_f32_16x16x32_bf16 v[32:35], v[140:143], v[184:187], v[32:35]
	v_mfma_f32_16x16x32_bf16 v[24:27], v[156:159], v[184:187], v[24:27]
	v_mfma_f32_16x16x32_bf16 v[16:19], v[140:143], v[192:195], v[16:19]
	v_mfma_f32_16x16x32_bf16 v[8:11], v[156:159], v[192:195], v[8:11]
	v_mfma_f32_16x16x32_bf16 v[60:63], v[152:155], v[168:171], v[60:63]
	v_mfma_f32_16x16x32_bf16 v[56:59], v[160:163], v[168:171], v[56:59]
	v_mfma_f32_16x16x32_bf16 v[48:51], v[152:155], v[180:183], v[48:51]
	v_mfma_f32_16x16x32_bf16 v[40:43], v[160:163], v[180:183], v[40:43]
	v_mfma_f32_16x16x32_bf16 v[32:35], v[152:155], v[188:191], v[32:35]
	v_mfma_f32_16x16x32_bf16 v[24:27], v[160:163], v[188:191], v[24:27]
	v_mfma_f32_16x16x32_bf16 v[16:19], v[152:155], v[196:199], v[16:19]
	v_mfma_f32_16x16x32_bf16 v[8:11], v[160:163], v[196:199], v[8:11]
	s_barrier
	s_add_u32 s22, s22, 0x20080
	s_addc_u32 s23, s23, 0
	s_add_i32 s24, s24, s27
	v_lshl_add_u64 v[140:141], s[22:23], 0, v[132:133]
	s_mov_b32 m0, s24
	s_nop 0
	global_load_lds_dwordx4 v[140:141], off
	v_lshl_add_u64 v[140:141], s[22:23], 0, v[128:129]
	s_add_i32 m0, s24, 0x2000
	s_nop 0
	global_load_lds_dwordx4 v[140:141], off
	s_waitcnt vmcnt(6)
	s_barrier
	v_mfma_f32_16x16x32_bf16 v[52:55], v[200:203], v[164:167], v[52:55]
	v_mfma_f32_16x16x32_bf16 v[44:47], v[208:211], v[164:167], v[44:47]
	v_mfma_f32_16x16x32_bf16 v[36:39], v[200:203], v[172:175], v[36:39]
	v_mfma_f32_16x16x32_bf16 v[28:31], v[208:211], v[172:175], v[28:31]
	v_mfma_f32_16x16x32_bf16 v[20:23], v[200:203], v[184:187], v[20:23]
	v_mfma_f32_16x16x32_bf16 v[12:15], v[208:211], v[184:187], v[12:15]
	v_mfma_f32_16x16x32_bf16 v[4:7], v[200:203], v[192:195], v[4:7]
	v_mfma_f32_16x16x32_bf16 v[0:3], v[208:211], v[192:195], v[0:3]
	v_mfma_f32_16x16x32_bf16 v[52:55], v[204:207], v[168:171], v[52:55]
	v_mfma_f32_16x16x32_bf16 v[44:47], v[212:215], v[168:171], v[44:47]
	v_mfma_f32_16x16x32_bf16 v[36:39], v[204:207], v[180:183], v[36:39]
	v_mfma_f32_16x16x32_bf16 v[28:31], v[212:215], v[180:183], v[28:31]
	v_mfma_f32_16x16x32_bf16 v[20:23], v[204:207], v[188:191], v[20:23]
	v_mfma_f32_16x16x32_bf16 v[12:15], v[212:215], v[188:191], v[12:15]
	v_mfma_f32_16x16x32_bf16 v[4:7], v[204:207], v[196:199], v[4:7]
	v_mfma_f32_16x16x32_bf16 v[0:3], v[212:215], v[196:199], v[0:3]
	s_barrier
	s_add_i32 s44, s44, 2
	s_add_u32 s10, s10, 0x100
	s_addc_u32 s11, s11, 0
	s_add_u32 s42, s42, 0x100
	s_addc_u32 s43, s43, 0
	s_cmp_gt_u32 s44, 5
	s_cbranch_scc0 .LBB0_1268
	v_lshl_add_u32 v142, s39, 8, v146
	s_nop 0
	v_lshl_or_b32 v140, s38, 8, v148
	v_ashrrev_i32_e32 v143, 31, v142
	s_nop 1
	v_readlane_b32 s46, v252, 13
	v_readlane_b32 s47, v252, 14
	v_ashrrev_i32_e32 v141, 31, v140
	v_lshlrev_b64 v[144:145], 12, v[142:143]
	s_mov_b64 s[42:43], s[46:47]
	v_lshl_add_u64 v[144:145], s[42:43], 0, v[144:145]
	v_lshlrev_b64 v[140:141], 1, v[140:141]
	v_or_b32_e32 v172, 16, v142
	v_lshl_add_u64 v[144:145], v[144:145], 0, v[140:141]
	v_ashrrev_i32_e32 v173, 31, v172
	global_load_dwordx4 v[152:155], v[144:145], off
	global_load_dwordx4 v[156:159], v[144:145], off offset:256
	v_lshlrev_b64 v[144:145], 12, v[172:173]
	v_lshl_add_u64 v[144:145], s[42:43], 0, v[144:145]
	v_lshl_add_u64 v[144:145], v[144:145], 0, v[140:141]
	global_load_dwordx4 v[160:163], v[144:145], off
	global_load_dwordx4 v[164:167], v[144:145], off offset:256
	v_or_b32_e32 v176, 32, v142
	v_ashrrev_i32_e32 v177, 31, v176
	v_lshlrev_b64 v[168:169], 12, v[176:177]
	v_lshl_add_u64 v[168:169], s[42:43], 0, v[168:169]
	v_lshl_add_u64 v[182:183], v[168:169], 0, v[140:141]
	global_load_dwordx4 v[168:171], v[182:183], off
	v_or_b32_e32 v144, 48, v142
	v_ashrrev_i32_e32 v145, 31, v144
	v_lshlrev_b64 v[180:181], 12, v[144:145]
	v_lshlrev_b64 v[174:175], 11, v[142:143]
	v_lshlrev_b64 v[172:173], 11, v[172:173]
	v_lshl_add_u64 v[180:181], s[42:43], 0, v[180:181]
	v_lshl_add_u64 v[174:175], s[82:83], 0, v[174:175]
	v_lshl_add_u64 v[172:173], s[82:83], 0, v[172:173]
	v_lshl_add_u64 v[184:185], v[180:181], 0, v[140:141]
	v_lshl_add_u64 v[188:189], v[174:175], 0, v[140:141]
	v_lshl_add_u64 v[190:191], v[172:173], 0, v[140:141]
	global_load_dwordx4 v[172:175], v[182:183], off offset:256
	s_nop 0
	global_load_dwordx4 v[180:183], v[184:185], off
	s_nop 0
	global_load_dwordx4 v[184:187], v[184:185], off offset:256
	v_add_u32_e32 v234, 0x80, v142
	v_ashrrev_i32_e32 v235, 31, v234
	v_lshlrev_b64 v[236:237], 12, v[234:235]
	v_lshl_add_u64 v[236:237], s[42:43], 0, v[236:237]
	v_lshl_add_u64 v[236:237], v[236:237], 0, v[140:141]
	global_load_dwordx4 v[200:203], v[236:237], off
	global_load_dwordx4 v[204:207], v[236:237], off offset:256
	v_add_u32_e32 v234, 0x90, v142
	v_ashrrev_i32_e32 v235, 31, v234
	v_lshlrev_b64 v[236:237], 12, v[234:235]
	v_lshl_add_u64 v[236:237], s[42:43], 0, v[236:237]
	v_lshl_add_u64 v[236:237], v[236:237], 0, v[140:141]
	global_load_dwordx4 v[208:211], v[236:237], off
	global_load_dwordx4 v[212:215], v[236:237], off offset:256
	v_add_u32_e32 v234, 0xa0, v142
	v_ashrrev_i32_e32 v235, 31, v234
	v_lshlrev_b64 v[236:237], 12, v[234:235]
	v_lshl_add_u64 v[236:237], s[42:43], 0, v[236:237]
	v_lshl_add_u64 v[236:237], v[236:237], 0, v[140:141]
	global_load_dwordx4 v[216:219], v[236:237], off
	global_load_dwordx4 v[222:225], v[236:237], off offset:256
	v_add_u32_e32 v234, 0xb0, v142
	v_ashrrev_i32_e32 v235, 31, v234
	v_lshlrev_b64 v[236:237], 12, v[234:235]
	v_lshl_add_u64 v[236:237], s[42:43], 0, v[236:237]
	v_lshl_add_u64 v[236:237], v[236:237], 0, v[140:141]
	global_load_dwordx4 v[226:229], v[236:237], off
	global_load_dwordx4 v[230:233], v[236:237], off offset:256
	s_and_b64 vcc, exec, s[18:19]
	s_mov_b32 s38, s14
	s_mov_b32 s39, s12
	s_mov_b32 s15, s14
	s_mov_b32 s18, s12
	s_mov_b64 s[22:23], s[20:21]
	s_mov_b64 s[10:11], s[16:17]
	s_mov_b32 s13, s37
	s_nop 7
	s_nop 2
	s_waitcnt vmcnt(8)
	v_lshlrev_b32_e32 v194, 16, v154
	v_and_b32_e32 v195, 0xffff0000, v154
	v_lshlrev_b32_e32 v154, 16, v155
	v_and_b32_e32 v155, 0xffff0000, v155
	v_lshlrev_b32_e32 v196, 16, v156
	v_and_b32_e32 v197, 0xffff0000, v156
	v_lshlrev_b32_e32 v156, 16, v157
	v_and_b32_e32 v157, 0xffff0000, v157
	v_lshlrev_b32_e32 v198, 16, v158
	v_and_b32_e32 v199, 0xffff0000, v158
	v_lshlrev_b32_e32 v158, 16, v159
	v_and_b32_e32 v159, 0xffff0000, v159
	v_lshlrev_b32_e32 v192, 16, v152
	v_and_b32_e32 v193, 0xffff0000, v152
	v_lshlrev_b32_e32 v152, 16, v153
	v_and_b32_e32 v153, 0xffff0000, v153
	v_pk_mul_f32 v[120:121], v[120:121], v[194:195]
	v_pk_mul_f32 v[122:123], v[122:123], v[154:155]
	v_pk_mul_f32 v[118:119], v[118:119], v[156:157]
	v_pk_mul_f32 v[154:155], v[110:111], v[158:159]
	v_lshlrev_b32_e32 v156, 16, v160
	v_and_b32_e32 v157, 0xffff0000, v160
	v_lshlrev_b32_e32 v158, 16, v161
	v_and_b32_e32 v159, 0xffff0000, v161
	v_lshlrev_b32_e32 v160, 16, v162
	v_and_b32_e32 v161, 0xffff0000, v162
	v_lshlrev_b32_e32 v162, 16, v163
	v_and_b32_e32 v163, 0xffff0000, v163
	v_pk_mul_f32 v[124:125], v[124:125], v[192:193]
	v_pk_mul_f32 v[126:127], v[126:127], v[152:153]
	v_cvt_pk_bf16_f32 v110, v120, v121
	v_cvt_pk_bf16_f32 v111, v122, v123
	v_pk_mul_f32 v[112:113], v[112:113], v[156:157]
	v_pk_mul_f32 v[114:115], v[114:115], v[158:159]
	v_pk_mul_f32 v[120:121], v[104:105], v[160:161]
	v_pk_mul_f32 v[122:123], v[106:107], v[162:163]
	v_pk_mul_f32 v[116:117], v[116:117], v[196:197]
	v_pk_mul_f32 v[152:153], v[108:109], v[198:199]
	v_cvt_pk_bf16_f32 v108, v124, v125
	v_cvt_pk_bf16_f32 v109, v126, v127
	v_cvt_pk_bf16_f32 v104, v112, v113
	v_cvt_pk_bf16_f32 v105, v114, v115
	v_cvt_pk_bf16_f32 v106, v120, v121
	v_cvt_pk_bf16_f32 v107, v122, v123
	v_cvt_pk_bf16_f32 v116, v116, v117
	v_cvt_pk_bf16_f32 v117, v118, v119
	v_cvt_pk_bf16_f32 v118, v152, v153
	v_cvt_pk_bf16_f32 v119, v154, v155
	global_store_dwordx4 v[188:189], v[108:111], off
	global_store_dwordx4 v[188:189], v[116:119], off offset:256
	global_store_dwordx4 v[190:191], v[104:107], off
	v_lshlrev_b32_e32 v192, 16, v164
	v_and_b32_e32 v193, 0xffff0000, v164
	v_lshlrev_b32_e32 v104, 16, v165
	v_and_b32_e32 v105, 0xffff0000, v165
	v_pk_mul_f32 v[102:103], v[102:103], v[104:105]
	v_lshlrev_b32_e32 v104, 16, v166
	v_and_b32_e32 v105, 0xffff0000, v166
	v_pk_mul_f32 v[104:105], v[92:93], v[104:105]
	v_lshlrev_b32_e32 v92, 16, v167
	v_and_b32_e32 v93, 0xffff0000, v167
	v_pk_mul_f32 v[100:101], v[100:101], v[192:193]
	v_pk_mul_f32 v[106:107], v[94:95], v[92:93]
	v_cvt_pk_bf16_f32 v92, v100, v101
	v_cvt_pk_bf16_f32 v93, v102, v103
	v_cvt_pk_bf16_f32 v94, v104, v105
	v_cvt_pk_bf16_f32 v95, v106, v107
	global_store_dwordx4 v[190:191], v[92:95], off offset:256
	v_add_u32_e32 v102, 0xb0, v142
	v_ashrrev_i32_e32 v103, 31, v102
	v_lshlrev_b32_e32 v94, 16, v168
	v_and_b32_e32 v95, 0xffff0000, v168
	v_pk_mul_f32 v[94:95], v[96:97], v[94:95]
	v_lshlrev_b32_e32 v96, 16, v169
	v_and_b32_e32 v97, 0xffff0000, v169
	v_pk_mul_f32 v[96:97], v[98:99], v[96:97]
	v_lshlrev_b32_e32 v98, 16, v170
	v_and_b32_e32 v99, 0xffff0000, v170
	v_lshlrev_b64 v[92:93], 11, v[176:177]
	v_pk_mul_f32 v[98:99], v[88:89], v[98:99]
	v_lshlrev_b32_e32 v88, 16, v171
	v_and_b32_e32 v89, 0xffff0000, v171
	v_pk_mul_f32 v[100:101], v[90:91], v[88:89]
	v_lshl_add_u64 v[92:93], s[82:83], 0, v[92:93]
	v_cvt_pk_bf16_f32 v88, v94, v95
	v_cvt_pk_bf16_f32 v89, v96, v97
	v_cvt_pk_bf16_f32 v90, v98, v99
	v_cvt_pk_bf16_f32 v91, v100, v101
	v_lshl_add_u64 v[92:93], v[92:93], 0, v[140:141]
	global_store_dwordx4 v[92:93], v[88:91], off
	v_add_u32_e32 v96, 0x80, v142
	v_ashrrev_i32_e32 v97, 31, v96
	v_lshlrev_b32_e32 v88, 16, v172
	v_and_b32_e32 v89, 0xffff0000, v172
	v_pk_mul_f32 v[84:85], v[84:85], v[88:89]
	v_lshlrev_b32_e32 v88, 16, v173
	v_and_b32_e32 v89, 0xffff0000, v173
	v_pk_mul_f32 v[86:87], v[86:87], v[88:89]
	v_lshlrev_b32_e32 v88, 16, v174
	v_and_b32_e32 v89, 0xffff0000, v174
	v_pk_mul_f32 v[88:89], v[76:77], v[88:89]
	v_lshlrev_b32_e32 v76, 16, v175
	v_and_b32_e32 v77, 0xffff0000, v175
	v_pk_mul_f32 v[90:91], v[78:79], v[76:77]
	v_cvt_pk_bf16_f32 v76, v84, v85
	v_cvt_pk_bf16_f32 v77, v86, v87
	v_cvt_pk_bf16_f32 v78, v88, v89
	v_cvt_pk_bf16_f32 v79, v90, v91
	global_store_dwordx4 v[92:93], v[76:79], off offset:256
	v_add_u32_e32 v98, 0x90, v142
	v_ashrrev_i32_e32 v99, 31, v98
	v_lshlrev_b32_e32 v78, 16, v180
	v_and_b32_e32 v79, 0xffff0000, v180
	v_pk_mul_f32 v[78:79], v[80:81], v[78:79]
	v_lshlrev_b32_e32 v80, 16, v181
	v_and_b32_e32 v81, 0xffff0000, v181
	v_pk_mul_f32 v[80:81], v[82:83], v[80:81]
	v_lshlrev_b32_e32 v82, 16, v182
	v_and_b32_e32 v83, 0xffff0000, v182
	v_lshlrev_b64 v[76:77], 11, v[144:145]
	v_pk_mul_f32 v[82:83], v[72:73], v[82:83]
	v_lshlrev_b32_e32 v72, 16, v183
	v_and_b32_e32 v73, 0xffff0000, v183
	v_pk_mul_f32 v[84:85], v[74:75], v[72:73]
	v_lshl_add_u64 v[76:77], s[82:83], 0, v[76:77]
	v_cvt_pk_bf16_f32 v72, v78, v79
	v_cvt_pk_bf16_f32 v73, v80, v81
	v_cvt_pk_bf16_f32 v74, v82, v83
	v_cvt_pk_bf16_f32 v75, v84, v85
	v_lshl_add_u64 v[76:77], v[76:77], 0, v[140:141]
	global_store_dwordx4 v[76:77], v[72:75], off
	v_add_u32_e32 v100, 0xa0, v142
	v_ashrrev_i32_e32 v101, 31, v100
	v_lshlrev_b32_e32 v72, 16, v184
	v_and_b32_e32 v73, 0xffff0000, v184
	v_pk_mul_f32 v[68:69], v[68:69], v[72:73]
	v_lshlrev_b32_e32 v72, 16, v185
	v_and_b32_e32 v73, 0xffff0000, v185
	v_pk_mul_f32 v[70:71], v[70:71], v[72:73]
	v_lshlrev_b32_e32 v72, 16, v186
	v_and_b32_e32 v73, 0xffff0000, v186
	v_pk_mul_f32 v[72:73], v[64:65], v[72:73]
	v_lshlrev_b32_e32 v64, 16, v187
	v_and_b32_e32 v65, 0xffff0000, v187
	v_pk_mul_f32 v[74:75], v[66:67], v[64:65]
	v_cvt_pk_bf16_f32 v64, v68, v69
	v_cvt_pk_bf16_f32 v65, v70, v71
	v_cvt_pk_bf16_f32 v66, v72, v73
	v_cvt_pk_bf16_f32 v67, v74, v75
	global_store_dwordx4 v[76:77], v[64:67], off offset:256
	s_nop 1
	v_lshlrev_b64 v[64:65], 12, v[96:97]
	v_lshl_add_u64 v[64:65], s[42:43], 0, v[64:65]
	v_lshl_add_u64 v[64:65], v[64:65], 0, v[140:141]
	v_lshlrev_b64 v[64:65], 12, v[98:99]
	v_lshl_add_u64 v[64:65], s[42:43], 0, v[64:65]
	v_lshl_add_u64 v[64:65], v[64:65], 0, v[140:141]
	v_lshlrev_b64 v[64:65], 12, v[100:101]
	v_lshl_add_u64 v[64:65], s[42:43], 0, v[64:65]
	v_lshl_add_u64 v[64:65], v[64:65], 0, v[140:141]
	v_lshlrev_b64 v[64:65], 12, v[102:103]
	v_lshl_add_u64 v[64:65], s[42:43], 0, v[64:65]
	v_lshl_add_u64 v[64:65], v[64:65], 0, v[140:141]
	s_nop 0
	v_lshlrev_b64 v[96:97], 11, v[96:97]
	s_waitcnt vmcnt(8)
	v_lshlrev_b32_e32 v104, 16, v200
	v_and_b32_e32 v105, 0xffff0000, v200
	v_lshlrev_b32_e32 v68, 16, v201
	v_and_b32_e32 v69, 0xffff0000, v201
	v_pk_mul_f32 v[62:63], v[62:63], v[68:69]
	v_lshlrev_b32_e32 v68, 16, v202
	v_and_b32_e32 v69, 0xffff0000, v202
	v_pk_mul_f32 v[60:61], v[60:61], v[104:105]
	v_pk_mul_f32 v[68:69], v[56:57], v[68:69]
	v_lshlrev_b32_e32 v56, 16, v203
	v_and_b32_e32 v57, 0xffff0000, v203
	v_pk_mul_f32 v[70:71], v[58:59], v[56:57]
	v_cvt_pk_bf16_f32 v56, v60, v61
	v_lshl_add_u64 v[60:61], s[82:83], 0, v[96:97]
	v_cvt_pk_bf16_f32 v57, v62, v63
	v_cvt_pk_bf16_f32 v58, v68, v69
	v_cvt_pk_bf16_f32 v59, v70, v71
	v_lshl_add_u64 v[60:61], v[60:61], 0, v[140:141]
	global_store_dwordx4 v[60:61], v[56:59], off
	s_nop 1
	v_lshlrev_b32_e32 v56, 16, v204
	v_and_b32_e32 v57, 0xffff0000, v204
	v_pk_mul_f32 v[52:53], v[52:53], v[56:57]
	v_lshlrev_b32_e32 v56, 16, v205
	v_and_b32_e32 v57, 0xffff0000, v205
	v_pk_mul_f32 v[54:55], v[54:55], v[56:57]
	v_lshlrev_b32_e32 v56, 16, v206
	v_and_b32_e32 v57, 0xffff0000, v206
	v_pk_mul_f32 v[56:57], v[44:45], v[56:57]
	v_lshlrev_b32_e32 v44, 16, v207
	v_and_b32_e32 v45, 0xffff0000, v207
	v_pk_mul_f32 v[58:59], v[46:47], v[44:45]
	v_cvt_pk_bf16_f32 v44, v52, v53
	v_cvt_pk_bf16_f32 v45, v54, v55
	v_cvt_pk_bf16_f32 v46, v56, v57
	v_cvt_pk_bf16_f32 v47, v58, v59
	global_store_dwordx4 v[60:61], v[44:47], off offset:256
	s_nop 1
	v_lshlrev_b32_e32 v46, 16, v208
	v_and_b32_e32 v47, 0xffff0000, v208
	v_pk_mul_f32 v[46:47], v[48:49], v[46:47]
	v_lshlrev_b32_e32 v48, 16, v209
	v_and_b32_e32 v49, 0xffff0000, v209
	v_pk_mul_f32 v[48:49], v[50:51], v[48:49]
	v_lshlrev_b32_e32 v50, 16, v210
	v_and_b32_e32 v51, 0xffff0000, v210
	v_lshlrev_b64 v[44:45], 11, v[98:99]
	v_pk_mul_f32 v[50:51], v[40:41], v[50:51]
	v_lshlrev_b32_e32 v40, 16, v211
	v_and_b32_e32 v41, 0xffff0000, v211
	v_pk_mul_f32 v[52:53], v[42:43], v[40:41]
	v_lshl_add_u64 v[44:45], s[82:83], 0, v[44:45]
	v_cvt_pk_bf16_f32 v40, v46, v47
	v_cvt_pk_bf16_f32 v41, v48, v49
	v_cvt_pk_bf16_f32 v42, v50, v51
	v_cvt_pk_bf16_f32 v43, v52, v53
	v_lshl_add_u64 v[44:45], v[44:45], 0, v[140:141]
	global_store_dwordx4 v[44:45], v[40:43], off
	s_nop 1
	v_lshlrev_b32_e32 v40, 16, v212
	v_and_b32_e32 v41, 0xffff0000, v212
	v_pk_mul_f32 v[36:37], v[36:37], v[40:41]
	v_lshlrev_b32_e32 v40, 16, v213
	v_and_b32_e32 v41, 0xffff0000, v213
	v_pk_mul_f32 v[38:39], v[38:39], v[40:41]
	v_lshlrev_b32_e32 v40, 16, v214
	v_and_b32_e32 v41, 0xffff0000, v214
	v_pk_mul_f32 v[40:41], v[28:29], v[40:41]
	v_lshlrev_b32_e32 v28, 16, v215
	v_and_b32_e32 v29, 0xffff0000, v215
	v_pk_mul_f32 v[42:43], v[30:31], v[28:29]
	v_cvt_pk_bf16_f32 v28, v36, v37
	v_cvt_pk_bf16_f32 v29, v38, v39
	v_cvt_pk_bf16_f32 v30, v40, v41
	v_cvt_pk_bf16_f32 v31, v42, v43
	global_store_dwordx4 v[44:45], v[28:31], off offset:256
	s_nop 1
	v_lshlrev_b32_e32 v30, 16, v216
	v_and_b32_e32 v31, 0xffff0000, v216
	v_pk_mul_f32 v[30:31], v[32:33], v[30:31]
	v_lshlrev_b32_e32 v32, 16, v217
	v_and_b32_e32 v33, 0xffff0000, v217
	v_pk_mul_f32 v[32:33], v[34:35], v[32:33]
	v_lshlrev_b32_e32 v34, 16, v218
	v_and_b32_e32 v35, 0xffff0000, v218
	v_lshlrev_b64 v[28:29], 11, v[100:101]
	v_pk_mul_f32 v[34:35], v[24:25], v[34:35]
	v_lshlrev_b32_e32 v24, 16, v219
	v_and_b32_e32 v25, 0xffff0000, v219
	v_pk_mul_f32 v[36:37], v[26:27], v[24:25]
	v_lshl_add_u64 v[28:29], s[82:83], 0, v[28:29]
	v_cvt_pk_bf16_f32 v24, v30, v31
	v_cvt_pk_bf16_f32 v25, v32, v33
	v_cvt_pk_bf16_f32 v26, v34, v35
	v_cvt_pk_bf16_f32 v27, v36, v37
	v_lshl_add_u64 v[28:29], v[28:29], 0, v[140:141]
	global_store_dwordx4 v[28:29], v[24:27], off
	s_nop 1
	v_lshlrev_b32_e32 v24, 16, v222
	v_and_b32_e32 v25, 0xffff0000, v222
	v_pk_mul_f32 v[20:21], v[20:21], v[24:25]
	v_lshlrev_b32_e32 v24, 16, v223
	v_and_b32_e32 v25, 0xffff0000, v223
	v_pk_mul_f32 v[22:23], v[22:23], v[24:25]
	v_lshlrev_b32_e32 v24, 16, v224
	v_and_b32_e32 v25, 0xffff0000, v224
	v_pk_mul_f32 v[24:25], v[12:13], v[24:25]
	v_lshlrev_b32_e32 v12, 16, v225
	v_and_b32_e32 v13, 0xffff0000, v225
	v_pk_mul_f32 v[26:27], v[14:15], v[12:13]
	v_cvt_pk_bf16_f32 v12, v20, v21
	v_cvt_pk_bf16_f32 v13, v22, v23
	v_cvt_pk_bf16_f32 v14, v24, v25
	v_cvt_pk_bf16_f32 v15, v26, v27
	global_store_dwordx4 v[28:29], v[12:15], off offset:256
	s_nop 1
	v_lshlrev_b32_e32 v14, 16, v226
	v_and_b32_e32 v15, 0xffff0000, v226
	v_pk_mul_f32 v[14:15], v[16:17], v[14:15]
	v_lshlrev_b32_e32 v16, 16, v227
	v_and_b32_e32 v17, 0xffff0000, v227
	v_pk_mul_f32 v[16:17], v[18:19], v[16:17]
	v_lshlrev_b32_e32 v18, 16, v228
	v_and_b32_e32 v19, 0xffff0000, v228
	v_lshlrev_b64 v[12:13], 11, v[102:103]
	v_pk_mul_f32 v[18:19], v[8:9], v[18:19]
	v_lshlrev_b32_e32 v8, 16, v229
	v_and_b32_e32 v9, 0xffff0000, v229
	v_pk_mul_f32 v[20:21], v[10:11], v[8:9]
	v_lshl_add_u64 v[12:13], s[82:83], 0, v[12:13]
	v_cvt_pk_bf16_f32 v8, v14, v15
	v_cvt_pk_bf16_f32 v9, v16, v17
	v_cvt_pk_bf16_f32 v10, v18, v19
	v_cvt_pk_bf16_f32 v11, v20, v21
	v_lshl_add_u64 v[12:13], v[12:13], 0, v[140:141]
	global_store_dwordx4 v[12:13], v[8:11], off
	s_nop 1
	v_lshlrev_b32_e32 v8, 16, v230
	v_and_b32_e32 v9, 0xffff0000, v230
	v_pk_mul_f32 v[4:5], v[4:5], v[8:9]
	v_lshlrev_b32_e32 v8, 16, v231
	v_and_b32_e32 v9, 0xffff0000, v231
	v_pk_mul_f32 v[6:7], v[6:7], v[8:9]
	v_lshlrev_b32_e32 v8, 16, v232
	v_and_b32_e32 v9, 0xffff0000, v232
	v_pk_mul_f32 v[8:9], v[0:1], v[8:9]
	v_lshlrev_b32_e32 v0, 16, v233
	v_and_b32_e32 v1, 0xffff0000, v233
	v_pk_mul_f32 v[10:11], v[2:3], v[0:1]
	v_cvt_pk_bf16_f32 v0, v4, v5
	v_cvt_pk_bf16_f32 v1, v6, v7
	v_cvt_pk_bf16_f32 v2, v8, v9
	v_cvt_pk_bf16_f32 v3, v10, v11
	global_store_dwordx4 v[12:13], v[0:3], off offset:256
	s_cbranch_vccz .LBB0_1260
	s_waitcnt vmcnt(0)
	s_cmpk_gt_u32 s26, 0xff
	s_cbranch_scc1 .LBB0_1272
	s_barrier

.LBB0_1285:
	ds_read_b128 v[144:147], v176
	ds_read_b128 v[148:151], v176 offset:1024
	ds_read_b128 v[164:167], v176 offset:2048
	ds_read_b128 v[168:171], v176 offset:3072
	ds_read_b128 v[180:183], v176 offset:4096
	ds_read_b128 v[184:187], v176 offset:5120
	ds_read_b128 v[188:191], v176 offset:6144
	ds_read_b128 v[192:195], v176 offset:7168
	ds_read_b128 v[128:131], v175
	ds_read_b128 v[132:135], v175 offset:1024
	ds_read_b128 v[136:139], v175 offset:2048
	ds_read_b128 v[140:143], v175 offset:3072
	s_add_u32 s22, s10, 0xfffe0080
	s_addc_u32 s23, s11, -1
	s_cmp_eq_u32 s43, 4
	s_cselect_b32 s25, s13, s23
	s_cselect_b32 s24, s39, s22
	s_cselect_b32 s23, s15, s42
	s_cselect_b32 s22, s40, s41
	v_lshl_add_u64 v[196:197], s[10:11], 0, v[160:161]
	s_add_i32 m0, s1, 0xc000
	s_nop 0
	global_load_lds_dwordx4 v[196:197], off
	v_lshl_add_u64 v[196:197], s[10:11], 0, v[162:163]
	s_add_i32 m0, s1, 0xe000
	s_nop 0
	global_load_lds_dwordx4 v[196:197], off
	s_waitcnt lgkmcnt(0)
	s_barrier
	v_mfma_f32_16x16x32_bf16 v[124:127], v[128:131], v[144:147], v[124:127]
	v_mfma_f32_16x16x32_bf16 v[120:123], v[136:139], v[144:147], v[120:123]
	v_mfma_f32_16x16x32_bf16 v[108:111], v[128:131], v[164:167], v[108:111]
	v_mfma_f32_16x16x32_bf16 v[104:107], v[136:139], v[164:167], v[104:107]
	v_mfma_f32_16x16x32_bf16 v[92:95], v[128:131], v[180:183], v[92:95]
	v_mfma_f32_16x16x32_bf16 v[88:91], v[136:139], v[180:183], v[88:91]
	v_mfma_f32_16x16x32_bf16 v[76:79], v[128:131], v[188:191], v[76:79]
	v_mfma_f32_16x16x32_bf16 v[72:75], v[136:139], v[188:191], v[72:75]
	v_mfma_f32_16x16x32_bf16 v[124:127], v[132:135], v[148:151], v[124:127]
	v_mfma_f32_16x16x32_bf16 v[120:123], v[140:143], v[148:151], v[120:123]
	v_mfma_f32_16x16x32_bf16 v[108:111], v[132:135], v[168:171], v[108:111]
	v_mfma_f32_16x16x32_bf16 v[104:107], v[140:143], v[168:171], v[104:107]
	v_mfma_f32_16x16x32_bf16 v[92:95], v[132:135], v[184:187], v[92:95]
	v_mfma_f32_16x16x32_bf16 v[88:91], v[140:143], v[184:187], v[88:91]
	v_mfma_f32_16x16x32_bf16 v[76:79], v[132:135], v[192:195], v[76:79]
	v_mfma_f32_16x16x32_bf16 v[72:75], v[140:143], v[192:195], v[72:75]
	s_barrier
	s_add_i32 s44, s35, s27
	v_lshl_add_u64 v[212:213], s[22:23], 0, v[156:157]
	s_mov_b32 m0, s44
	ds_read_b128 v[196:199], v177
	ds_read_b128 v[200:203], v177 offset:1024
	ds_read_b128 v[204:207], v177 offset:2048
	ds_read_b128 v[208:211], v177 offset:3072
	global_load_lds_dwordx4 v[212:213], off
	v_lshl_add_u64 v[214:215], s[22:23], 0, v[152:153]
	s_add_i32 m0, s44, 0x2000
	s_nop 0
	global_load_lds_dwordx4 v[214:215], off
	s_barrier
	s_waitcnt lgkmcnt(0)
	v_mfma_f32_16x16x32_bf16 v[116:119], v[196:199], v[144:147], v[116:119]
	v_mfma_f32_16x16x32_bf16 v[112:115], v[204:207], v[144:147], v[112:115]
	v_mfma_f32_16x16x32_bf16 v[100:103], v[196:199], v[164:167], v[100:103]
	v_mfma_f32_16x16x32_bf16 v[96:99], v[204:207], v[164:167], v[96:99]
	v_mfma_f32_16x16x32_bf16 v[84:87], v[196:199], v[180:183], v[84:87]
	v_mfma_f32_16x16x32_bf16 v[80:83], v[204:207], v[180:183], v[80:83]
	v_mfma_f32_16x16x32_bf16 v[68:71], v[196:199], v[188:191], v[68:71]
	v_mfma_f32_16x16x32_bf16 v[64:67], v[204:207], v[188:191], v[64:67]
	v_mfma_f32_16x16x32_bf16 v[116:119], v[200:203], v[148:151], v[116:119]
	v_mfma_f32_16x16x32_bf16 v[112:115], v[208:211], v[148:151], v[112:115]
	v_mfma_f32_16x16x32_bf16 v[100:103], v[200:203], v[168:171], v[100:103]
	v_mfma_f32_16x16x32_bf16 v[96:99], v[208:211], v[168:171], v[96:99]
	v_mfma_f32_16x16x32_bf16 v[84:87], v[200:203], v[184:187], v[84:87]
	v_mfma_f32_16x16x32_bf16 v[80:83], v[208:211], v[184:187], v[80:83]
	v_mfma_f32_16x16x32_bf16 v[68:71], v[200:203], v[192:195], v[68:71]
	v_mfma_f32_16x16x32_bf16 v[64:67], v[208:211], v[192:195], v[64:67]
	s_barrier
	s_mov_b32 m0, s1
	v_lshl_add_u64 v[216:217], s[24:25], 0, v[158:159]
	ds_read_b128 v[144:147], v176 offset:16384
	ds_read_b128 v[148:151], v176 offset:17408
	ds_read_b128 v[164:167], v176 offset:18432
	ds_read_b128 v[168:171], v176 offset:19456
	ds_read_b128 v[180:183], v176 offset:20480
	ds_read_b128 v[184:187], v176 offset:21504
	ds_read_b128 v[188:191], v176 offset:22528
	ds_read_b128 v[192:195], v176 offset:23552
	global_load_lds_dwordx4 v[216:217], off
	v_lshl_add_u64 v[218:219], s[24:25], 0, v[154:155]
	s_mov_b32 m0, s7
	s_nop 0
	global_load_lds_dwordx4 v[218:219], off
	s_barrier
	s_waitcnt lgkmcnt(0)
	v_mfma_f32_16x16x32_bf16 v[60:63], v[128:131], v[144:147], v[60:63]
	v_mfma_f32_16x16x32_bf16 v[56:59], v[136:139], v[144:147], v[56:59]
	v_mfma_f32_16x16x32_bf16 v[44:47], v[128:131], v[164:167], v[44:47]
	v_mfma_f32_16x16x32_bf16 v[40:43], v[136:139], v[164:167], v[40:43]
	v_mfma_f32_16x16x32_bf16 v[28:31], v[128:131], v[180:183], v[28:31]
	v_mfma_f32_16x16x32_bf16 v[24:27], v[136:139], v[180:183], v[24:27]
	v_mfma_f32_16x16x32_bf16 v[12:15], v[128:131], v[188:191], v[12:15]
	v_mfma_f32_16x16x32_bf16 v[8:11], v[136:139], v[188:191], v[8:11]
	v_mfma_f32_16x16x32_bf16 v[60:63], v[132:135], v[148:151], v[60:63]
	v_mfma_f32_16x16x32_bf16 v[56:59], v[140:143], v[148:151], v[56:59]
	v_mfma_f32_16x16x32_bf16 v[44:47], v[132:135], v[168:171], v[44:47]
	v_mfma_f32_16x16x32_bf16 v[40:43], v[140:143], v[168:171], v[40:43]
	v_mfma_f32_16x16x32_bf16 v[28:31], v[132:135], v[184:187], v[28:31]
	v_mfma_f32_16x16x32_bf16 v[24:27], v[140:143], v[184:187], v[24:27]
	v_mfma_f32_16x16x32_bf16 v[12:15], v[132:135], v[192:195], v[12:15]
	v_mfma_f32_16x16x32_bf16 v[8:11], v[140:143], v[192:195], v[8:11]
	s_barrier
	s_add_u32 s44, s22, 0x20000
	s_addc_u32 s45, s23, 0
	s_add_i32 s46, s36, s27
	v_lshl_add_u64 v[128:129], s[44:45], 0, v[156:157]
	s_mov_b32 m0, s46
	s_nop 0
	global_load_lds_dwordx4 v[128:129], off
	v_lshl_add_u64 v[128:129], s[44:45], 0, v[152:153]
	s_add_i32 m0, s46, 0x2000
	s_nop 0
	global_load_lds_dwordx4 v[128:129], off
	s_waitcnt vmcnt(6)
	s_barrier
	v_mfma_f32_16x16x32_bf16 v[52:55], v[196:199], v[144:147], v[52:55]
	v_mfma_f32_16x16x32_bf16 v[48:51], v[204:207], v[144:147], v[48:51]
	v_mfma_f32_16x16x32_bf16 v[36:39], v[196:199], v[164:167], v[36:39]
	v_mfma_f32_16x16x32_bf16 v[32:35], v[204:207], v[164:167], v[32:35]
	v_mfma_f32_16x16x32_bf16 v[20:23], v[196:199], v[180:183], v[20:23]
	v_mfma_f32_16x16x32_bf16 v[16:19], v[204:207], v[180:183], v[16:19]
	v_mfma_f32_16x16x32_bf16 v[4:7], v[196:199], v[188:191], v[4:7]
	v_mfma_f32_16x16x32_bf16 v[0:3], v[204:207], v[188:191], v[0:3]
	v_mfma_f32_16x16x32_bf16 v[52:55], v[200:203], v[148:151], v[52:55]
	v_mfma_f32_16x16x32_bf16 v[48:51], v[208:211], v[148:151], v[48:51]
	v_mfma_f32_16x16x32_bf16 v[36:39], v[200:203], v[168:171], v[36:39]
	v_mfma_f32_16x16x32_bf16 v[32:35], v[208:211], v[168:171], v[32:35]
	v_mfma_f32_16x16x32_bf16 v[20:23], v[200:203], v[184:187], v[20:23]
	v_mfma_f32_16x16x32_bf16 v[16:19], v[208:211], v[184:187], v[16:19]
	v_mfma_f32_16x16x32_bf16 v[4:7], v[200:203], v[192:195], v[4:7]
	v_mfma_f32_16x16x32_bf16 v[0:3], v[208:211], v[192:195], v[0:3]
	s_barrier
	s_add_i32 s44, 0, 0x18000
	v_add_u32_e32 v140, s44, v173
	ds_read_b128 v[144:147], v176 offset:32768
	ds_read_b128 v[148:151], v176 offset:33792
	ds_read_b128 v[164:167], v176 offset:34816
	ds_read_b128 v[168:171], v176 offset:35840
	ds_read_b128 v[180:183], v176 offset:36864
	ds_read_b128 v[184:187], v176 offset:37888
	ds_read_b128 v[188:191], v176 offset:38912
	ds_read_b128 v[192:195], v176 offset:39936
	ds_read_b128 v[128:131], v140
	ds_read_b128 v[132:135], v140 offset:1024
	ds_read_b128 v[136:139], v140 offset:2048
	ds_read_b128 v[140:143], v140 offset:3072
	s_add_u32 s24, s24, 0x20000
	s_addc_u32 s25, s25, 0
	s_mov_b32 m0, s28
	v_lshl_add_u64 v[196:197], s[24:25], 0, v[158:159]
	global_load_lds_dwordx4 v[196:197], off
	v_lshl_add_u64 v[196:197], s[24:25], 0, v[154:155]
	s_mov_b32 m0, s29
	s_nop 0
	global_load_lds_dwordx4 v[196:197], off
	s_waitcnt lgkmcnt(0)
	s_barrier
	v_mfma_f32_16x16x32_bf16 v[124:127], v[128:131], v[144:147], v[124:127]
	v_mfma_f32_16x16x32_bf16 v[120:123], v[136:139], v[144:147], v[120:123]
	v_mfma_f32_16x16x32_bf16 v[108:111], v[128:131], v[164:167], v[108:111]
	v_mfma_f32_16x16x32_bf16 v[104:107], v[136:139], v[164:167], v[104:107]
	v_mfma_f32_16x16x32_bf16 v[92:95], v[128:131], v[180:183], v[92:95]
	v_mfma_f32_16x16x32_bf16 v[88:91], v[136:139], v[180:183], v[88:91]
	v_mfma_f32_16x16x32_bf16 v[76:79], v[128:131], v[188:191], v[76:79]
	v_mfma_f32_16x16x32_bf16 v[72:75], v[136:139], v[188:191], v[72:75]
	v_mfma_f32_16x16x32_bf16 v[124:127], v[132:135], v[148:151], v[124:127]
	v_mfma_f32_16x16x32_bf16 v[120:123], v[140:143], v[148:151], v[120:123]
	v_mfma_f32_16x16x32_bf16 v[108:111], v[132:135], v[168:171], v[108:111]
	v_mfma_f32_16x16x32_bf16 v[104:107], v[140:143], v[168:171], v[104:107]
	v_mfma_f32_16x16x32_bf16 v[92:95], v[132:135], v[184:187], v[92:95]
	v_mfma_f32_16x16x32_bf16 v[88:91], v[140:143], v[184:187], v[88:91]
	v_mfma_f32_16x16x32_bf16 v[76:79], v[132:135], v[192:195], v[76:79]
	v_mfma_f32_16x16x32_bf16 v[72:75], v[140:143], v[192:195], v[72:75]
	s_barrier
	s_add_i32 s24, 0, 0x1c000
	s_add_i32 s25, s44, s27
	v_add_u32_e32 v179, s24, v173
	v_lshl_add_u64 v[212:213], v[212:213], 0, s[4:5]
	s_mov_b32 m0, s25
	ds_read_b128 v[196:199], v179
	ds_read_b128 v[200:203], v179 offset:1024
	ds_read_b128 v[204:207], v179 offset:2048
	ds_read_b128 v[208:211], v179 offset:3072
	global_load_lds_dwordx4 v[212:213], off
	v_lshl_add_u64 v[212:213], v[214:215], 0, s[4:5]
	s_add_i32 m0, s25, 0x2000
	s_nop 0
	global_load_lds_dwordx4 v[212:213], off
	s_barrier
	s_waitcnt lgkmcnt(0)
	v_mfma_f32_16x16x32_bf16 v[116:119], v[196:199], v[144:147], v[116:119]
	v_mfma_f32_16x16x32_bf16 v[112:115], v[204:207], v[144:147], v[112:115]
	v_mfma_f32_16x16x32_bf16 v[100:103], v[196:199], v[164:167], v[100:103]
	v_mfma_f32_16x16x32_bf16 v[96:99], v[204:207], v[164:167], v[96:99]
	v_mfma_f32_16x16x32_bf16 v[84:87], v[196:199], v[180:183], v[84:87]
	v_mfma_f32_16x16x32_bf16 v[80:83], v[204:207], v[180:183], v[80:83]
	v_mfma_f32_16x16x32_bf16 v[68:71], v[196:199], v[188:191], v[68:71]
	v_mfma_f32_16x16x32_bf16 v[64:67], v[204:207], v[188:191], v[64:67]
	v_mfma_f32_16x16x32_bf16 v[116:119], v[200:203], v[148:151], v[116:119]
	v_mfma_f32_16x16x32_bf16 v[112:115], v[208:211], v[148:151], v[112:115]
	v_mfma_f32_16x16x32_bf16 v[100:103], v[200:203], v[168:171], v[100:103]
	v_mfma_f32_16x16x32_bf16 v[96:99], v[208:211], v[168:171], v[96:99]
	v_mfma_f32_16x16x32_bf16 v[84:87], v[200:203], v[184:187], v[84:87]
	v_mfma_f32_16x16x32_bf16 v[80:83], v[208:211], v[184:187], v[80:83]
	v_mfma_f32_16x16x32_bf16 v[68:71], v[200:203], v[192:195], v[68:71]
	v_mfma_f32_16x16x32_bf16 v[64:67], v[208:211], v[192:195], v[64:67]
	s_barrier
	s_mov_b32 m0, s31
	v_lshl_add_u64 v[212:213], v[216:217], 0, s[4:5]
	ds_read_b128 v[144:147], v176 offset:49152
	ds_read_b128 v[148:151], v176 offset:50176
	ds_read_b128 v[164:167], v176 offset:51200
	ds_read_b128 v[168:171], v176 offset:52224
	ds_read_b128 v[180:183], v176 offset:53248
	ds_read_b128 v[184:187], v176 offset:54272
	ds_read_b128 v[188:191], v176 offset:55296
	ds_read_b128 v[192:195], v176 offset:56320
	global_load_lds_dwordx4 v[212:213], off
	v_lshl_add_u64 v[212:213], v[218:219], 0, s[4:5]
	s_mov_b32 m0, s33
	s_nop 0
	global_load_lds_dwordx4 v[212:213], off
	s_barrier
	s_waitcnt lgkmcnt(0)
	v_mfma_f32_16x16x32_bf16 v[60:63], v[128:131], v[144:147], v[60:63]
	v_mfma_f32_16x16x32_bf16 v[56:59], v[136:139], v[144:147], v[56:59]
	v_mfma_f32_16x16x32_bf16 v[44:47], v[128:131], v[164:167], v[44:47]
	v_mfma_f32_16x16x32_bf16 v[40:43], v[136:139], v[164:167], v[40:43]
	v_mfma_f32_16x16x32_bf16 v[28:31], v[128:131], v[180:183], v[28:31]
	v_mfma_f32_16x16x32_bf16 v[24:27], v[136:139], v[180:183], v[24:27]
	v_mfma_f32_16x16x32_bf16 v[12:15], v[128:131], v[188:191], v[12:15]
	v_mfma_f32_16x16x32_bf16 v[8:11], v[136:139], v[188:191], v[8:11]
	v_mfma_f32_16x16x32_bf16 v[60:63], v[132:135], v[148:151], v[60:63]
	v_mfma_f32_16x16x32_bf16 v[56:59], v[140:143], v[148:151], v[56:59]
	v_mfma_f32_16x16x32_bf16 v[44:47], v[132:135], v[168:171], v[44:47]
	v_mfma_f32_16x16x32_bf16 v[40:43], v[140:143], v[168:171], v[40:43]
	v_mfma_f32_16x16x32_bf16 v[28:31], v[132:135], v[184:187], v[28:31]
	v_mfma_f32_16x16x32_bf16 v[24:27], v[140:143], v[184:187], v[24:27]
	v_mfma_f32_16x16x32_bf16 v[12:15], v[132:135], v[192:195], v[12:15]
	v_mfma_f32_16x16x32_bf16 v[8:11], v[140:143], v[192:195], v[8:11]
	s_barrier
	s_add_u32 s22, s22, 0x20080
	s_addc_u32 s23, s23, 0
	s_add_i32 s24, s24, s27
	v_lshl_add_u64 v[128:129], s[22:23], 0, v[156:157]
	s_mov_b32 m0, s24
	s_nop 0
	global_load_lds_dwordx4 v[128:129], off
	v_lshl_add_u64 v[128:129], s[22:23], 0, v[152:153]
	s_add_i32 m0, s24, 0x2000
	s_nop 0
	global_load_lds_dwordx4 v[128:129], off
	s_waitcnt vmcnt(6)
	s_barrier
	v_mfma_f32_16x16x32_bf16 v[52:55], v[196:199], v[144:147], v[52:55]
	v_mfma_f32_16x16x32_bf16 v[48:51], v[204:207], v[144:147], v[48:51]
	v_mfma_f32_16x16x32_bf16 v[36:39], v[196:199], v[164:167], v[36:39]
	v_mfma_f32_16x16x32_bf16 v[32:35], v[204:207], v[164:167], v[32:35]
	v_mfma_f32_16x16x32_bf16 v[20:23], v[196:199], v[180:183], v[20:23]
	v_mfma_f32_16x16x32_bf16 v[16:19], v[204:207], v[180:183], v[16:19]
	v_mfma_f32_16x16x32_bf16 v[4:7], v[196:199], v[188:191], v[4:7]
	v_mfma_f32_16x16x32_bf16 v[0:3], v[204:207], v[188:191], v[0:3]
	v_mfma_f32_16x16x32_bf16 v[52:55], v[200:203], v[148:151], v[52:55]
	v_mfma_f32_16x16x32_bf16 v[48:51], v[208:211], v[148:151], v[48:51]
	v_mfma_f32_16x16x32_bf16 v[36:39], v[200:203], v[168:171], v[36:39]
	v_mfma_f32_16x16x32_bf16 v[32:35], v[208:211], v[168:171], v[32:35]
	v_mfma_f32_16x16x32_bf16 v[20:23], v[200:203], v[184:187], v[20:23]
	v_mfma_f32_16x16x32_bf16 v[16:19], v[208:211], v[184:187], v[16:19]
	v_mfma_f32_16x16x32_bf16 v[4:7], v[200:203], v[192:195], v[4:7]
	v_mfma_f32_16x16x32_bf16 v[0:3], v[208:211], v[192:195], v[0:3]
	s_barrier
	s_add_i32 s43, s43, 2
	s_add_u32 s10, s10, 0x100
	s_addc_u32 s11, s11, 0
	s_add_u32 s41, s41, 0x100
	s_addc_u32 s42, s42, 0
	s_cmp_gt_u32 s43, 5
	s_cbranch_scc0 .LBB0_1285
	v_lshl_add_u32 v164, s38, 8, v172
	s_nop 0
	v_lshl_or_b32 v128, s0, 8, v174
	v_ashrrev_i32_e32 v165, 31, v164
	s_nop 1
	v_readlane_b32 s46, v252, 13
	v_readlane_b32 s47, v252, 14
	v_ashrrev_i32_e32 v129, 31, v128
	v_lshlrev_b64 v[130:131], 12, v[164:165]
	s_mov_b64 s[42:43], s[46:47]
	v_lshl_add_u64 v[130:131], s[42:43], 0, v[130:131]
	v_lshlrev_b64 v[132:133], 11, v[164:165]
	v_lshlrev_b64 v[166:167], 1, v[128:129]
	v_lshl_add_u64 v[132:133], s[82:83], 0, v[132:133]
	v_lshl_add_u64 v[128:129], v[130:131], 0, v[166:167]
	global_load_dwordx4 v[180:183], v[128:129], off offset:2048
	v_lshl_add_u64 v[222:223], v[132:133], 0, v[166:167]
	global_load_dwordx4 v[184:187], v[222:223], off
	global_load_dwordx4 v[188:191], v[128:129], off offset:2304
	global_load_dwordx4 v[192:195], v[222:223], off offset:256
	v_or_b32_e32 v128, 16, v164
	v_ashrrev_i32_e32 v129, 31, v128
	v_lshlrev_b64 v[130:131], 12, v[128:129]
	v_lshlrev_b64 v[128:129], 11, v[128:129]
	v_lshl_add_u64 v[130:131], s[42:43], 0, v[130:131]
	v_lshl_add_u64 v[128:129], s[82:83], 0, v[128:129]
	v_lshl_add_u64 v[130:131], v[130:131], 0, v[166:167]
	v_lshl_add_u64 v[224:225], v[128:129], 0, v[166:167]
	global_load_dwordx4 v[196:199], v[130:131], off offset:2048
	global_load_dwordx4 v[200:203], v[224:225], off
	v_or_b32_e32 v128, 32, v164
	v_or_b32_e32 v132, 48, v164
	v_ashrrev_i32_e32 v129, 31, v128
	v_ashrrev_i32_e32 v133, 31, v132
	v_lshlrev_b64 v[134:135], 12, v[128:129]
	v_lshlrev_b64 v[128:129], 11, v[128:129]
	v_lshlrev_b64 v[136:137], 12, v[132:133]
	v_lshlrev_b64 v[132:133], 11, v[132:133]
	v_lshl_add_u64 v[134:135], s[42:43], 0, v[134:135]
	v_lshl_add_u64 v[128:129], s[82:83], 0, v[128:129]
	v_lshl_add_u64 v[136:137], s[42:43], 0, v[136:137]
	v_lshl_add_u64 v[132:133], s[82:83], 0, v[132:133]
	v_lshl_add_u64 v[134:135], v[134:135], 0, v[166:167]
	v_lshl_add_u64 v[170:171], v[128:129], 0, v[166:167]
	v_lshl_add_u64 v[128:129], v[136:137], 0, v[166:167]
	v_lshl_add_u64 v[168:169], v[132:133], 0, v[166:167]
	global_load_dwordx4 v[204:207], v[130:131], off offset:2304
	global_load_dwordx4 v[208:211], v[224:225], off offset:256
	global_load_dwordx4 v[212:215], v[134:135], off offset:2048
	global_load_dwordx4 v[148:151], v[134:135], off offset:2304
	global_load_dwordx4 v[216:219], v[170:171], off
	global_load_dwordx4 v[144:147], v[170:171], off offset:256
	global_load_dwordx4 v[140:143], v[128:129], off offset:2048
	s_nop 0
	global_load_dwordx4 v[132:135], v[128:129], off offset:2304
	global_load_dwordx4 v[136:139], v[168:169], off
	s_nop 0
	global_load_dwordx4 v[128:131], v[168:169], off offset:256
	s_and_b64 vcc, exec, s[18:19]
	s_mov_b32 s0, s14
	s_mov_b32 s38, s12
	s_mov_b32 s15, s14
	s_mov_b32 s18, s12
	s_mov_b64 s[22:23], s[20:21]
	s_mov_b64 s[10:11], s[16:17]
	s_mov_b32 s13, s37
	s_nop 7
	s_nop 2
	s_waitcnt vmcnt(0)
	v_lshlrev_b32_e32 v228, 16, v184
	v_lshlrev_b32_e32 v226, 16, v180
	v_and_b32_e32 v227, 0xffff0000, v180
	v_and_b32_e32 v229, 0xffff0000, v184
	v_lshlrev_b32_e32 v180, 16, v181
	v_and_b32_e32 v181, 0xffff0000, v181
	v_lshlrev_b32_e32 v184, 16, v185
	v_and_b32_e32 v185, 0xffff0000, v185
	v_lshlrev_b32_e32 v230, 16, v182
	v_and_b32_e32 v231, 0xffff0000, v182
	v_lshlrev_b32_e32 v232, 16, v186
	v_and_b32_e32 v233, 0xffff0000, v186
	v_lshlrev_b32_e32 v182, 16, v183
	v_and_b32_e32 v183, 0xffff0000, v183
	v_lshlrev_b32_e32 v186, 16, v187
	v_and_b32_e32 v187, 0xffff0000, v187
	v_lshlrev_b32_e32 v234, 16, v188
	v_and_b32_e32 v235, 0xffff0000, v188
	v_lshlrev_b32_e32 v236, 16, v192
	v_and_b32_e32 v237, 0xffff0000, v192
	v_lshlrev_b32_e32 v188, 16, v189
	v_and_b32_e32 v189, 0xffff0000, v189
	v_lshlrev_b32_e32 v192, 16, v193
	v_and_b32_e32 v193, 0xffff0000, v193
	v_pk_fma_f32 v[124:125], v[124:125], v[226:227], v[228:229]
	v_pk_fma_f32 v[126:127], v[126:127], v[180:181], v[184:185]
	v_pk_fma_f32 v[120:121], v[120:121], v[230:231], v[232:233]
	v_pk_fma_f32 v[122:123], v[122:123], v[182:183], v[186:187]
	v_lshlrev_b32_e32 v238, 16, v190
	v_and_b32_e32 v239, 0xffff0000, v190
	v_lshlrev_b32_e32 v240, 16, v194
	v_pk_fma_f32 v[180:181], v[116:117], v[234:235], v[236:237]
	v_pk_fma_f32 v[182:183], v[118:119], v[188:189], v[192:193]
	v_cvt_pk_bf16_f32 v116, v124, v125
	v_cvt_pk_bf16_f32 v117, v126, v127
	v_cvt_pk_bf16_f32 v118, v120, v121
	v_cvt_pk_bf16_f32 v119, v122, v123
	v_and_b32_e32 v241, 0xffff0000, v194
	global_store_dwordx4 v[222:223], v[116:119], off
	s_nop 1
	v_pk_fma_f32 v[116:117], v[112:113], v[238:239], v[240:241]
	v_lshlrev_b32_e32 v112, 16, v191
	v_and_b32_e32 v113, 0xffff0000, v191
	v_lshlrev_b32_e32 v118, 16, v195
	v_and_b32_e32 v119, 0xffff0000, v195
	v_pk_fma_f32 v[118:119], v[114:115], v[112:113], v[118:119]
	v_cvt_pk_bf16_f32 v112, v180, v181
	v_cvt_pk_bf16_f32 v113, v182, v183
	v_cvt_pk_bf16_f32 v114, v116, v117
	v_cvt_pk_bf16_f32 v115, v118, v119
	global_store_dwordx4 v[222:223], v[112:115], off offset:256
	s_nop 1
	v_lshlrev_b32_e32 v112, 16, v196
	v_and_b32_e32 v113, 0xffff0000, v196
	v_lshlrev_b32_e32 v114, 16, v200
	v_and_b32_e32 v115, 0xffff0000, v200
	v_pk_fma_f32 v[108:109], v[108:109], v[112:113], v[114:115]
	v_lshlrev_b32_e32 v112, 16, v197
	v_and_b32_e32 v113, 0xffff0000, v197
	v_lshlrev_b32_e32 v114, 16, v201
	v_and_b32_e32 v115, 0xffff0000, v201
	v_pk_fma_f32 v[110:111], v[110:111], v[112:113], v[114:115]
	v_lshlrev_b32_e32 v112, 16, v198
	v_and_b32_e32 v113, 0xffff0000, v198
	v_lshlrev_b32_e32 v114, 16, v202
	v_and_b32_e32 v115, 0xffff0000, v202
	v_pk_fma_f32 v[112:113], v[104:105], v[112:113], v[114:115]
	v_lshlrev_b32_e32 v104, 16, v199
	v_and_b32_e32 v105, 0xffff0000, v199
	v_lshlrev_b32_e32 v114, 16, v203
	v_and_b32_e32 v115, 0xffff0000, v203
	v_pk_fma_f32 v[114:115], v[106:107], v[104:105], v[114:115]
	v_cvt_pk_bf16_f32 v104, v108, v109
	v_cvt_pk_bf16_f32 v105, v110, v111
	v_cvt_pk_bf16_f32 v106, v112, v113
	v_cvt_pk_bf16_f32 v107, v114, v115
	global_store_dwordx4 v[224:225], v[104:107], off
	s_nop 1
	v_lshlrev_b32_e32 v104, 16, v204
	v_and_b32_e32 v105, 0xffff0000, v204
	v_lshlrev_b32_e32 v106, 16, v208
	v_and_b32_e32 v107, 0xffff0000, v208
	v_pk_fma_f32 v[100:101], v[100:101], v[104:105], v[106:107]
	v_lshlrev_b32_e32 v104, 16, v205
	v_and_b32_e32 v105, 0xffff0000, v205
	v_lshlrev_b32_e32 v106, 16, v209
	v_and_b32_e32 v107, 0xffff0000, v209
	v_pk_fma_f32 v[102:103], v[102:103], v[104:105], v[106:107]
	v_lshlrev_b32_e32 v104, 16, v206
	v_and_b32_e32 v105, 0xffff0000, v206
	v_lshlrev_b32_e32 v106, 16, v210
	v_and_b32_e32 v107, 0xffff0000, v210
	v_pk_fma_f32 v[104:105], v[96:97], v[104:105], v[106:107]
	v_lshlrev_b32_e32 v96, 16, v207
	v_and_b32_e32 v97, 0xffff0000, v207
	v_lshlrev_b32_e32 v106, 16, v211
	v_and_b32_e32 v107, 0xffff0000, v211
	v_pk_fma_f32 v[106:107], v[98:99], v[96:97], v[106:107]
	v_cvt_pk_bf16_f32 v96, v100, v101
	v_cvt_pk_bf16_f32 v97, v102, v103
	v_cvt_pk_bf16_f32 v98, v104, v105
	v_cvt_pk_bf16_f32 v99, v106, v107
	global_store_dwordx4 v[224:225], v[96:99], off offset:256
	s_nop 1
	v_lshlrev_b32_e32 v96, 16, v212
	v_and_b32_e32 v97, 0xffff0000, v212
	v_lshlrev_b32_e32 v98, 16, v216
	v_and_b32_e32 v99, 0xffff0000, v216
	v_pk_fma_f32 v[92:93], v[92:93], v[96:97], v[98:99]
	v_lshlrev_b32_e32 v96, 16, v213
	v_and_b32_e32 v97, 0xffff0000, v213
	v_lshlrev_b32_e32 v98, 16, v217
	v_and_b32_e32 v99, 0xffff0000, v217
	v_pk_fma_f32 v[94:95], v[94:95], v[96:97], v[98:99]
	v_lshlrev_b32_e32 v96, 16, v214
	v_and_b32_e32 v97, 0xffff0000, v214
	v_lshlrev_b32_e32 v98, 16, v218
	v_and_b32_e32 v99, 0xffff0000, v218
	v_pk_fma_f32 v[96:97], v[88:89], v[96:97], v[98:99]
	v_lshlrev_b32_e32 v88, 16, v215
	v_and_b32_e32 v89, 0xffff0000, v215
	v_lshlrev_b32_e32 v98, 16, v219
	v_and_b32_e32 v99, 0xffff0000, v219
	v_pk_fma_f32 v[98:99], v[90:91], v[88:89], v[98:99]
	v_cvt_pk_bf16_f32 v88, v92, v93
	v_cvt_pk_bf16_f32 v89, v94, v95
	v_cvt_pk_bf16_f32 v90, v96, v97
	v_cvt_pk_bf16_f32 v91, v98, v99
	global_store_dwordx4 v[170:171], v[88:91], off
	s_nop 1
	v_lshlrev_b32_e32 v88, 16, v148
	v_and_b32_e32 v89, 0xffff0000, v148
	v_lshlrev_b32_e32 v90, 16, v144
	v_and_b32_e32 v91, 0xffff0000, v144
	v_pk_fma_f32 v[84:85], v[84:85], v[88:89], v[90:91]
	v_lshlrev_b32_e32 v88, 16, v149
	v_and_b32_e32 v89, 0xffff0000, v149
	v_lshlrev_b32_e32 v90, 16, v145
	v_and_b32_e32 v91, 0xffff0000, v145
	v_pk_fma_f32 v[86:87], v[86:87], v[88:89], v[90:91]
	v_lshlrev_b32_e32 v88, 16, v150
	v_and_b32_e32 v89, 0xffff0000, v150
	v_lshlrev_b32_e32 v90, 16, v146
	v_and_b32_e32 v91, 0xffff0000, v146
	v_pk_fma_f32 v[88:89], v[80:81], v[88:89], v[90:91]
	v_lshlrev_b32_e32 v80, 16, v151
	v_and_b32_e32 v81, 0xffff0000, v151
	v_lshlrev_b32_e32 v90, 16, v147
	v_and_b32_e32 v91, 0xffff0000, v147
	v_pk_fma_f32 v[90:91], v[82:83], v[80:81], v[90:91]
	v_cvt_pk_bf16_f32 v80, v84, v85
	v_cvt_pk_bf16_f32 v81, v86, v87
	v_cvt_pk_bf16_f32 v82, v88, v89
	v_cvt_pk_bf16_f32 v83, v90, v91
	global_store_dwordx4 v[170:171], v[80:83], off offset:256
	s_nop 1
	v_lshlrev_b32_e32 v80, 16, v140
	v_and_b32_e32 v81, 0xffff0000, v140
	v_lshlrev_b32_e32 v82, 16, v136
	v_and_b32_e32 v83, 0xffff0000, v136
	v_pk_fma_f32 v[76:77], v[76:77], v[80:81], v[82:83]
	v_lshlrev_b32_e32 v80, 16, v141
	v_and_b32_e32 v81, 0xffff0000, v141
	v_lshlrev_b32_e32 v82, 16, v137
	v_and_b32_e32 v83, 0xffff0000, v137
	v_pk_fma_f32 v[78:79], v[78:79], v[80:81], v[82:83]
	v_lshlrev_b32_e32 v80, 16, v142
	v_and_b32_e32 v81, 0xffff0000, v142
	v_lshlrev_b32_e32 v82, 16, v138
	v_and_b32_e32 v83, 0xffff0000, v138
	v_pk_fma_f32 v[80:81], v[72:73], v[80:81], v[82:83]
	v_lshlrev_b32_e32 v72, 16, v143
	v_and_b32_e32 v73, 0xffff0000, v143
	v_lshlrev_b32_e32 v82, 16, v139
	v_and_b32_e32 v83, 0xffff0000, v139
	v_pk_fma_f32 v[82:83], v[74:75], v[72:73], v[82:83]
	v_cvt_pk_bf16_f32 v72, v76, v77
	v_cvt_pk_bf16_f32 v73, v78, v79
	v_cvt_pk_bf16_f32 v74, v80, v81
	v_cvt_pk_bf16_f32 v75, v82, v83
	global_store_dwordx4 v[168:169], v[72:75], off
	s_nop 1
	v_lshlrev_b32_e32 v72, 16, v132
	v_and_b32_e32 v73, 0xffff0000, v132
	v_lshlrev_b32_e32 v74, 16, v128
	v_and_b32_e32 v75, 0xffff0000, v128
	v_pk_fma_f32 v[68:69], v[68:69], v[72:73], v[74:75]
	v_lshlrev_b32_e32 v72, 16, v133
	v_and_b32_e32 v73, 0xffff0000, v133
	v_lshlrev_b32_e32 v74, 16, v129
	v_and_b32_e32 v75, 0xffff0000, v129
	v_pk_fma_f32 v[70:71], v[70:71], v[72:73], v[74:75]
	v_lshlrev_b32_e32 v72, 16, v134
	v_and_b32_e32 v73, 0xffff0000, v134
	v_lshlrev_b32_e32 v74, 16, v130
	v_and_b32_e32 v75, 0xffff0000, v130
	v_pk_fma_f32 v[72:73], v[64:65], v[72:73], v[74:75]
	v_lshlrev_b32_e32 v64, 16, v135
	v_and_b32_e32 v65, 0xffff0000, v135
	v_lshlrev_b32_e32 v74, 16, v131
	v_and_b32_e32 v75, 0xffff0000, v131
	v_pk_fma_f32 v[74:75], v[66:67], v[64:65], v[74:75]
	v_cvt_pk_bf16_f32 v64, v68, v69
	v_cvt_pk_bf16_f32 v65, v70, v71
	v_cvt_pk_bf16_f32 v66, v72, v73
	v_cvt_pk_bf16_f32 v67, v74, v75
	global_store_dwordx4 v[168:169], v[64:67], off offset:256
	s_nop 1
	v_add_u32_e32 v64, 0x80, v164
	v_ashrrev_i32_e32 v65, 31, v64
	v_lshlrev_b64 v[66:67], 12, v[64:65]
	v_lshl_add_u64 v[66:67], s[42:43], 0, v[66:67]
	v_lshlrev_b64 v[64:65], 11, v[64:65]
	v_lshl_add_u64 v[66:67], v[66:67], 0, v[166:167]
	v_lshl_add_u64 v[64:65], s[82:83], 0, v[64:65]
	global_load_dwordx4 v[92:95], v[66:67], off offset:2048
	v_lshl_add_u64 v[132:133], v[64:65], 0, v[166:167]
	global_load_dwordx4 v[96:99], v[132:133], off
	global_load_dwordx4 v[100:103], v[66:67], off offset:2304
	global_load_dwordx4 v[104:107], v[132:133], off offset:256
	v_add_u32_e32 v64, 0x90, v164
	v_ashrrev_i32_e32 v65, 31, v64
	v_lshlrev_b64 v[66:67], 12, v[64:65]
	v_lshl_add_u64 v[66:67], s[42:43], 0, v[66:67]
	v_lshlrev_b64 v[64:65], 11, v[64:65]
	v_lshl_add_u64 v[66:67], v[66:67], 0, v[166:167]
	v_lshl_add_u64 v[64:65], s[82:83], 0, v[64:65]
	global_load_dwordx4 v[108:111], v[66:67], off offset:2048
	v_lshl_add_u64 v[134:135], v[64:65], 0, v[166:167]
	global_load_dwordx4 v[112:115], v[134:135], off
	global_load_dwordx4 v[116:119], v[66:67], off offset:2304
	global_load_dwordx4 v[120:123], v[134:135], off offset:256
	v_add_u32_e32 v64, 0xa0, v164
	v_ashrrev_i32_e32 v65, 31, v64
	v_lshlrev_b64 v[66:67], 12, v[64:65]
	v_lshl_add_u64 v[66:67], s[42:43], 0, v[66:67]
	v_lshlrev_b64 v[64:65], 11, v[64:65]
	v_lshl_add_u64 v[64:65], s[82:83], 0, v[64:65]
	v_lshl_add_u64 v[66:67], v[66:67], 0, v[166:167]
	v_lshl_add_u64 v[90:91], v[64:65], 0, v[166:167]
	global_load_dwordx4 v[124:127], v[66:67], off offset:2048
	global_load_dwordx4 v[84:87], v[66:67], off offset:2304
	global_load_dwordx4 v[128:131], v[90:91], off
	global_load_dwordx4 v[80:83], v[90:91], off offset:256
	v_add_u32_e32 v64, 0xb0, v164
	v_ashrrev_i32_e32 v65, 31, v64
	v_lshlrev_b64 v[66:67], 12, v[64:65]
	v_lshl_add_u64 v[66:67], s[42:43], 0, v[66:67]
	v_lshlrev_b64 v[64:65], 11, v[64:65]
	v_lshl_add_u64 v[64:65], s[82:83], 0, v[64:65]
	v_lshl_add_u64 v[66:67], v[66:67], 0, v[166:167]
	v_lshl_add_u64 v[88:89], v[64:65], 0, v[166:167]
	global_load_dwordx4 v[76:79], v[66:67], off offset:2048
	global_load_dwordx4 v[68:71], v[66:67], off offset:2304
	global_load_dwordx4 v[72:75], v[88:89], off
	s_nop 0
	global_load_dwordx4 v[64:67], v[88:89], off offset:256
	s_waitcnt vmcnt(0)
	v_lshlrev_b32_e32 v136, 16, v92
	v_and_b32_e32 v137, 0xffff0000, v92
	v_lshlrev_b32_e32 v138, 16, v96
	v_and_b32_e32 v139, 0xffff0000, v96
	v_lshlrev_b32_e32 v92, 16, v93
	v_and_b32_e32 v93, 0xffff0000, v93
	v_lshlrev_b32_e32 v96, 16, v97
	v_and_b32_e32 v97, 0xffff0000, v97
	v_pk_fma_f32 v[62:63], v[62:63], v[92:93], v[96:97]
	v_lshlrev_b32_e32 v92, 16, v94
	v_and_b32_e32 v93, 0xffff0000, v94
	v_lshlrev_b32_e32 v96, 16, v98
	v_and_b32_e32 v97, 0xffff0000, v98
	v_pk_fma_f32 v[92:93], v[56:57], v[92:93], v[96:97]
	v_lshlrev_b32_e32 v56, 16, v95
	v_and_b32_e32 v57, 0xffff0000, v95
	v_lshlrev_b32_e32 v94, 16, v99
	v_and_b32_e32 v95, 0xffff0000, v99
	v_pk_fma_f32 v[60:61], v[60:61], v[136:137], v[138:139]
	v_pk_fma_f32 v[94:95], v[58:59], v[56:57], v[94:95]
	v_cvt_pk_bf16_f32 v56, v60, v61
	v_cvt_pk_bf16_f32 v57, v62, v63
	v_cvt_pk_bf16_f32 v58, v92, v93
	v_cvt_pk_bf16_f32 v59, v94, v95
	global_store_dwordx4 v[132:133], v[56:59], off
	s_nop 1
	v_lshlrev_b32_e32 v56, 16, v100
	v_and_b32_e32 v57, 0xffff0000, v100
	v_lshlrev_b32_e32 v58, 16, v104
	v_and_b32_e32 v59, 0xffff0000, v104
	v_pk_fma_f32 v[52:53], v[52:53], v[56:57], v[58:59]
	v_lshlrev_b32_e32 v56, 16, v101
	v_and_b32_e32 v57, 0xffff0000, v101
	v_lshlrev_b32_e32 v58, 16, v105
	v_and_b32_e32 v59, 0xffff0000, v105
	v_pk_fma_f32 v[54:55], v[54:55], v[56:57], v[58:59]
	v_lshlrev_b32_e32 v56, 16, v102
	v_and_b32_e32 v57, 0xffff0000, v102
	v_lshlrev_b32_e32 v58, 16, v106
	v_and_b32_e32 v59, 0xffff0000, v106
	v_pk_fma_f32 v[56:57], v[48:49], v[56:57], v[58:59]
	v_lshlrev_b32_e32 v48, 16, v103
	v_and_b32_e32 v49, 0xffff0000, v103
	v_lshlrev_b32_e32 v58, 16, v107
	v_and_b32_e32 v59, 0xffff0000, v107
	v_pk_fma_f32 v[58:59], v[50:51], v[48:49], v[58:59]
	v_cvt_pk_bf16_f32 v48, v52, v53
	v_cvt_pk_bf16_f32 v49, v54, v55
	v_cvt_pk_bf16_f32 v50, v56, v57
	v_cvt_pk_bf16_f32 v51, v58, v59
	global_store_dwordx4 v[132:133], v[48:51], off offset:256
	s_nop 1
	v_lshlrev_b32_e32 v48, 16, v108
	v_and_b32_e32 v49, 0xffff0000, v108
	v_lshlrev_b32_e32 v50, 16, v112
	v_and_b32_e32 v51, 0xffff0000, v112
	v_pk_fma_f32 v[44:45], v[44:45], v[48:49], v[50:51]
	v_lshlrev_b32_e32 v48, 16, v109
	v_and_b32_e32 v49, 0xffff0000, v109
	v_lshlrev_b32_e32 v50, 16, v113
	v_and_b32_e32 v51, 0xffff0000, v113
	v_pk_fma_f32 v[46:47], v[46:47], v[48:49], v[50:51]
	v_lshlrev_b32_e32 v48, 16, v110
	v_and_b32_e32 v49, 0xffff0000, v110
	v_lshlrev_b32_e32 v50, 16, v114
	v_and_b32_e32 v51, 0xffff0000, v114
	v_pk_fma_f32 v[48:49], v[40:41], v[48:49], v[50:51]
	v_lshlrev_b32_e32 v40, 16, v111
	v_and_b32_e32 v41, 0xffff0000, v111
	v_lshlrev_b32_e32 v50, 16, v115
	v_and_b32_e32 v51, 0xffff0000, v115
	v_pk_fma_f32 v[50:51], v[42:43], v[40:41], v[50:51]
	v_cvt_pk_bf16_f32 v40, v44, v45
	v_cvt_pk_bf16_f32 v41, v46, v47
	v_cvt_pk_bf16_f32 v42, v48, v49
	v_cvt_pk_bf16_f32 v43, v50, v51
	global_store_dwordx4 v[134:135], v[40:43], off
	s_nop 1
	v_lshlrev_b32_e32 v40, 16, v116
	v_and_b32_e32 v41, 0xffff0000, v116
	v_lshlrev_b32_e32 v42, 16, v120
	v_and_b32_e32 v43, 0xffff0000, v120
	v_pk_fma_f32 v[36:37], v[36:37], v[40:41], v[42:43]
	v_lshlrev_b32_e32 v40, 16, v117
	v_and_b32_e32 v41, 0xffff0000, v117
	v_lshlrev_b32_e32 v42, 16, v121
	v_and_b32_e32 v43, 0xffff0000, v121
	v_pk_fma_f32 v[38:39], v[38:39], v[40:41], v[42:43]
	v_lshlrev_b32_e32 v40, 16, v118
	v_and_b32_e32 v41, 0xffff0000, v118
	v_lshlrev_b32_e32 v42, 16, v122
	v_and_b32_e32 v43, 0xffff0000, v122
	v_pk_fma_f32 v[40:41], v[32:33], v[40:41], v[42:43]
	v_lshlrev_b32_e32 v32, 16, v119
	v_and_b32_e32 v33, 0xffff0000, v119
	v_lshlrev_b32_e32 v42, 16, v123
	v_and_b32_e32 v43, 0xffff0000, v123
	v_pk_fma_f32 v[42:43], v[34:35], v[32:33], v[42:43]
	v_cvt_pk_bf16_f32 v32, v36, v37
	v_cvt_pk_bf16_f32 v33, v38, v39
	v_cvt_pk_bf16_f32 v34, v40, v41
	v_cvt_pk_bf16_f32 v35, v42, v43
	global_store_dwordx4 v[134:135], v[32:35], off offset:256
	s_nop 1
	v_lshlrev_b32_e32 v32, 16, v124
	v_and_b32_e32 v33, 0xffff0000, v124
	v_lshlrev_b32_e32 v34, 16, v128
	v_and_b32_e32 v35, 0xffff0000, v128
	v_pk_fma_f32 v[28:29], v[28:29], v[32:33], v[34:35]
	v_lshlrev_b32_e32 v32, 16, v125
	v_and_b32_e32 v33, 0xffff0000, v125
	v_lshlrev_b32_e32 v34, 16, v129
	v_and_b32_e32 v35, 0xffff0000, v129
	v_pk_fma_f32 v[30:31], v[30:31], v[32:33], v[34:35]
	v_lshlrev_b32_e32 v32, 16, v126
	v_and_b32_e32 v33, 0xffff0000, v126
	v_lshlrev_b32_e32 v34, 16, v130
	v_and_b32_e32 v35, 0xffff0000, v130
	v_pk_fma_f32 v[32:33], v[24:25], v[32:33], v[34:35]
	v_lshlrev_b32_e32 v24, 16, v127
	v_and_b32_e32 v25, 0xffff0000, v127
	v_lshlrev_b32_e32 v34, 16, v131
	v_and_b32_e32 v35, 0xffff0000, v131
	v_pk_fma_f32 v[34:35], v[26:27], v[24:25], v[34:35]
	v_cvt_pk_bf16_f32 v24, v28, v29
	v_cvt_pk_bf16_f32 v25, v30, v31
	v_cvt_pk_bf16_f32 v26, v32, v33
	v_cvt_pk_bf16_f32 v27, v34, v35
	global_store_dwordx4 v[90:91], v[24:27], off
	s_nop 1
	v_lshlrev_b32_e32 v24, 16, v84
	v_and_b32_e32 v25, 0xffff0000, v84
	v_lshlrev_b32_e32 v26, 16, v80
	v_and_b32_e32 v27, 0xffff0000, v80
	v_pk_fma_f32 v[20:21], v[20:21], v[24:25], v[26:27]
	v_lshlrev_b32_e32 v24, 16, v85
	v_and_b32_e32 v25, 0xffff0000, v85
	v_lshlrev_b32_e32 v26, 16, v81
	v_and_b32_e32 v27, 0xffff0000, v81
	v_pk_fma_f32 v[22:23], v[22:23], v[24:25], v[26:27]
	v_lshlrev_b32_e32 v24, 16, v86
	v_and_b32_e32 v25, 0xffff0000, v86
	v_lshlrev_b32_e32 v26, 16, v82
	v_and_b32_e32 v27, 0xffff0000, v82
	v_pk_fma_f32 v[24:25], v[16:17], v[24:25], v[26:27]
	v_lshlrev_b32_e32 v16, 16, v87
	v_and_b32_e32 v17, 0xffff0000, v87
	v_lshlrev_b32_e32 v26, 16, v83
	v_and_b32_e32 v27, 0xffff0000, v83
	v_pk_fma_f32 v[26:27], v[18:19], v[16:17], v[26:27]
	v_cvt_pk_bf16_f32 v16, v20, v21
	v_cvt_pk_bf16_f32 v17, v22, v23
	v_cvt_pk_bf16_f32 v18, v24, v25
	v_cvt_pk_bf16_f32 v19, v26, v27
	global_store_dwordx4 v[90:91], v[16:19], off offset:256
	s_nop 1
	v_lshlrev_b32_e32 v16, 16, v76
	v_and_b32_e32 v17, 0xffff0000, v76
	v_lshlrev_b32_e32 v18, 16, v72
	v_and_b32_e32 v19, 0xffff0000, v72
	v_pk_fma_f32 v[12:13], v[12:13], v[16:17], v[18:19]
	v_lshlrev_b32_e32 v16, 16, v77
	v_and_b32_e32 v17, 0xffff0000, v77
	v_lshlrev_b32_e32 v18, 16, v73
	v_and_b32_e32 v19, 0xffff0000, v73
	v_pk_fma_f32 v[14:15], v[14:15], v[16:17], v[18:19]
	v_lshlrev_b32_e32 v16, 16, v78
	v_and_b32_e32 v17, 0xffff0000, v78
	v_lshlrev_b32_e32 v18, 16, v74
	v_and_b32_e32 v19, 0xffff0000, v74
	v_pk_fma_f32 v[16:17], v[8:9], v[16:17], v[18:19]
	v_lshlrev_b32_e32 v8, 16, v79
	v_and_b32_e32 v9, 0xffff0000, v79
	v_lshlrev_b32_e32 v18, 16, v75
	v_and_b32_e32 v19, 0xffff0000, v75
	v_pk_fma_f32 v[18:19], v[10:11], v[8:9], v[18:19]
	v_cvt_pk_bf16_f32 v8, v12, v13
	v_cvt_pk_bf16_f32 v9, v14, v15
	v_cvt_pk_bf16_f32 v10, v16, v17
	v_cvt_pk_bf16_f32 v11, v18, v19
	global_store_dwordx4 v[88:89], v[8:11], off
	s_nop 1
	v_lshlrev_b32_e32 v8, 16, v68
	v_and_b32_e32 v9, 0xffff0000, v68
	v_lshlrev_b32_e32 v10, 16, v64
	v_and_b32_e32 v11, 0xffff0000, v64
	v_pk_fma_f32 v[4:5], v[4:5], v[8:9], v[10:11]
	v_lshlrev_b32_e32 v8, 16, v69
	v_and_b32_e32 v9, 0xffff0000, v69
	v_lshlrev_b32_e32 v10, 16, v65
	v_and_b32_e32 v11, 0xffff0000, v65
	v_pk_fma_f32 v[6:7], v[6:7], v[8:9], v[10:11]
	v_lshlrev_b32_e32 v8, 16, v70
	v_and_b32_e32 v9, 0xffff0000, v70
	v_lshlrev_b32_e32 v10, 16, v66
	v_and_b32_e32 v11, 0xffff0000, v66
	v_pk_fma_f32 v[8:9], v[0:1], v[8:9], v[10:11]
	v_lshlrev_b32_e32 v0, 16, v71
	v_and_b32_e32 v1, 0xffff0000, v71
	v_lshlrev_b32_e32 v10, 16, v67
	v_and_b32_e32 v11, 0xffff0000, v67
	v_pk_fma_f32 v[10:11], v[2:3], v[0:1], v[10:11]
	v_cvt_pk_bf16_f32 v0, v4, v5
	v_cvt_pk_bf16_f32 v1, v6, v7
	v_cvt_pk_bf16_f32 v2, v8, v9
	v_cvt_pk_bf16_f32 v3, v10, v11
	global_store_dwordx4 v[88:89], v[0:3], off offset:256
	s_cbranch_vccz .LBB0_1277
	s_waitcnt vmcnt(0)
	s_cmpk_gt_u32 s26, 0xff
	s_cbranch_scc1 .LBB0_1289
	s_barrier

.LBB0_1356:
	ds_read_b128 v[144:147], v190
	ds_read_b128 v[148:151], v190 offset:1024
	ds_read_b128 v[166:169], v190 offset:2048
	ds_read_b128 v[170:173], v190 offset:3072
	ds_read_b128 v[174:177], v190 offset:4096
	ds_read_b128 v[180:183], v190 offset:5120
	ds_read_b128 v[184:187], v190 offset:6144
	ds_read_b128 v[194:197], v190 offset:7168
	ds_read_b128 v[128:131], v189
	ds_read_b128 v[132:135], v189 offset:1024
	ds_read_b128 v[136:139], v189 offset:2048
	ds_read_b128 v[140:143], v189 offset:3072
	s_add_u32 s24, s10, 0xfffc0080
	s_addc_u32 s25, s11, -1
	s_cmp_eq_u32 s47, 12
	s_cselect_b32 s27, s15, s25
	s_cselect_b32 s26, s29, s24
	s_cselect_b32 s25, s17, s46
	s_cselect_b32 s24, s44, s45
	v_lshl_add_u64 v[198:199], s[10:11], 0, v[162:163]
	s_add_i32 m0, s7, 0xc000
	s_nop 0
	global_load_lds_dwordx4 v[198:199], off
	v_lshl_add_u64 v[198:199], s[10:11], 0, v[164:165]
	s_add_i32 m0, s7, 0xe000
	s_nop 0
	global_load_lds_dwordx4 v[198:199], off
	s_waitcnt lgkmcnt(0)
	s_barrier
	v_mfma_f32_16x16x32_bf16 v[124:127], v[128:131], v[144:147], v[124:127]
	v_mfma_f32_16x16x32_bf16 v[120:123], v[136:139], v[144:147], v[120:123]
	v_mfma_f32_16x16x32_bf16 v[108:111], v[128:131], v[166:169], v[108:111]
	v_mfma_f32_16x16x32_bf16 v[104:107], v[136:139], v[166:169], v[104:107]
	v_mfma_f32_16x16x32_bf16 v[92:95], v[128:131], v[174:177], v[92:95]
	v_mfma_f32_16x16x32_bf16 v[88:91], v[136:139], v[174:177], v[88:91]
	v_mfma_f32_16x16x32_bf16 v[76:79], v[128:131], v[184:187], v[76:79]
	v_mfma_f32_16x16x32_bf16 v[72:75], v[136:139], v[184:187], v[72:75]
	v_mfma_f32_16x16x32_bf16 v[124:127], v[132:135], v[148:151], v[124:127]
	v_mfma_f32_16x16x32_bf16 v[120:123], v[140:143], v[148:151], v[120:123]
	v_mfma_f32_16x16x32_bf16 v[108:111], v[132:135], v[170:173], v[108:111]
	v_mfma_f32_16x16x32_bf16 v[104:107], v[140:143], v[170:173], v[104:107]
	v_mfma_f32_16x16x32_bf16 v[92:95], v[132:135], v[180:183], v[92:95]
	v_mfma_f32_16x16x32_bf16 v[88:91], v[140:143], v[180:183], v[88:91]
	v_mfma_f32_16x16x32_bf16 v[76:79], v[132:135], v[194:197], v[76:79]
	v_mfma_f32_16x16x32_bf16 v[72:75], v[140:143], v[194:197], v[72:75]
	s_barrier
	s_add_i32 s48, s41, s33
	v_lshl_add_u64 v[214:215], s[24:25], 0, v[156:157]
	s_mov_b32 m0, s48
	ds_read_b128 v[198:201], v191
	ds_read_b128 v[202:205], v191 offset:1024
	ds_read_b128 v[206:209], v191 offset:2048
	ds_read_b128 v[210:213], v191 offset:3072
	global_load_lds_dwordx4 v[214:215], off
	v_lshl_add_u64 v[216:217], s[24:25], 0, v[152:153]
	s_add_i32 m0, s48, 0x2000
	s_nop 0
	global_load_lds_dwordx4 v[216:217], off
	s_barrier
	s_waitcnt lgkmcnt(0)
	v_mfma_f32_16x16x32_bf16 v[116:119], v[198:201], v[144:147], v[116:119]
	v_mfma_f32_16x16x32_bf16 v[112:115], v[206:209], v[144:147], v[112:115]
	v_mfma_f32_16x16x32_bf16 v[100:103], v[198:201], v[166:169], v[100:103]
	v_mfma_f32_16x16x32_bf16 v[96:99], v[206:209], v[166:169], v[96:99]
	v_mfma_f32_16x16x32_bf16 v[84:87], v[198:201], v[174:177], v[84:87]
	v_mfma_f32_16x16x32_bf16 v[80:83], v[206:209], v[174:177], v[80:83]
	v_mfma_f32_16x16x32_bf16 v[68:71], v[198:201], v[184:187], v[68:71]
	v_mfma_f32_16x16x32_bf16 v[64:67], v[206:209], v[184:187], v[64:67]
	v_mfma_f32_16x16x32_bf16 v[116:119], v[202:205], v[148:151], v[116:119]
	v_mfma_f32_16x16x32_bf16 v[112:115], v[210:213], v[148:151], v[112:115]
	v_mfma_f32_16x16x32_bf16 v[100:103], v[202:205], v[170:173], v[100:103]
	v_mfma_f32_16x16x32_bf16 v[96:99], v[210:213], v[170:173], v[96:99]
	v_mfma_f32_16x16x32_bf16 v[84:87], v[202:205], v[180:183], v[84:87]
	v_mfma_f32_16x16x32_bf16 v[80:83], v[210:213], v[180:183], v[80:83]
	v_mfma_f32_16x16x32_bf16 v[68:71], v[202:205], v[194:197], v[68:71]
	v_mfma_f32_16x16x32_bf16 v[64:67], v[210:213], v[194:197], v[64:67]
	s_barrier
	s_mov_b32 m0, s7
	v_lshl_add_u64 v[218:219], s[26:27], 0, v[158:159]
	ds_read_b128 v[144:147], v190 offset:16384
	ds_read_b128 v[148:151], v190 offset:17408
	ds_read_b128 v[166:169], v190 offset:18432
	ds_read_b128 v[170:173], v190 offset:19456
	ds_read_b128 v[174:177], v190 offset:20480
	ds_read_b128 v[180:183], v190 offset:21504
	ds_read_b128 v[184:187], v190 offset:22528
	ds_read_b128 v[194:197], v190 offset:23552
	global_load_lds_dwordx4 v[218:219], off
	v_lshl_add_u64 v[222:223], s[26:27], 0, v[154:155]
	s_mov_b32 m0, s35
	s_nop 0
	global_load_lds_dwordx4 v[222:223], off
	s_barrier
	s_waitcnt lgkmcnt(0)
	v_mfma_f32_16x16x32_bf16 v[60:63], v[128:131], v[144:147], v[60:63]
	v_mfma_f32_16x16x32_bf16 v[56:59], v[136:139], v[144:147], v[56:59]
	v_mfma_f32_16x16x32_bf16 v[44:47], v[128:131], v[166:169], v[44:47]
	v_mfma_f32_16x16x32_bf16 v[40:43], v[136:139], v[166:169], v[40:43]
	v_mfma_f32_16x16x32_bf16 v[28:31], v[128:131], v[174:177], v[28:31]
	v_mfma_f32_16x16x32_bf16 v[24:27], v[136:139], v[174:177], v[24:27]
	v_mfma_f32_16x16x32_bf16 v[12:15], v[128:131], v[184:187], v[12:15]
	v_mfma_f32_16x16x32_bf16 v[8:11], v[136:139], v[184:187], v[8:11]
	v_mfma_f32_16x16x32_bf16 v[60:63], v[132:135], v[148:151], v[60:63]
	v_mfma_f32_16x16x32_bf16 v[56:59], v[140:143], v[148:151], v[56:59]
	v_mfma_f32_16x16x32_bf16 v[44:47], v[132:135], v[170:173], v[44:47]
	v_mfma_f32_16x16x32_bf16 v[40:43], v[140:143], v[170:173], v[40:43]
	v_mfma_f32_16x16x32_bf16 v[28:31], v[132:135], v[180:183], v[28:31]
	v_mfma_f32_16x16x32_bf16 v[24:27], v[140:143], v[180:183], v[24:27]
	v_mfma_f32_16x16x32_bf16 v[12:15], v[132:135], v[194:197], v[12:15]
	v_mfma_f32_16x16x32_bf16 v[8:11], v[140:143], v[194:197], v[8:11]
	s_barrier
	s_add_u32 s48, s24, 0x40000
	s_addc_u32 s49, s25, 0
	s_add_i32 s50, s42, s33
	v_lshl_add_u64 v[128:129], s[48:49], 0, v[156:157]
	s_mov_b32 m0, s50
	s_nop 0
	global_load_lds_dwordx4 v[128:129], off
	v_lshl_add_u64 v[128:129], s[48:49], 0, v[152:153]
	s_add_i32 m0, s50, 0x2000
	s_nop 0
	global_load_lds_dwordx4 v[128:129], off
	s_waitcnt vmcnt(6)
	s_barrier
	v_mfma_f32_16x16x32_bf16 v[52:55], v[198:201], v[144:147], v[52:55]
	v_mfma_f32_16x16x32_bf16 v[48:51], v[206:209], v[144:147], v[48:51]
	v_mfma_f32_16x16x32_bf16 v[36:39], v[198:201], v[166:169], v[36:39]
	v_mfma_f32_16x16x32_bf16 v[32:35], v[206:209], v[166:169], v[32:35]
	v_mfma_f32_16x16x32_bf16 v[20:23], v[198:201], v[174:177], v[20:23]
	v_mfma_f32_16x16x32_bf16 v[16:19], v[206:209], v[174:177], v[16:19]
	v_mfma_f32_16x16x32_bf16 v[4:7], v[198:201], v[184:187], v[4:7]
	v_mfma_f32_16x16x32_bf16 v[0:3], v[206:209], v[184:187], v[0:3]
	v_mfma_f32_16x16x32_bf16 v[52:55], v[202:205], v[148:151], v[52:55]
	v_mfma_f32_16x16x32_bf16 v[48:51], v[210:213], v[148:151], v[48:51]
	v_mfma_f32_16x16x32_bf16 v[36:39], v[202:205], v[170:173], v[36:39]
	v_mfma_f32_16x16x32_bf16 v[32:35], v[210:213], v[170:173], v[32:35]
	v_mfma_f32_16x16x32_bf16 v[20:23], v[202:205], v[180:183], v[20:23]
	v_mfma_f32_16x16x32_bf16 v[16:19], v[210:213], v[180:183], v[16:19]
	v_mfma_f32_16x16x32_bf16 v[4:7], v[202:205], v[194:197], v[4:7]
	v_mfma_f32_16x16x32_bf16 v[0:3], v[210:213], v[194:197], v[0:3]
	s_barrier
	s_add_i32 s48, 0, 0x18000
	v_add_u32_e32 v140, s48, v188
	ds_read_b128 v[144:147], v190 offset:32768
	ds_read_b128 v[148:151], v190 offset:33792
	ds_read_b128 v[166:169], v190 offset:34816
	ds_read_b128 v[170:173], v190 offset:35840
	ds_read_b128 v[174:177], v190 offset:36864
	ds_read_b128 v[180:183], v190 offset:37888
	ds_read_b128 v[184:187], v190 offset:38912
	ds_read_b128 v[194:197], v190 offset:39936
	ds_read_b128 v[128:131], v140
	ds_read_b128 v[132:135], v140 offset:1024
	ds_read_b128 v[136:139], v140 offset:2048
	ds_read_b128 v[140:143], v140 offset:3072
	s_add_u32 s26, s26, 0x40000
	s_addc_u32 s27, s27, 0
	s_mov_b32 m0, s36
	v_lshl_add_u64 v[198:199], s[26:27], 0, v[158:159]
	global_load_lds_dwordx4 v[198:199], off
	v_lshl_add_u64 v[198:199], s[26:27], 0, v[154:155]
	s_mov_b32 m0, s37
	s_nop 0
	global_load_lds_dwordx4 v[198:199], off
	s_waitcnt lgkmcnt(0)
	s_barrier
	v_mfma_f32_16x16x32_bf16 v[124:127], v[128:131], v[144:147], v[124:127]
	v_mfma_f32_16x16x32_bf16 v[120:123], v[136:139], v[144:147], v[120:123]
	v_mfma_f32_16x16x32_bf16 v[108:111], v[128:131], v[166:169], v[108:111]
	v_mfma_f32_16x16x32_bf16 v[104:107], v[136:139], v[166:169], v[104:107]
	v_mfma_f32_16x16x32_bf16 v[92:95], v[128:131], v[174:177], v[92:95]
	v_mfma_f32_16x16x32_bf16 v[88:91], v[136:139], v[174:177], v[88:91]
	v_mfma_f32_16x16x32_bf16 v[76:79], v[128:131], v[184:187], v[76:79]
	v_mfma_f32_16x16x32_bf16 v[72:75], v[136:139], v[184:187], v[72:75]
	v_mfma_f32_16x16x32_bf16 v[124:127], v[132:135], v[148:151], v[124:127]
	v_mfma_f32_16x16x32_bf16 v[120:123], v[140:143], v[148:151], v[120:123]
	v_mfma_f32_16x16x32_bf16 v[108:111], v[132:135], v[170:173], v[108:111]
	v_mfma_f32_16x16x32_bf16 v[104:107], v[140:143], v[170:173], v[104:107]
	v_mfma_f32_16x16x32_bf16 v[92:95], v[132:135], v[180:183], v[92:95]
	v_mfma_f32_16x16x32_bf16 v[88:91], v[140:143], v[180:183], v[88:91]
	v_mfma_f32_16x16x32_bf16 v[76:79], v[132:135], v[194:197], v[76:79]
	v_mfma_f32_16x16x32_bf16 v[72:75], v[140:143], v[194:197], v[72:75]
	s_barrier
	s_add_i32 s26, 0, 0x1c000
	s_add_i32 s27, s48, s33
	v_add_u32_e32 v193, s26, v188
	v_lshl_add_u64 v[214:215], v[214:215], 0, s[12:13]
	s_mov_b32 m0, s27
	ds_read_b128 v[198:201], v193
	ds_read_b128 v[202:205], v193 offset:1024
	ds_read_b128 v[206:209], v193 offset:2048
	ds_read_b128 v[210:213], v193 offset:3072
	global_load_lds_dwordx4 v[214:215], off
	v_lshl_add_u64 v[214:215], v[216:217], 0, s[12:13]
	s_add_i32 m0, s27, 0x2000
	s_nop 0
	global_load_lds_dwordx4 v[214:215], off
	s_barrier
	s_waitcnt lgkmcnt(0)
	v_mfma_f32_16x16x32_bf16 v[116:119], v[198:201], v[144:147], v[116:119]
	v_mfma_f32_16x16x32_bf16 v[112:115], v[206:209], v[144:147], v[112:115]
	v_mfma_f32_16x16x32_bf16 v[100:103], v[198:201], v[166:169], v[100:103]
	v_mfma_f32_16x16x32_bf16 v[96:99], v[206:209], v[166:169], v[96:99]
	v_mfma_f32_16x16x32_bf16 v[84:87], v[198:201], v[174:177], v[84:87]
	v_mfma_f32_16x16x32_bf16 v[80:83], v[206:209], v[174:177], v[80:83]
	v_mfma_f32_16x16x32_bf16 v[68:71], v[198:201], v[184:187], v[68:71]
	v_mfma_f32_16x16x32_bf16 v[64:67], v[206:209], v[184:187], v[64:67]
	v_mfma_f32_16x16x32_bf16 v[116:119], v[202:205], v[148:151], v[116:119]
	v_mfma_f32_16x16x32_bf16 v[112:115], v[210:213], v[148:151], v[112:115]
	v_mfma_f32_16x16x32_bf16 v[100:103], v[202:205], v[170:173], v[100:103]
	v_mfma_f32_16x16x32_bf16 v[96:99], v[210:213], v[170:173], v[96:99]
	v_mfma_f32_16x16x32_bf16 v[84:87], v[202:205], v[180:183], v[84:87]
	v_mfma_f32_16x16x32_bf16 v[80:83], v[210:213], v[180:183], v[80:83]
	v_mfma_f32_16x16x32_bf16 v[68:71], v[202:205], v[194:197], v[68:71]
	v_mfma_f32_16x16x32_bf16 v[64:67], v[210:213], v[194:197], v[64:67]
	s_barrier
	s_mov_b32 m0, s39
	v_lshl_add_u64 v[214:215], v[218:219], 0, s[12:13]
	ds_read_b128 v[144:147], v190 offset:49152
	ds_read_b128 v[148:151], v190 offset:50176
	ds_read_b128 v[166:169], v190 offset:51200
	ds_read_b128 v[170:173], v190 offset:52224
	ds_read_b128 v[174:177], v190 offset:53248
	ds_read_b128 v[180:183], v190 offset:54272
	ds_read_b128 v[184:187], v190 offset:55296
	ds_read_b128 v[194:197], v190 offset:56320
	global_load_lds_dwordx4 v[214:215], off
	v_lshl_add_u64 v[214:215], v[222:223], 0, s[12:13]
	s_mov_b32 m0, s40
	s_nop 0
	global_load_lds_dwordx4 v[214:215], off
	s_barrier
	s_waitcnt lgkmcnt(0)
	v_mfma_f32_16x16x32_bf16 v[60:63], v[128:131], v[144:147], v[60:63]
	v_mfma_f32_16x16x32_bf16 v[56:59], v[136:139], v[144:147], v[56:59]
	v_mfma_f32_16x16x32_bf16 v[44:47], v[128:131], v[166:169], v[44:47]
	v_mfma_f32_16x16x32_bf16 v[40:43], v[136:139], v[166:169], v[40:43]
	v_mfma_f32_16x16x32_bf16 v[28:31], v[128:131], v[174:177], v[28:31]
	v_mfma_f32_16x16x32_bf16 v[24:27], v[136:139], v[174:177], v[24:27]
	v_mfma_f32_16x16x32_bf16 v[12:15], v[128:131], v[184:187], v[12:15]
	v_mfma_f32_16x16x32_bf16 v[8:11], v[136:139], v[184:187], v[8:11]
	v_mfma_f32_16x16x32_bf16 v[60:63], v[132:135], v[148:151], v[60:63]
	v_mfma_f32_16x16x32_bf16 v[56:59], v[140:143], v[148:151], v[56:59]
	v_mfma_f32_16x16x32_bf16 v[44:47], v[132:135], v[170:173], v[44:47]
	v_mfma_f32_16x16x32_bf16 v[40:43], v[140:143], v[170:173], v[40:43]
	v_mfma_f32_16x16x32_bf16 v[28:31], v[132:135], v[180:183], v[28:31]
	v_mfma_f32_16x16x32_bf16 v[24:27], v[140:143], v[180:183], v[24:27]
	v_mfma_f32_16x16x32_bf16 v[12:15], v[132:135], v[194:197], v[12:15]
	v_mfma_f32_16x16x32_bf16 v[8:11], v[140:143], v[194:197], v[8:11]
	s_barrier
	s_add_u32 s24, s24, 0x40080
	s_addc_u32 s25, s25, 0
	s_add_i32 s26, s26, s33
	v_lshl_add_u64 v[128:129], s[24:25], 0, v[156:157]
	s_mov_b32 m0, s26
	s_nop 0
	global_load_lds_dwordx4 v[128:129], off
	v_lshl_add_u64 v[128:129], s[24:25], 0, v[152:153]
	s_add_i32 m0, s26, 0x2000
	s_nop 0
	global_load_lds_dwordx4 v[128:129], off
	s_waitcnt vmcnt(6)
	s_barrier
	v_mfma_f32_16x16x32_bf16 v[52:55], v[198:201], v[144:147], v[52:55]
	v_mfma_f32_16x16x32_bf16 v[48:51], v[206:209], v[144:147], v[48:51]
	v_mfma_f32_16x16x32_bf16 v[36:39], v[198:201], v[166:169], v[36:39]
	v_mfma_f32_16x16x32_bf16 v[32:35], v[206:209], v[166:169], v[32:35]
	v_mfma_f32_16x16x32_bf16 v[20:23], v[198:201], v[174:177], v[20:23]
	v_mfma_f32_16x16x32_bf16 v[16:19], v[206:209], v[174:177], v[16:19]
	v_mfma_f32_16x16x32_bf16 v[4:7], v[198:201], v[184:187], v[4:7]
	v_mfma_f32_16x16x32_bf16 v[0:3], v[206:209], v[184:187], v[0:3]
	v_mfma_f32_16x16x32_bf16 v[52:55], v[202:205], v[148:151], v[52:55]
	v_mfma_f32_16x16x32_bf16 v[48:51], v[210:213], v[148:151], v[48:51]
	v_mfma_f32_16x16x32_bf16 v[36:39], v[202:205], v[170:173], v[36:39]
	v_mfma_f32_16x16x32_bf16 v[32:35], v[210:213], v[170:173], v[32:35]
	v_mfma_f32_16x16x32_bf16 v[20:23], v[202:205], v[180:183], v[20:23]
	v_mfma_f32_16x16x32_bf16 v[16:19], v[210:213], v[180:183], v[16:19]
	v_mfma_f32_16x16x32_bf16 v[4:7], v[202:205], v[194:197], v[4:7]
	v_mfma_f32_16x16x32_bf16 v[0:3], v[210:213], v[194:197], v[0:3]
	s_barrier
	s_add_i32 s47, s47, 2
	s_add_u32 s10, s10, 0x100
	s_addc_u32 s11, s11, 0
	s_add_u32 s45, s45, 0x100
	s_addc_u32 s46, s46, 0
	s_cmp_gt_u32 s47, 13
	s_cbranch_scc0 .LBB0_1356
	s_lshl_b32 s24, s4, 8
	s_ashr_i32 s25, s24, 31
	s_lshl_b32 s10, s4, 2
	s_nop 0
	v_lshl_add_u32 v166, s28, 8, v179
	s_ashr_i32 s11, s10, 31
	s_lshl_b64 s[28:29], s[24:25], 1
	v_readlane_b32 s50, v253, 40
	v_readlane_b32 s51, v253, 41
	s_add_u32 s26, s50, s28
	v_ashrrev_i32_e32 v167, 31, v166
	s_addc_u32 s27, s51, s29
	v_lshlrev_b64 v[204:205], 11, v[166:167]
	v_lshl_add_u64 v[128:129], s[26:27], 0, v[204:205]
	v_lshl_add_u64 v[206:207], v[128:129], 0, v[160:161]
	global_load_dwordx4 v[196:199], v[206:207], off
	global_load_dwordx4 v[200:203], v[206:207], off offset:256
	v_or_b32_e32 v182, 16, v166
	v_or_b32_e32 v174, 32, v166
	v_or_b32_e32 v168, 48, v166
	v_ashrrev_i32_e32 v183, 31, v182
	v_ashrrev_i32_e32 v175, 31, v174
	v_ashrrev_i32_e32 v169, 31, v168
	v_lshlrev_b64 v[186:187], 11, v[182:183]
	v_lshlrev_b64 v[180:181], 11, v[174:175]
	v_lshlrev_b64 v[172:173], 11, v[168:169]
	v_lshl_add_u64 v[128:129], s[26:27], 0, v[186:187]
	v_lshl_add_u64 v[130:131], s[26:27], 0, v[180:181]
	v_lshl_add_u64 v[132:133], s[26:27], 0, v[172:173]
	v_lshl_add_u64 v[184:185], v[128:129], 0, v[160:161]
	v_lshl_add_u64 v[176:177], v[130:131], 0, v[160:161]
	v_lshl_add_u64 v[170:171], v[132:133], 0, v[160:161]
	global_load_dwordx4 v[148:151], v[184:185], off
	global_load_dwordx4 v[144:147], v[184:185], off offset:256
	global_load_dwordx4 v[140:143], v[176:177], off
	global_load_dwordx4 v[136:139], v[176:177], off offset:256
	global_load_dwordx4 v[132:135], v[170:171], off
	global_load_dwordx4 v[128:131], v[170:171], off offset:256
	v_and_b32_e32 v194, 64, v192
	v_xor_b32_e32 v193, 16, v192
	v_add_u32_e32 v194, 64, v194
	v_cmp_lt_i32_e32 vcc, v193, v194
	v_xor_b32_e32 v195, 32, v192
	v_lshl_add_u64 v[204:205], s[50:51], 0, v[204:205]
	v_cndmask_b32_e32 v193, v192, v193, vcc
	v_cmp_lt_i32_e32 vcc, v195, v194
	v_lshlrev_b32_e32 v194, 2, v193
	s_nop 0
	v_cndmask_b32_e32 v195, v192, v195, vcc
	v_lshlrev_b32_e32 v193, 2, v195
	s_nop 7
	s_nop 3
	s_waitcnt vmcnt(0)
	v_lshlrev_b32_e32 v210, 16, v198
	v_and_b32_e32 v211, 0xffff0000, v198
	v_lshlrev_b32_e32 v208, 16, v196
	v_and_b32_e32 v209, 0xffff0000, v196
	v_lshlrev_b32_e32 v198, 16, v199
	v_and_b32_e32 v199, 0xffff0000, v199
	v_lshlrev_b32_e32 v214, 16, v202
	v_and_b32_e32 v215, 0xffff0000, v202
	v_lshlrev_b32_e32 v202, 16, v203
	v_and_b32_e32 v203, 0xffff0000, v203
	v_pk_add_f32 v[120:121], v[120:121], v[210:211]
	v_lshlrev_b32_e32 v196, 16, v197
	v_and_b32_e32 v197, 0xffff0000, v197
	v_pk_add_f32 v[124:125], v[124:125], v[208:209]
	v_pk_add_f32 v[122:123], v[122:123], v[198:199]
	v_pk_add_f32 v[198:199], v[114:115], v[202:203]
	v_cvt_pk_bf16_f32 v114, v120, v121
	v_pk_mul_f32 v[120:121], v[120:121], v[120:121]
	v_pk_add_f32 v[126:127], v[126:127], v[196:197]
	v_cvt_pk_bf16_f32 v115, v122, v123
	v_pk_mul_f32 v[122:123], v[122:123], v[122:123]
	v_pk_fma_f32 v[120:121], v[124:125], v[124:125], v[120:121]
	v_lshlrev_b32_e32 v212, 16, v200
	v_and_b32_e32 v213, 0xffff0000, v200
	v_lshlrev_b32_e32 v200, 16, v201
	v_and_b32_e32 v201, 0xffff0000, v201
	v_pk_add_f32 v[196:197], v[112:113], v[214:215]
	v_pk_fma_f32 v[122:123], v[126:127], v[126:127], v[122:123]
	v_add_f32_e32 v120, v120, v121
	v_pk_add_f32 v[116:117], v[116:117], v[212:213]
	v_pk_add_f32 v[118:119], v[118:119], v[200:201]
	v_pk_mul_f32 v[200:201], v[196:197], v[196:197]
	v_add_f32_e32 v120, v122, v120
	v_cvt_pk_bf16_f32 v112, v124, v125
	v_pk_fma_f32 v[124:125], v[116:117], v[116:117], v[200:201]
	v_add_f32_e32 v120, v123, v120
	v_pk_mul_f32 v[202:203], v[198:199], v[198:199]
	v_add_f32_e32 v120, v124, v120
	v_cvt_pk_bf16_f32 v113, v126, v127
	v_pk_fma_f32 v[126:127], v[118:119], v[118:119], v[202:203]
	v_add_f32_e32 v120, v125, v120
	v_add_f32_e32 v120, v126, v120
	v_add_f32_e32 v122, v127, v120
	ds_bpermute_b32 v123, v194, v122
	global_store_dwordx4 v[206:207], v[112:115], off
	v_lshl_add_u64 v[120:121], v[204:205], 0, s[28:29]
	s_nop 0
	v_cvt_pk_bf16_f32 v114, v116, v117
	s_waitcnt lgkmcnt(0)
	v_add_f32_e32 v112, v122, v123
	ds_bpermute_b32 v113, v193, v112
	v_cvt_pk_bf16_f32 v115, v118, v119
	v_cvt_pk_bf16_f32 v116, v196, v197
	v_cvt_pk_bf16_f32 v117, v198, v199
	v_lshl_add_u64 v[118:119], v[120:121], 0, v[160:161]
	global_store_dwordx4 v[118:119], v[114:117], off offset:256
	s_and_saveexec_b64 s[28:29], s[0:1]
	s_cbranch_execz .LBB0_1359
	s_waitcnt lgkmcnt(0)
	v_add_f32_e32 v114, v112, v113
	v_lshlrev_b64 v[112:113], 6, v[166:167]
	v_lshl_add_u64 v[112:113], s[86:87], 0, v[112:113]
	v_lshl_add_u64 v[112:113], s[10:11], 2, v[112:113]
	s_lshl_b32 s4, s38, 2
	v_lshl_add_u64 v[112:113], v[112:113], 0, s[4:5]
	global_store_dword v[112:113], v114, off

.LBB0_1441:
	ds_read_b128 v[184:187], v165
	ds_read_b128 v[188:191], v165 offset:1024
	ds_read_b128 v[192:195], v165 offset:2048
	ds_read_b128 v[196:199], v165 offset:3072
	ds_read_b128 v[200:203], v165 offset:4096
	ds_read_b128 v[204:207], v165 offset:5120
	ds_read_b128 v[208:211], v165 offset:6144
	ds_read_b128 v[212:215], v165 offset:7168
	ds_read_b128 v[144:147], v161
	ds_read_b128 v[148:151], v161 offset:1024
	ds_read_b128 v[172:175], v161 offset:2048
	ds_read_b128 v[180:183], v161 offset:3072
	s_add_u32 s4, s0, 0xfffc0080
	s_addc_u32 s5, s1, -1
	s_cmp_eq_u32 s45, 12
	s_cselect_b32 s11, s19, s5
	s_cselect_b32 s10, s41, s4
	s_cselect_b32 s5, s21, s44
	s_cselect_b32 s4, s42, s43
	v_lshl_add_u64 v[154:155], s[0:1], 0, v[140:141]
	s_add_i32 m0, s17, 0xc000
	s_nop 0
	global_load_lds_dwordx4 v[154:155], off
	v_lshl_add_u64 v[154:155], s[0:1], 0, v[142:143]
	s_add_i32 m0, s17, 0xe000
	s_nop 0
	global_load_lds_dwordx4 v[154:155], off
	s_waitcnt lgkmcnt(0)
	s_barrier
	v_mfma_f32_16x16x32_bf16 v[124:127], v[144:147], v[184:187], v[124:127]
	v_mfma_f32_16x16x32_bf16 v[120:123], v[172:175], v[184:187], v[120:123]
	v_mfma_f32_16x16x32_bf16 v[108:111], v[144:147], v[192:195], v[108:111]
	v_mfma_f32_16x16x32_bf16 v[104:107], v[172:175], v[192:195], v[104:107]
	v_mfma_f32_16x16x32_bf16 v[92:95], v[144:147], v[200:203], v[92:95]
	v_mfma_f32_16x16x32_bf16 v[88:91], v[172:175], v[200:203], v[88:91]
	v_mfma_f32_16x16x32_bf16 v[76:79], v[144:147], v[208:211], v[76:79]
	v_mfma_f32_16x16x32_bf16 v[72:75], v[172:175], v[208:211], v[72:75]
	v_mfma_f32_16x16x32_bf16 v[124:127], v[148:151], v[188:191], v[124:127]
	v_mfma_f32_16x16x32_bf16 v[120:123], v[180:183], v[188:191], v[120:123]
	v_mfma_f32_16x16x32_bf16 v[108:111], v[148:151], v[196:199], v[108:111]
	v_mfma_f32_16x16x32_bf16 v[104:107], v[180:183], v[196:199], v[104:107]
	v_mfma_f32_16x16x32_bf16 v[92:95], v[148:151], v[204:207], v[92:95]
	v_mfma_f32_16x16x32_bf16 v[88:91], v[180:183], v[204:207], v[88:91]
	v_mfma_f32_16x16x32_bf16 v[76:79], v[148:151], v[212:215], v[76:79]
	v_mfma_f32_16x16x32_bf16 v[72:75], v[180:183], v[212:215], v[72:75]
	s_barrier
	s_add_i32 s46, s37, s15
	v_lshl_add_u64 v[154:155], s[4:5], 0, v[132:133]
	s_mov_b32 m0, s46
	ds_read_b128 v[216:219], v167
	ds_read_b128 v[222:225], v167 offset:1024
	ds_read_b128 v[226:229], v167 offset:2048
	ds_read_b128 v[230:233], v167 offset:3072
	global_load_lds_dwordx4 v[154:155], off
	v_lshl_add_u64 v[158:159], s[4:5], 0, v[128:129]
	s_add_i32 m0, s46, 0x2000
	s_nop 0
	global_load_lds_dwordx4 v[158:159], off
	s_barrier
	s_waitcnt lgkmcnt(0)
	v_mfma_f32_16x16x32_bf16 v[116:119], v[216:219], v[184:187], v[116:119]
	v_mfma_f32_16x16x32_bf16 v[112:115], v[226:229], v[184:187], v[112:115]
	v_mfma_f32_16x16x32_bf16 v[100:103], v[216:219], v[192:195], v[100:103]
	v_mfma_f32_16x16x32_bf16 v[96:99], v[226:229], v[192:195], v[96:99]
	v_mfma_f32_16x16x32_bf16 v[84:87], v[216:219], v[200:203], v[84:87]
	v_mfma_f32_16x16x32_bf16 v[80:83], v[226:229], v[200:203], v[80:83]
	v_mfma_f32_16x16x32_bf16 v[68:71], v[216:219], v[208:211], v[68:71]
	v_mfma_f32_16x16x32_bf16 v[64:67], v[226:229], v[208:211], v[64:67]
	v_mfma_f32_16x16x32_bf16 v[116:119], v[222:225], v[188:191], v[116:119]
	v_mfma_f32_16x16x32_bf16 v[112:115], v[230:233], v[188:191], v[112:115]
	v_mfma_f32_16x16x32_bf16 v[100:103], v[222:225], v[196:199], v[100:103]
	v_mfma_f32_16x16x32_bf16 v[96:99], v[230:233], v[196:199], v[96:99]
	v_mfma_f32_16x16x32_bf16 v[84:87], v[222:225], v[204:207], v[84:87]
	v_mfma_f32_16x16x32_bf16 v[80:83], v[230:233], v[204:207], v[80:83]
	v_mfma_f32_16x16x32_bf16 v[68:71], v[222:225], v[212:215], v[68:71]
	v_mfma_f32_16x16x32_bf16 v[64:67], v[230:233], v[212:215], v[64:67]
	s_barrier
	s_mov_b32 m0, s17
	v_lshl_add_u64 v[162:163], s[10:11], 0, v[134:135]
	ds_read_b128 v[184:187], v165 offset:16384
	ds_read_b128 v[188:191], v165 offset:17408
	ds_read_b128 v[192:195], v165 offset:18432
	ds_read_b128 v[196:199], v165 offset:19456
	ds_read_b128 v[200:203], v165 offset:20480
	ds_read_b128 v[204:207], v165 offset:21504
	ds_read_b128 v[208:211], v165 offset:22528
	ds_read_b128 v[212:215], v165 offset:23552
	global_load_lds_dwordx4 v[162:163], off
	v_lshl_add_u64 v[168:169], s[10:11], 0, v[130:131]
	s_mov_b32 m0, s28
	s_nop 0
	global_load_lds_dwordx4 v[168:169], off
	s_barrier
	s_waitcnt lgkmcnt(0)
	v_mfma_f32_16x16x32_bf16 v[60:63], v[144:147], v[184:187], v[60:63]
	v_mfma_f32_16x16x32_bf16 v[56:59], v[172:175], v[184:187], v[56:59]
	v_mfma_f32_16x16x32_bf16 v[44:47], v[144:147], v[192:195], v[44:47]
	v_mfma_f32_16x16x32_bf16 v[40:43], v[172:175], v[192:195], v[40:43]
	v_mfma_f32_16x16x32_bf16 v[28:31], v[144:147], v[200:203], v[28:31]
	v_mfma_f32_16x16x32_bf16 v[24:27], v[172:175], v[200:203], v[24:27]
	v_mfma_f32_16x16x32_bf16 v[12:15], v[144:147], v[208:211], v[12:15]
	v_mfma_f32_16x16x32_bf16 v[8:11], v[172:175], v[208:211], v[8:11]
	v_mfma_f32_16x16x32_bf16 v[60:63], v[148:151], v[188:191], v[60:63]
	v_mfma_f32_16x16x32_bf16 v[56:59], v[180:183], v[188:191], v[56:59]
	v_mfma_f32_16x16x32_bf16 v[44:47], v[148:151], v[196:199], v[44:47]
	v_mfma_f32_16x16x32_bf16 v[40:43], v[180:183], v[196:199], v[40:43]
	v_mfma_f32_16x16x32_bf16 v[28:31], v[148:151], v[204:207], v[28:31]
	v_mfma_f32_16x16x32_bf16 v[24:27], v[180:183], v[204:207], v[24:27]
	v_mfma_f32_16x16x32_bf16 v[12:15], v[148:151], v[212:215], v[12:15]
	v_mfma_f32_16x16x32_bf16 v[8:11], v[180:183], v[212:215], v[8:11]
	s_barrier
	s_add_u32 s46, s4, 0x40000
	s_addc_u32 s47, s5, 0
	s_add_i32 s48, s38, s15
	v_lshl_add_u64 v[144:145], s[46:47], 0, v[132:133]
	s_mov_b32 m0, s48
	s_nop 0
	global_load_lds_dwordx4 v[144:145], off
	v_lshl_add_u64 v[144:145], s[46:47], 0, v[128:129]
	s_add_i32 m0, s48, 0x2000
	s_nop 0
	global_load_lds_dwordx4 v[144:145], off
	s_waitcnt vmcnt(6)
	s_barrier
	v_mfma_f32_16x16x32_bf16 v[52:55], v[216:219], v[184:187], v[52:55]
	v_mfma_f32_16x16x32_bf16 v[48:51], v[226:229], v[184:187], v[48:51]
	v_mfma_f32_16x16x32_bf16 v[36:39], v[216:219], v[192:195], v[36:39]
	v_mfma_f32_16x16x32_bf16 v[32:35], v[226:229], v[192:195], v[32:35]
	v_mfma_f32_16x16x32_bf16 v[20:23], v[216:219], v[200:203], v[20:23]
	v_mfma_f32_16x16x32_bf16 v[16:19], v[226:229], v[200:203], v[16:19]
	v_mfma_f32_16x16x32_bf16 v[4:7], v[216:219], v[208:211], v[4:7]
	v_mfma_f32_16x16x32_bf16 v[0:3], v[226:229], v[208:211], v[0:3]
	v_mfma_f32_16x16x32_bf16 v[52:55], v[222:225], v[188:191], v[52:55]
	v_mfma_f32_16x16x32_bf16 v[48:51], v[230:233], v[188:191], v[48:51]
	v_mfma_f32_16x16x32_bf16 v[36:39], v[222:225], v[196:199], v[36:39]
	v_mfma_f32_16x16x32_bf16 v[32:35], v[230:233], v[196:199], v[32:35]
	v_mfma_f32_16x16x32_bf16 v[20:23], v[222:225], v[204:207], v[20:23]
	v_mfma_f32_16x16x32_bf16 v[16:19], v[230:233], v[204:207], v[16:19]
	v_mfma_f32_16x16x32_bf16 v[4:7], v[222:225], v[212:215], v[4:7]
	v_mfma_f32_16x16x32_bf16 v[0:3], v[230:233], v[212:215], v[0:3]
	s_barrier
	s_add_i32 s46, 0, 0x18000
	v_add_u32_e32 v152, s46, v157
	ds_read_b128 v[184:187], v165 offset:32768
	ds_read_b128 v[188:191], v165 offset:33792
	ds_read_b128 v[192:195], v165 offset:34816
	ds_read_b128 v[196:199], v165 offset:35840
	ds_read_b128 v[200:203], v165 offset:36864
	ds_read_b128 v[204:207], v165 offset:37888
	ds_read_b128 v[208:211], v165 offset:38912
	ds_read_b128 v[212:215], v165 offset:39936
	ds_read_b128 v[144:147], v152
	ds_read_b128 v[148:151], v152 offset:1024
	ds_read_b128 v[172:175], v152 offset:2048
	ds_read_b128 v[180:183], v152 offset:3072
	s_add_u32 s10, s10, 0x40000
	s_addc_u32 s11, s11, 0
	s_mov_b32 m0, s29
	v_lshl_add_u64 v[176:177], s[10:11], 0, v[134:135]
	global_load_lds_dwordx4 v[176:177], off
	v_lshl_add_u64 v[176:177], s[10:11], 0, v[130:131]
	s_mov_b32 m0, s31
	s_nop 0
	global_load_lds_dwordx4 v[176:177], off
	s_waitcnt lgkmcnt(0)
	s_barrier
	v_mfma_f32_16x16x32_bf16 v[124:127], v[144:147], v[184:187], v[124:127]
	v_mfma_f32_16x16x32_bf16 v[120:123], v[172:175], v[184:187], v[120:123]
	v_mfma_f32_16x16x32_bf16 v[108:111], v[144:147], v[192:195], v[108:111]
	v_mfma_f32_16x16x32_bf16 v[104:107], v[172:175], v[192:195], v[104:107]
	v_mfma_f32_16x16x32_bf16 v[92:95], v[144:147], v[200:203], v[92:95]
	v_mfma_f32_16x16x32_bf16 v[88:91], v[172:175], v[200:203], v[88:91]
	v_mfma_f32_16x16x32_bf16 v[76:79], v[144:147], v[208:211], v[76:79]
	v_mfma_f32_16x16x32_bf16 v[72:75], v[172:175], v[208:211], v[72:75]
	v_mfma_f32_16x16x32_bf16 v[124:127], v[148:151], v[188:191], v[124:127]
	v_mfma_f32_16x16x32_bf16 v[120:123], v[180:183], v[188:191], v[120:123]
	v_mfma_f32_16x16x32_bf16 v[108:111], v[148:151], v[196:199], v[108:111]
	v_mfma_f32_16x16x32_bf16 v[104:107], v[180:183], v[196:199], v[104:107]
	v_mfma_f32_16x16x32_bf16 v[92:95], v[148:151], v[204:207], v[92:95]
	v_mfma_f32_16x16x32_bf16 v[88:91], v[180:183], v[204:207], v[88:91]
	v_mfma_f32_16x16x32_bf16 v[76:79], v[148:151], v[212:215], v[76:79]
	v_mfma_f32_16x16x32_bf16 v[72:75], v[180:183], v[212:215], v[72:75]
	s_barrier
	s_add_i32 s10, 0, 0x1c000
	s_add_i32 s11, s46, s15
	v_add_u32_e32 v152, s10, v157
	v_lshl_add_u64 v[154:155], v[154:155], 0, s[12:13]
	s_mov_b32 m0, s11
	ds_read_b128 v[216:219], v152
	ds_read_b128 v[222:225], v152 offset:1024
	ds_read_b128 v[226:229], v152 offset:2048
	ds_read_b128 v[230:233], v152 offset:3072
	global_load_lds_dwordx4 v[154:155], off
	v_lshl_add_u64 v[154:155], v[158:159], 0, s[12:13]
	s_add_i32 m0, s11, 0x2000
	s_nop 0
	global_load_lds_dwordx4 v[154:155], off
	s_barrier
	s_waitcnt lgkmcnt(0)
	v_mfma_f32_16x16x32_bf16 v[116:119], v[216:219], v[184:187], v[116:119]
	v_mfma_f32_16x16x32_bf16 v[112:115], v[226:229], v[184:187], v[112:115]
	v_mfma_f32_16x16x32_bf16 v[100:103], v[216:219], v[192:195], v[100:103]
	v_mfma_f32_16x16x32_bf16 v[96:99], v[226:229], v[192:195], v[96:99]
	v_mfma_f32_16x16x32_bf16 v[84:87], v[216:219], v[200:203], v[84:87]
	v_mfma_f32_16x16x32_bf16 v[80:83], v[226:229], v[200:203], v[80:83]
	v_mfma_f32_16x16x32_bf16 v[68:71], v[216:219], v[208:211], v[68:71]
	v_mfma_f32_16x16x32_bf16 v[64:67], v[226:229], v[208:211], v[64:67]
	v_mfma_f32_16x16x32_bf16 v[116:119], v[222:225], v[188:191], v[116:119]
	v_mfma_f32_16x16x32_bf16 v[112:115], v[230:233], v[188:191], v[112:115]
	v_mfma_f32_16x16x32_bf16 v[100:103], v[222:225], v[196:199], v[100:103]
	v_mfma_f32_16x16x32_bf16 v[96:99], v[230:233], v[196:199], v[96:99]
	v_mfma_f32_16x16x32_bf16 v[84:87], v[222:225], v[204:207], v[84:87]
	v_mfma_f32_16x16x32_bf16 v[80:83], v[230:233], v[204:207], v[80:83]
	v_mfma_f32_16x16x32_bf16 v[68:71], v[222:225], v[212:215], v[68:71]
	v_mfma_f32_16x16x32_bf16 v[64:67], v[230:233], v[212:215], v[64:67]
	s_barrier
	s_mov_b32 m0, s35
	v_lshl_add_u64 v[154:155], v[162:163], 0, s[12:13]
	ds_read_b128 v[184:187], v165 offset:49152
	ds_read_b128 v[188:191], v165 offset:50176
	ds_read_b128 v[192:195], v165 offset:51200
	ds_read_b128 v[196:199], v165 offset:52224
	ds_read_b128 v[200:203], v165 offset:53248
	ds_read_b128 v[204:207], v165 offset:54272
	ds_read_b128 v[208:211], v165 offset:55296
	ds_read_b128 v[212:215], v165 offset:56320
	global_load_lds_dwordx4 v[154:155], off
	v_lshl_add_u64 v[154:155], v[168:169], 0, s[12:13]
	s_mov_b32 m0, s36
	s_nop 0
	global_load_lds_dwordx4 v[154:155], off
	s_barrier
	s_waitcnt lgkmcnt(0)
	v_mfma_f32_16x16x32_bf16 v[60:63], v[144:147], v[184:187], v[60:63]
	v_mfma_f32_16x16x32_bf16 v[56:59], v[172:175], v[184:187], v[56:59]
	v_mfma_f32_16x16x32_bf16 v[44:47], v[144:147], v[192:195], v[44:47]
	v_mfma_f32_16x16x32_bf16 v[40:43], v[172:175], v[192:195], v[40:43]
	v_mfma_f32_16x16x32_bf16 v[28:31], v[144:147], v[200:203], v[28:31]
	v_mfma_f32_16x16x32_bf16 v[24:27], v[172:175], v[200:203], v[24:27]
	v_mfma_f32_16x16x32_bf16 v[12:15], v[144:147], v[208:211], v[12:15]
	v_mfma_f32_16x16x32_bf16 v[8:11], v[172:175], v[208:211], v[8:11]
	v_mfma_f32_16x16x32_bf16 v[60:63], v[148:151], v[188:191], v[60:63]
	v_mfma_f32_16x16x32_bf16 v[56:59], v[180:183], v[188:191], v[56:59]
	v_mfma_f32_16x16x32_bf16 v[44:47], v[148:151], v[196:199], v[44:47]
	v_mfma_f32_16x16x32_bf16 v[40:43], v[180:183], v[196:199], v[40:43]
	v_mfma_f32_16x16x32_bf16 v[28:31], v[148:151], v[204:207], v[28:31]
	v_mfma_f32_16x16x32_bf16 v[24:27], v[180:183], v[204:207], v[24:27]
	v_mfma_f32_16x16x32_bf16 v[12:15], v[148:151], v[212:215], v[12:15]
	v_mfma_f32_16x16x32_bf16 v[8:11], v[180:183], v[212:215], v[8:11]
	s_barrier
	s_add_u32 s4, s4, 0x40080
	s_addc_u32 s5, s5, 0
	s_add_i32 s10, s10, s15
	v_lshl_add_u64 v[144:145], s[4:5], 0, v[132:133]
	s_mov_b32 m0, s10
	s_nop 0
	global_load_lds_dwordx4 v[144:145], off
	v_lshl_add_u64 v[144:145], s[4:5], 0, v[128:129]
	s_add_i32 m0, s10, 0x2000
	s_nop 0
	global_load_lds_dwordx4 v[144:145], off
	s_waitcnt vmcnt(6)
	s_barrier
	v_mfma_f32_16x16x32_bf16 v[52:55], v[216:219], v[184:187], v[52:55]
	v_mfma_f32_16x16x32_bf16 v[48:51], v[226:229], v[184:187], v[48:51]
	v_mfma_f32_16x16x32_bf16 v[36:39], v[216:219], v[192:195], v[36:39]
	v_mfma_f32_16x16x32_bf16 v[32:35], v[226:229], v[192:195], v[32:35]
	v_mfma_f32_16x16x32_bf16 v[20:23], v[216:219], v[200:203], v[20:23]
	v_mfma_f32_16x16x32_bf16 v[16:19], v[226:229], v[200:203], v[16:19]
	v_mfma_f32_16x16x32_bf16 v[4:7], v[216:219], v[208:211], v[4:7]
	v_mfma_f32_16x16x32_bf16 v[0:3], v[226:229], v[208:211], v[0:3]
	v_mfma_f32_16x16x32_bf16 v[52:55], v[222:225], v[188:191], v[52:55]
	v_mfma_f32_16x16x32_bf16 v[48:51], v[230:233], v[188:191], v[48:51]
	v_mfma_f32_16x16x32_bf16 v[36:39], v[222:225], v[196:199], v[36:39]
	v_mfma_f32_16x16x32_bf16 v[32:35], v[230:233], v[196:199], v[32:35]
	v_mfma_f32_16x16x32_bf16 v[20:23], v[222:225], v[204:207], v[20:23]
	v_mfma_f32_16x16x32_bf16 v[16:19], v[230:233], v[204:207], v[16:19]
	v_mfma_f32_16x16x32_bf16 v[4:7], v[222:225], v[212:215], v[4:7]
	v_mfma_f32_16x16x32_bf16 v[0:3], v[230:233], v[212:215], v[0:3]
	s_barrier
	s_add_i32 s45, s45, 2
	s_add_u32 s0, s0, 0x100
	s_addc_u32 s1, s1, 0
	s_add_u32 s43, s43, 0x100
	s_addc_u32 s44, s44, 0
	s_cmp_gt_u32 s45, 13
	s_cbranch_scc0 .LBB0_1441
	v_lshl_add_u32 v168, s72, 8, v153
	v_ashrrev_i32_e32 v169, 31, v168
	v_or_b32_e32 v162, 16, v168
	v_lshlrev_b64 v[144:145], 6, v[168:169]
	v_ashrrev_i32_e32 v163, 31, v162
	v_or_b32_e32 v158, 32, v168
	v_lshl_add_u64 v[144:145], v[138:139], 0, v[144:145]
	v_lshlrev_b64 v[146:147], 6, v[162:163]
	v_ashrrev_i32_e32 v159, 31, v158
	v_lshl_add_u64 v[146:147], v[138:139], 0, v[146:147]
	global_load_dwordx4 v[172:175], v[144:145], off
	global_load_dwordx4 v[180:183], v[146:147], off
	v_lshlrev_b64 v[144:145], 6, v[158:159]
	v_or_b32_e32 v154, 48, v168
	v_lshl_add_u64 v[144:145], v[138:139], 0, v[144:145]
	v_ashrrev_i32_e32 v155, 31, v154
	global_load_dwordx4 v[184:187], v[144:145], off
	v_lshlrev_b64 v[144:145], 6, v[154:155]
	v_lshl_add_u64 v[144:145], v[138:139], 0, v[144:145]
	global_load_dwordx4 v[188:191], v[144:145], off
	v_add_u32_e32 v150, 0x80, v168
	v_ashrrev_i32_e32 v151, 31, v150
	v_lshlrev_b64 v[144:145], 6, v[150:151]
	v_add_u32_e32 v148, 0x90, v168
	v_lshl_add_u64 v[144:145], v[138:139], 0, v[144:145]
	v_ashrrev_i32_e32 v149, 31, v148
	global_load_dwordx4 v[192:195], v[144:145], off
	v_lshlrev_b64 v[144:145], 6, v[148:149]
	v_lshl_add_u64 v[144:145], v[138:139], 0, v[144:145]
	global_load_dwordx4 v[196:199], v[144:145], off
	v_and_b32_e32 v145, 64, v171
	v_add_u32_e32 v146, 0xa0, v168
	v_add_u32_e32 v144, 0xb0, v168
	v_add_u32_e32 v160, 64, v145
	v_ashrrev_i32_e32 v147, 31, v146
	v_ashrrev_i32_e32 v145, 31, v144
	v_lshlrev_b64 v[200:201], 6, v[146:147]
	v_lshlrev_b64 v[202:203], 6, v[144:145]
	v_lshl_add_u64 v[200:201], v[138:139], 0, v[200:201]
	v_lshl_add_u64 v[204:205], v[138:139], 0, v[202:203]
	global_load_dwordx4 v[200:203], v[200:201], off
	s_nop 0
	global_load_dwordx4 v[204:207], v[204:205], off
	v_xor_b32_e32 v152, 16, v171
	v_cmp_lt_i32_e32 vcc, v152, v160
	v_xor_b32_e32 v156, 32, v171
	v_mov_b64_e32 v[176:177], s[16:17]
	v_cndmask_b32_e32 v152, v171, v152, vcc
	v_lshlrev_b32_e32 v152, 2, v152
	v_cmp_lt_i32_e32 vcc, v156, v160
	v_lshlrev_b64 v[168:169], 7, v[168:169]
	s_mov_b32 s72, s18
	v_cndmask_b32_e32 v156, v171, v156, vcc
	v_lshlrev_b32_e32 v156, 2, v156
	s_mov_b32 s21, s18
	s_mov_b32 s19, s40
	s_waitcnt vmcnt(0)
	v_mov_b32_e32 v208, v173
	v_mov_b32_e32 v209, v174
	v_mov_b32_e32 v173, v175
	v_mov_b32_e32 v174, v181
	v_mov_b32_e32 v175, v182
	v_mov_b32_e32 v181, v183
	v_pk_add_f32 v[172:173], v[208:209], v[172:173]
	v_pk_add_f32 v[174:175], v[174:175], v[180:181]
	v_mov_b32_e32 v181, v172
	v_mov_b32_e32 v180, v174
	v_mov_b32_e32 v172, v175
	v_mov_b32_e32 v182, v185
	v_mov_b32_e32 v183, v186
	v_mov_b32_e32 v185, v187
	v_mov_b32_e32 v186, v189
	v_mov_b32_e32 v187, v190
	v_mov_b32_e32 v189, v191
	v_pk_add_f32 v[172:173], v[180:181], v[172:173]
	v_pk_add_f32 v[182:183], v[182:183], v[184:185]
	v_pk_add_f32 v[184:185], v[186:187], v[188:189]
	ds_bpermute_b32 v181, v152, v173
	ds_bpermute_b32 v180, v152, v172
	v_mov_b32_e32 v174, v184
	v_mov_b32_e32 v175, v182
	v_mov_b32_e32 v182, v185
	v_pk_add_f32 v[174:175], v[174:175], v[182:183]
	ds_bpermute_b32 v183, v152, v175
	ds_bpermute_b32 v182, v152, v174
	s_waitcnt lgkmcnt(0)
	v_pk_add_f32 v[172:173], v[172:173], v[180:181]
	ds_bpermute_b32 v181, v156, v173
	ds_bpermute_b32 v180, v156, v172
	v_mov_b32_e32 v184, v193
	v_pk_add_f32 v[174:175], v[174:175], v[182:183]
	ds_bpermute_b32 v183, v156, v175
	ds_bpermute_b32 v182, v156, v174
	s_waitcnt lgkmcnt(2)
	v_pk_add_f32 v[172:173], v[172:173], v[180:181]
	v_mov_b32_e32 v185, v194
	v_mov_b32_e32 v193, v195
	v_mov_b32_e32 v186, v197
	v_mov_b32_e32 v187, v198
	v_pk_fma_f32 v[172:173], v[172:173], s[14:15], v[176:177] op_sel_hi:[1,0,0]
	v_mov_b32_e32 v197, v199
	v_pk_add_f32 v[184:185], v[184:185], v[192:193]
	v_mul_f32_e32 v160, 0x4b800000, v173
	v_cmp_gt_f32_e32 vcc, s39, v173
	v_pk_add_f32 v[180:181], v[186:187], v[196:197]
	s_waitcnt lgkmcnt(0)
	v_pk_add_f32 v[174:175], v[174:175], v[182:183]
	v_cndmask_b32_e32 v160, v173, v160, vcc
	v_mov_b32_e32 v182, v180
	v_mov_b32_e32 v183, v184
	v_mov_b32_e32 v184, v181
	v_rsq_f32_e32 v160, v160
	v_pk_add_f32 v[180:181], v[182:183], v[184:185]
	ds_bpermute_b32 v183, v152, v181
	ds_bpermute_b32 v182, v152, v180
	v_pk_fma_f32 v[174:175], v[174:175], s[14:15], v[176:177] op_sel_hi:[1,0,0]
	v_mul_f32_e32 v164, 0x4b800000, v172
	v_cmp_gt_f32_e64 s[0:1], s39, v172
	v_mul_f32_e32 v170, 0x45800000, v160
	v_mul_f32_e32 v166, 0x4b800000, v175
	v_cndmask_b32_e64 v164, v172, v164, s[0:1]
	v_cmp_gt_f32_e64 s[4:5], s39, v175
	v_cndmask_b32_e32 v172, v160, v170, vcc
	v_mul_f32_e32 v160, 0x4b800000, v174
	v_cmp_gt_f32_e32 vcc, s39, v174
	v_cndmask_b32_e64 v166, v175, v166, s[4:5]
	v_mov_b32_e32 v184, v205
	v_cndmask_b32_e32 v160, v174, v160, vcc
	s_waitcnt lgkmcnt(0)
	v_pk_add_f32 v[174:175], v[180:181], v[182:183]
	ds_bpermute_b32 v181, v156, v175
	ds_bpermute_b32 v180, v156, v174
	v_mov_b32_e32 v185, v206
	v_mov_b32_e32 v205, v207
	v_pk_add_f32 v[184:185], v[184:185], v[204:205]
	v_rsq_f32_e32 v164, v164
	s_waitcnt lgkmcnt(0)
	v_pk_add_f32 v[174:175], v[174:175], v[180:181]
	v_mov_b32_e32 v180, v201
	v_mov_b32_e32 v181, v202
	v_mov_b32_e32 v201, v203
	v_pk_add_f32 v[180:181], v[180:181], v[200:201]
	v_mov_b32_e32 v186, v184
	v_mov_b32_e32 v187, v180
	v_mov_b32_e32 v180, v185
	v_rsq_f32_e32 v166, v166
	v_pk_add_f32 v[180:181], v[186:187], v[180:181]
	ds_bpermute_b32 v185, v152, v181
	ds_bpermute_b32 v184, v152, v180
	v_mul_f32_e32 v173, 0x45800000, v164
	v_cndmask_b32_e64 v182, v164, v173, s[0:1]
	v_mul_f32_e32 v164, 0x45800000, v166
	v_pk_fma_f32 v[174:175], v[174:175], s[14:15], v[176:177] op_sel_hi:[1,0,0]
	v_cndmask_b32_e64 v170, v166, v164, s[4:5]
	v_mul_f32_e32 v166, 0x4b800000, v175
	v_cmp_gt_f32_e64 s[0:1], s39, v175
	v_mul_f32_e32 v152, 0x4b800000, v174
	v_cmp_gt_f32_e64 s[4:5], s39, v174
	v_cndmask_b32_e64 v166, v175, v166, s[0:1]
	v_rsq_f32_e32 v160, v160
	v_cndmask_b32_e64 v152, v174, v152, s[4:5]
	s_waitcnt lgkmcnt(0)
	v_pk_add_f32 v[174:175], v[180:181], v[184:185]
	ds_bpermute_b32 v181, v156, v175
	ds_bpermute_b32 v180, v156, v174
	v_rsq_f32_e32 v173, v166
	v_mul_f32_e32 v164, 0x45800000, v160
	v_cndmask_b32_e32 v166, v160, v164, vcc
	v_rsq_f32_e32 v152, v152
	s_waitcnt lgkmcnt(0)
	v_pk_add_f32 v[174:175], v[174:175], v[180:181]
	v_mul_f32_e32 v156, 0x45800000, v173
	v_pk_fma_f32 v[174:175], v[174:175], s[14:15], v[176:177] op_sel_hi:[1,0,0]
	v_cndmask_b32_e64 v164, v173, v156, s[0:1]
	v_mul_f32_e32 v160, 0x4b800000, v175
	v_cmp_gt_f32_e32 vcc, s39, v175
	v_cmp_gt_f32_e64 s[0:1], s39, v174
	v_mul_f32_e32 v156, 0x45800000, v152
	v_cndmask_b32_e32 v160, v175, v160, vcc
	v_rsq_f32_e32 v173, v160
	v_mul_f32_e32 v160, 0x4b800000, v174
	v_cndmask_b32_e64 v160, v174, v160, s[0:1]
	v_rsq_f32_e32 v174, v160
	v_cndmask_b32_e64 v160, v152, v156, s[4:5]
	v_mul_f32_e32 v152, 0x45800000, v173
	v_cndmask_b32_e32 v156, v173, v152, vcc
	v_mul_f32_e32 v152, 0x45800000, v174
	v_cndmask_b32_e64 v152, v174, v152, s[0:1]
	s_lshl_b32 s0, s70, 8
	s_or_b32 s0, s0, s33
	s_ashr_i32 s4, s0, 6
	s_ashr_i32 s5, s4, 31
	s_lshl_b64 s[0:1], s[4:5], 22
	v_pk_mul_f32 v[124:125], v[124:125], v[172:173] op_sel_hi:[1,0]
	v_pk_mul_f32 v[120:121], v[120:121], v[172:173] op_sel_hi:[1,0]
	s_add_u32 s0, s84, s0
	v_pk_mul_f32 v[126:127], v[126:127], v[172:173] op_sel_hi:[1,0]
	v_pk_mul_f32 v[122:123], v[122:123], v[172:173] op_sel_hi:[1,0]
	v_max_f32_e32 v124, 0, v124
	v_max_f32_e32 v120, 0, v120
	v_max_f32_e32 v125, 0, v125
	v_max_f32_e32 v121, 0, v121
	s_addc_u32 s1, s85, s1
	s_or_b32 s4, s4, 2
	v_pk_mul_f32 v[124:125], v[124:125], v[124:125]
	v_pk_mul_f32 v[174:175], v[120:121], v[120:121]
	v_max_f32_e32 v120, 0, v126
	v_max_f32_e32 v122, 0, v122
	v_max_f32_e32 v121, 0, v127
	v_max_f32_e32 v123, 0, v123
	s_ashr_i32 s5, s4, 31
	v_pk_mul_f32 v[126:127], v[120:121], v[120:121]
	v_pk_mul_f32 v[176:177], v[122:123], v[122:123]
	v_cvt_pk_bf16_f32 v120, v124, v125
	v_lshl_add_u64 v[124:125], s[0:1], 0, v[168:169]
	v_pk_mul_f32 v[116:117], v[116:117], v[172:173] op_sel_hi:[1,0]
	v_pk_mul_f32 v[112:113], v[112:113], v[172:173] op_sel_hi:[1,0]
	s_lshl_b64 s[4:5], s[4:5], 22
	v_cvt_pk_bf16_f32 v121, v126, v127
	v_cvt_pk_bf16_f32 v122, v174, v175
	v_cvt_pk_bf16_f32 v123, v176, v177
	v_lshl_add_u64 v[124:125], v[124:125], 0, v[136:137]
	v_pk_mul_f32 v[118:119], v[118:119], v[172:173] op_sel_hi:[1,0]
	v_pk_mul_f32 v[114:115], v[114:115], v[172:173] op_sel_hi:[1,0]
	v_max_f32_e32 v116, 0, v116
	v_max_f32_e32 v112, 0, v112
	v_max_f32_e32 v117, 0, v117
	v_max_f32_e32 v113, 0, v113
	s_add_u32 s4, s84, s4
	global_store_dwordx4 v[124:125], v[120:123], off nt
	v_pk_mul_f32 v[116:117], v[116:117], v[116:117]
	v_max_f32_e32 v114, 0, v114
	v_pk_mul_f32 v[120:121], v[112:113], v[112:113]
	v_max_f32_e32 v112, 0, v118
	v_max_f32_e32 v113, 0, v119
	v_max_f32_e32 v115, 0, v115
	s_addc_u32 s5, s85, s5
	v_pk_mul_f32 v[118:119], v[112:113], v[112:113]
	v_pk_mul_f32 v[122:123], v[114:115], v[114:115]
	v_cvt_pk_bf16_f32 v112, v116, v117
	v_lshl_add_u64 v[116:117], s[4:5], 0, v[168:169]
	v_pk_mul_f32 v[108:109], v[108:109], v[182:183] op_sel_hi:[1,0]
	v_pk_mul_f32 v[104:105], v[104:105], v[182:183] op_sel_hi:[1,0]
	v_cvt_pk_bf16_f32 v113, v118, v119
	v_cvt_pk_bf16_f32 v114, v120, v121
	v_cvt_pk_bf16_f32 v115, v122, v123
	v_lshl_add_u64 v[116:117], v[116:117], 0, v[136:137]
	v_pk_mul_f32 v[110:111], v[110:111], v[182:183] op_sel_hi:[1,0]
	v_pk_mul_f32 v[106:107], v[106:107], v[182:183] op_sel_hi:[1,0]
	v_max_f32_e32 v108, 0, v108
	v_max_f32_e32 v104, 0, v104
	v_max_f32_e32 v109, 0, v109
	v_max_f32_e32 v105, 0, v105
	global_store_dwordx4 v[116:117], v[112:115], off nt
	v_pk_mul_f32 v[108:109], v[108:109], v[108:109]
	v_max_f32_e32 v106, 0, v106
	v_lshlrev_b64 v[112:113], 7, v[162:163]
	v_pk_mul_f32 v[114:115], v[104:105], v[104:105]
	v_max_f32_e32 v104, 0, v110
	v_max_f32_e32 v105, 0, v111
	v_max_f32_e32 v107, 0, v107
	v_pk_mul_f32 v[110:111], v[104:105], v[104:105]
	v_pk_mul_f32 v[116:117], v[106:107], v[106:107]
	v_cvt_pk_bf16_f32 v104, v108, v109
	v_lshl_add_u64 v[108:109], s[0:1], 0, v[112:113]
	v_pk_mul_f32 v[100:101], v[100:101], v[182:183] op_sel_hi:[1,0]
	v_pk_mul_f32 v[96:97], v[96:97], v[182:183] op_sel_hi:[1,0]
	v_cvt_pk_bf16_f32 v105, v110, v111
	v_cvt_pk_bf16_f32 v106, v114, v115
	v_cvt_pk_bf16_f32 v107, v116, v117
	v_lshl_add_u64 v[108:109], v[108:109], 0, v[136:137]
	v_pk_mul_f32 v[102:103], v[102:103], v[182:183] op_sel_hi:[1,0]
	v_pk_mul_f32 v[98:99], v[98:99], v[182:183] op_sel_hi:[1,0]
	v_max_f32_e32 v100, 0, v100
	v_max_f32_e32 v96, 0, v96
	v_max_f32_e32 v101, 0, v101
	v_max_f32_e32 v97, 0, v97
	global_store_dwordx4 v[108:109], v[104:107], off nt
	v_pk_mul_f32 v[100:101], v[100:101], v[100:101]
	v_max_f32_e32 v98, 0, v98
	v_pk_mul_f32 v[104:105], v[96:97], v[96:97]
	v_max_f32_e32 v96, 0, v102
	v_max_f32_e32 v97, 0, v103
	v_max_f32_e32 v99, 0, v99
	v_pk_mul_f32 v[102:103], v[96:97], v[96:97]
	v_pk_mul_f32 v[106:107], v[98:99], v[98:99]
	v_cvt_pk_bf16_f32 v96, v100, v101
	v_lshl_add_u64 v[100:101], s[4:5], 0, v[112:113]
	v_pk_mul_f32 v[92:93], v[92:93], v[170:171] op_sel_hi:[1,0]
	v_pk_mul_f32 v[88:89], v[88:89], v[170:171] op_sel_hi:[1,0]
	v_cvt_pk_bf16_f32 v97, v102, v103
	v_cvt_pk_bf16_f32 v98, v104, v105
	v_cvt_pk_bf16_f32 v99, v106, v107
	v_lshl_add_u64 v[100:101], v[100:101], 0, v[136:137]
	v_pk_mul_f32 v[94:95], v[94:95], v[170:171] op_sel_hi:[1,0]
	v_pk_mul_f32 v[90:91], v[90:91], v[170:171] op_sel_hi:[1,0]
	v_max_f32_e32 v92, 0, v92
	v_max_f32_e32 v88, 0, v88
	v_max_f32_e32 v93, 0, v93
	v_max_f32_e32 v89, 0, v89
	global_store_dwordx4 v[100:101], v[96:99], off nt
	v_pk_mul_f32 v[92:93], v[92:93], v[92:93]
	v_max_f32_e32 v90, 0, v90
	v_lshlrev_b64 v[96:97], 7, v[158:159]
	v_pk_mul_f32 v[98:99], v[88:89], v[88:89]
	v_max_f32_e32 v88, 0, v94
	v_max_f32_e32 v89, 0, v95
	v_max_f32_e32 v91, 0, v91
	v_pk_mul_f32 v[94:95], v[88:89], v[88:89]
	v_pk_mul_f32 v[100:101], v[90:91], v[90:91]
	v_cvt_pk_bf16_f32 v88, v92, v93
	v_lshl_add_u64 v[92:93], s[0:1], 0, v[96:97]
	v_pk_mul_f32 v[84:85], v[84:85], v[170:171] op_sel_hi:[1,0]
	v_pk_mul_f32 v[80:81], v[80:81], v[170:171] op_sel_hi:[1,0]
	v_cvt_pk_bf16_f32 v89, v94, v95
	v_cvt_pk_bf16_f32 v90, v98, v99
	v_cvt_pk_bf16_f32 v91, v100, v101
	v_lshl_add_u64 v[92:93], v[92:93], 0, v[136:137]
	v_pk_mul_f32 v[86:87], v[86:87], v[170:171] op_sel_hi:[1,0]
	v_pk_mul_f32 v[82:83], v[82:83], v[170:171] op_sel_hi:[1,0]
	v_max_f32_e32 v84, 0, v84
	v_max_f32_e32 v80, 0, v80
	v_max_f32_e32 v85, 0, v85
	v_max_f32_e32 v81, 0, v81
	global_store_dwordx4 v[92:93], v[88:91], off nt
	v_pk_mul_f32 v[84:85], v[84:85], v[84:85]
	v_max_f32_e32 v82, 0, v82
	v_pk_mul_f32 v[88:89], v[80:81], v[80:81]
	v_max_f32_e32 v80, 0, v86
	v_max_f32_e32 v81, 0, v87
	v_max_f32_e32 v83, 0, v83
	v_pk_mul_f32 v[86:87], v[80:81], v[80:81]
	v_pk_mul_f32 v[90:91], v[82:83], v[82:83]
	v_cvt_pk_bf16_f32 v80, v84, v85
	v_lshl_add_u64 v[84:85], s[4:5], 0, v[96:97]
	v_pk_mul_f32 v[76:77], v[76:77], v[166:167] op_sel_hi:[1,0]
	v_pk_mul_f32 v[72:73], v[72:73], v[166:167] op_sel_hi:[1,0]
	v_cvt_pk_bf16_f32 v81, v86, v87
	v_cvt_pk_bf16_f32 v82, v88, v89
	v_cvt_pk_bf16_f32 v83, v90, v91
	v_lshl_add_u64 v[84:85], v[84:85], 0, v[136:137]
	v_pk_mul_f32 v[78:79], v[78:79], v[166:167] op_sel_hi:[1,0]
	v_pk_mul_f32 v[74:75], v[74:75], v[166:167] op_sel_hi:[1,0]
	v_max_f32_e32 v76, 0, v76
	v_max_f32_e32 v72, 0, v72
	v_max_f32_e32 v77, 0, v77
	v_max_f32_e32 v73, 0, v73
	global_store_dwordx4 v[84:85], v[80:83], off nt
	v_pk_mul_f32 v[76:77], v[76:77], v[76:77]
	v_max_f32_e32 v74, 0, v74
	v_lshlrev_b64 v[80:81], 7, v[154:155]
	v_pk_mul_f32 v[82:83], v[72:73], v[72:73]
	v_max_f32_e32 v72, 0, v78
	v_max_f32_e32 v73, 0, v79
	v_max_f32_e32 v75, 0, v75
	v_pk_mul_f32 v[78:79], v[72:73], v[72:73]
	v_pk_mul_f32 v[84:85], v[74:75], v[74:75]
	v_cvt_pk_bf16_f32 v72, v76, v77
	v_lshl_add_u64 v[76:77], s[0:1], 0, v[80:81]
	v_pk_mul_f32 v[68:69], v[68:69], v[166:167] op_sel_hi:[1,0]
	v_pk_mul_f32 v[64:65], v[64:65], v[166:167] op_sel_hi:[1,0]
	v_cvt_pk_bf16_f32 v73, v78, v79
	v_cvt_pk_bf16_f32 v74, v82, v83
	v_cvt_pk_bf16_f32 v75, v84, v85
	v_lshl_add_u64 v[76:77], v[76:77], 0, v[136:137]
	v_pk_mul_f32 v[70:71], v[70:71], v[166:167] op_sel_hi:[1,0]
	v_pk_mul_f32 v[66:67], v[66:67], v[166:167] op_sel_hi:[1,0]
	v_max_f32_e32 v68, 0, v68
	v_max_f32_e32 v64, 0, v64
	v_max_f32_e32 v69, 0, v69
	v_max_f32_e32 v65, 0, v65
	global_store_dwordx4 v[76:77], v[72:75], off nt
	v_pk_mul_f32 v[68:69], v[68:69], v[68:69]
	v_max_f32_e32 v66, 0, v66
	v_pk_mul_f32 v[72:73], v[64:65], v[64:65]
	v_max_f32_e32 v64, 0, v70
	v_max_f32_e32 v65, 0, v71
	v_max_f32_e32 v67, 0, v67
	v_pk_mul_f32 v[70:71], v[64:65], v[64:65]
	v_pk_mul_f32 v[74:75], v[66:67], v[66:67]
	v_cvt_pk_bf16_f32 v64, v68, v69
	v_lshl_add_u64 v[68:69], s[4:5], 0, v[80:81]
	v_pk_mul_f32 v[60:61], v[60:61], v[164:165] op_sel_hi:[1,0]
	v_pk_mul_f32 v[56:57], v[56:57], v[164:165] op_sel_hi:[1,0]
	v_cvt_pk_bf16_f32 v65, v70, v71
	v_cvt_pk_bf16_f32 v66, v72, v73
	v_cvt_pk_bf16_f32 v67, v74, v75
	v_lshl_add_u64 v[68:69], v[68:69], 0, v[136:137]
	v_pk_mul_f32 v[62:63], v[62:63], v[164:165] op_sel_hi:[1,0]
	v_pk_mul_f32 v[58:59], v[58:59], v[164:165] op_sel_hi:[1,0]
	v_max_f32_e32 v60, 0, v60
	v_max_f32_e32 v56, 0, v56
	v_max_f32_e32 v61, 0, v61
	v_max_f32_e32 v57, 0, v57
	global_store_dwordx4 v[68:69], v[64:67], off nt
	v_pk_mul_f32 v[60:61], v[60:61], v[60:61]
	v_max_f32_e32 v58, 0, v58
	v_lshlrev_b64 v[64:65], 7, v[150:151]
	v_pk_mul_f32 v[66:67], v[56:57], v[56:57]
	v_max_f32_e32 v56, 0, v62
	v_max_f32_e32 v57, 0, v63
	v_max_f32_e32 v59, 0, v59
	v_pk_mul_f32 v[62:63], v[56:57], v[56:57]
	v_pk_mul_f32 v[68:69], v[58:59], v[58:59]
	v_cvt_pk_bf16_f32 v56, v60, v61
	v_lshl_add_u64 v[60:61], s[0:1], 0, v[64:65]
	v_pk_mul_f32 v[52:53], v[52:53], v[164:165] op_sel_hi:[1,0]
	v_pk_mul_f32 v[48:49], v[48:49], v[164:165] op_sel_hi:[1,0]
	v_cvt_pk_bf16_f32 v57, v62, v63
	v_cvt_pk_bf16_f32 v58, v66, v67
	v_cvt_pk_bf16_f32 v59, v68, v69
	v_lshl_add_u64 v[60:61], v[60:61], 0, v[136:137]
	v_pk_mul_f32 v[54:55], v[54:55], v[164:165] op_sel_hi:[1,0]
	v_pk_mul_f32 v[50:51], v[50:51], v[164:165] op_sel_hi:[1,0]
	v_max_f32_e32 v52, 0, v52
	v_max_f32_e32 v48, 0, v48
	v_max_f32_e32 v53, 0, v53
	v_max_f32_e32 v49, 0, v49
	global_store_dwordx4 v[60:61], v[56:59], off nt
	v_pk_mul_f32 v[52:53], v[52:53], v[52:53]
	v_max_f32_e32 v50, 0, v50
	v_pk_mul_f32 v[56:57], v[48:49], v[48:49]
	v_max_f32_e32 v48, 0, v54
	v_max_f32_e32 v49, 0, v55
	v_max_f32_e32 v51, 0, v51
	v_pk_mul_f32 v[54:55], v[48:49], v[48:49]
	v_pk_mul_f32 v[58:59], v[50:51], v[50:51]
	v_cvt_pk_bf16_f32 v48, v52, v53
	v_lshl_add_u64 v[52:53], s[4:5], 0, v[64:65]
	v_pk_mul_f32 v[44:45], v[44:45], v[160:161] op_sel_hi:[1,0]
	v_pk_mul_f32 v[40:41], v[40:41], v[160:161] op_sel_hi:[1,0]
	v_cvt_pk_bf16_f32 v49, v54, v55
	v_cvt_pk_bf16_f32 v50, v56, v57
	v_cvt_pk_bf16_f32 v51, v58, v59
	v_lshl_add_u64 v[52:53], v[52:53], 0, v[136:137]
	v_pk_mul_f32 v[46:47], v[46:47], v[160:161] op_sel_hi:[1,0]
	v_pk_mul_f32 v[42:43], v[42:43], v[160:161] op_sel_hi:[1,0]
	v_max_f32_e32 v44, 0, v44
	v_max_f32_e32 v40, 0, v40
	v_max_f32_e32 v45, 0, v45
	v_max_f32_e32 v41, 0, v41
	global_store_dwordx4 v[52:53], v[48:51], off nt
	v_pk_mul_f32 v[44:45], v[44:45], v[44:45]
	v_max_f32_e32 v42, 0, v42
	v_lshlrev_b64 v[48:49], 7, v[148:149]
	v_pk_mul_f32 v[50:51], v[40:41], v[40:41]
	v_max_f32_e32 v40, 0, v46
	v_max_f32_e32 v41, 0, v47
	v_max_f32_e32 v43, 0, v43
	v_pk_mul_f32 v[46:47], v[40:41], v[40:41]
	v_pk_mul_f32 v[52:53], v[42:43], v[42:43]
	v_cvt_pk_bf16_f32 v40, v44, v45
	v_lshl_add_u64 v[44:45], s[0:1], 0, v[48:49]
	v_pk_mul_f32 v[36:37], v[36:37], v[160:161] op_sel_hi:[1,0]
	v_pk_mul_f32 v[32:33], v[32:33], v[160:161] op_sel_hi:[1,0]
	v_cvt_pk_bf16_f32 v41, v46, v47
	v_cvt_pk_bf16_f32 v42, v50, v51
	v_cvt_pk_bf16_f32 v43, v52, v53
	v_lshl_add_u64 v[44:45], v[44:45], 0, v[136:137]
	v_pk_mul_f32 v[38:39], v[38:39], v[160:161] op_sel_hi:[1,0]
	v_pk_mul_f32 v[34:35], v[34:35], v[160:161] op_sel_hi:[1,0]
	v_max_f32_e32 v36, 0, v36
	v_max_f32_e32 v32, 0, v32
	v_max_f32_e32 v37, 0, v37
	v_max_f32_e32 v33, 0, v33
	global_store_dwordx4 v[44:45], v[40:43], off nt
	v_pk_mul_f32 v[36:37], v[36:37], v[36:37]
	v_max_f32_e32 v34, 0, v34
	v_pk_mul_f32 v[40:41], v[32:33], v[32:33]
	v_max_f32_e32 v32, 0, v38
	v_max_f32_e32 v33, 0, v39
	v_max_f32_e32 v35, 0, v35
	v_pk_mul_f32 v[38:39], v[32:33], v[32:33]
	v_pk_mul_f32 v[42:43], v[34:35], v[34:35]
	v_cvt_pk_bf16_f32 v32, v36, v37
	v_lshl_add_u64 v[36:37], s[4:5], 0, v[48:49]
	v_pk_mul_f32 v[28:29], v[28:29], v[156:157] op_sel_hi:[1,0]
	v_pk_mul_f32 v[24:25], v[24:25], v[156:157] op_sel_hi:[1,0]
	v_cvt_pk_bf16_f32 v33, v38, v39
	v_cvt_pk_bf16_f32 v34, v40, v41
	v_cvt_pk_bf16_f32 v35, v42, v43
	v_lshl_add_u64 v[36:37], v[36:37], 0, v[136:137]
	v_pk_mul_f32 v[30:31], v[30:31], v[156:157] op_sel_hi:[1,0]
	v_pk_mul_f32 v[26:27], v[26:27], v[156:157] op_sel_hi:[1,0]
	v_max_f32_e32 v28, 0, v28
	v_max_f32_e32 v24, 0, v24
	v_max_f32_e32 v29, 0, v29
	v_max_f32_e32 v25, 0, v25
	global_store_dwordx4 v[36:37], v[32:35], off nt
	v_pk_mul_f32 v[28:29], v[28:29], v[28:29]
	v_max_f32_e32 v26, 0, v26
	v_lshlrev_b64 v[32:33], 7, v[146:147]
	v_pk_mul_f32 v[34:35], v[24:25], v[24:25]
	v_max_f32_e32 v24, 0, v30
	v_max_f32_e32 v25, 0, v31
	v_max_f32_e32 v27, 0, v27
	v_pk_mul_f32 v[30:31], v[24:25], v[24:25]
	v_pk_mul_f32 v[36:37], v[26:27], v[26:27]
	v_cvt_pk_bf16_f32 v24, v28, v29
	v_lshl_add_u64 v[28:29], s[0:1], 0, v[32:33]
	v_pk_mul_f32 v[20:21], v[20:21], v[156:157] op_sel_hi:[1,0]
	v_pk_mul_f32 v[16:17], v[16:17], v[156:157] op_sel_hi:[1,0]
	v_cvt_pk_bf16_f32 v25, v30, v31
	v_cvt_pk_bf16_f32 v26, v34, v35
	v_cvt_pk_bf16_f32 v27, v36, v37
	v_lshl_add_u64 v[28:29], v[28:29], 0, v[136:137]
	v_pk_mul_f32 v[22:23], v[22:23], v[156:157] op_sel_hi:[1,0]
	v_pk_mul_f32 v[18:19], v[18:19], v[156:157] op_sel_hi:[1,0]
	v_max_f32_e32 v20, 0, v20
	v_max_f32_e32 v16, 0, v16
	v_max_f32_e32 v21, 0, v21
	v_max_f32_e32 v17, 0, v17
	global_store_dwordx4 v[28:29], v[24:27], off nt
	v_pk_mul_f32 v[20:21], v[20:21], v[20:21]
	v_max_f32_e32 v18, 0, v18
	v_pk_mul_f32 v[24:25], v[16:17], v[16:17]
	v_max_f32_e32 v16, 0, v22
	v_max_f32_e32 v17, 0, v23
	v_max_f32_e32 v19, 0, v19
	v_pk_mul_f32 v[22:23], v[16:17], v[16:17]
	v_pk_mul_f32 v[26:27], v[18:19], v[18:19]
	v_cvt_pk_bf16_f32 v16, v20, v21
	v_lshl_add_u64 v[20:21], s[4:5], 0, v[32:33]
	v_pk_mul_f32 v[12:13], v[12:13], v[152:153] op_sel_hi:[1,0]
	v_pk_mul_f32 v[8:9], v[8:9], v[152:153] op_sel_hi:[1,0]
	v_cvt_pk_bf16_f32 v17, v22, v23
	v_cvt_pk_bf16_f32 v18, v24, v25
	v_cvt_pk_bf16_f32 v19, v26, v27
	v_lshl_add_u64 v[20:21], v[20:21], 0, v[136:137]
	v_pk_mul_f32 v[14:15], v[14:15], v[152:153] op_sel_hi:[1,0]
	v_pk_mul_f32 v[10:11], v[10:11], v[152:153] op_sel_hi:[1,0]
	v_max_f32_e32 v12, 0, v12
	v_max_f32_e32 v8, 0, v8
	v_max_f32_e32 v13, 0, v13
	v_max_f32_e32 v9, 0, v9
	global_store_dwordx4 v[20:21], v[16:19], off nt
	v_pk_mul_f32 v[12:13], v[12:13], v[12:13]
	v_max_f32_e32 v10, 0, v10
	v_lshlrev_b64 v[16:17], 7, v[144:145]
	v_pk_mul_f32 v[18:19], v[8:9], v[8:9]
	v_max_f32_e32 v8, 0, v14
	v_max_f32_e32 v9, 0, v15
	v_max_f32_e32 v11, 0, v11
	v_pk_mul_f32 v[14:15], v[8:9], v[8:9]
	v_pk_mul_f32 v[20:21], v[10:11], v[10:11]
	v_cvt_pk_bf16_f32 v8, v12, v13
	v_lshl_add_u64 v[12:13], s[0:1], 0, v[16:17]
	v_pk_mul_f32 v[4:5], v[4:5], v[152:153] op_sel_hi:[1,0]
	v_pk_mul_f32 v[0:1], v[0:1], v[152:153] op_sel_hi:[1,0]
	v_cvt_pk_bf16_f32 v9, v14, v15
	v_cvt_pk_bf16_f32 v10, v18, v19
	v_cvt_pk_bf16_f32 v11, v20, v21
	v_lshl_add_u64 v[12:13], v[12:13], 0, v[136:137]
	v_pk_mul_f32 v[6:7], v[6:7], v[152:153] op_sel_hi:[1,0]
	v_pk_mul_f32 v[2:3], v[2:3], v[152:153] op_sel_hi:[1,0]
	v_max_f32_e32 v4, 0, v4
	v_max_f32_e32 v0, 0, v0
	v_max_f32_e32 v5, 0, v5
	v_max_f32_e32 v1, 0, v1
	global_store_dwordx4 v[12:13], v[8:11], off nt
	v_pk_mul_f32 v[4:5], v[4:5], v[4:5]
	v_max_f32_e32 v2, 0, v2
	v_pk_mul_f32 v[8:9], v[0:1], v[0:1]
	v_max_f32_e32 v0, 0, v6
	v_max_f32_e32 v1, 0, v7
	v_max_f32_e32 v3, 0, v3
	v_pk_mul_f32 v[6:7], v[0:1], v[0:1]
	v_pk_mul_f32 v[10:11], v[2:3], v[2:3]
	v_cvt_pk_bf16_f32 v0, v4, v5
	v_lshl_add_u64 v[4:5], s[4:5], 0, v[16:17]
	v_cvt_pk_bf16_f32 v1, v6, v7
	v_cvt_pk_bf16_f32 v2, v8, v9
	v_cvt_pk_bf16_f32 v3, v10, v11
	v_lshl_add_u64 v[4:5], v[4:5], 0, v[136:137]
	s_and_b64 vcc, exec, s[24:25]
	s_mov_b32 s70, s20
	s_mov_b32 s24, s20
	s_mov_b64 s[4:5], s[26:27]
	s_mov_b64 s[0:1], s[22:23]
	global_store_dwordx4 v[4:5], v[0:3], off nt
	s_cbranch_vccz .LBB0_1433
	s_waitcnt vmcnt(0)
	s_cmpk_gt_u32 s7, 0xff
	s_cbranch_scc1 .LBB0_1445
	s_barrier

.LBB0_1512:
	ds_read_b128 v[144:147], v204
	ds_read_b128 v[148:151], v204 offset:1024
	ds_read_b128 v[172:175], v204 offset:2048
	ds_read_b128 v[176:179], v204 offset:3072
	ds_read_b128 v[180:183], v204 offset:4096
	ds_read_b128 v[184:187], v204 offset:5120
	ds_read_b128 v[188:191], v204 offset:6144
	ds_read_b128 v[192:195], v204 offset:7168
	ds_read_b128 v[128:131], v203
	ds_read_b128 v[132:135], v203 offset:1024
	ds_read_b128 v[136:139], v203 offset:2048
	ds_read_b128 v[140:143], v203 offset:3072
	s_add_u32 s26, s24, 0x3fc000
	s_addc_u32 s27, s25, 0
	s_cmp_eq_u32 s49, 60
	s_cselect_b32 s30, s7, s26
	s_cselect_b32 s31, s5, s27
	s_cselect_b32 s26, s15, s17
	s_cselect_b32 s27, s8, s48
	s_add_u32 s28, s30, 0x400000
	s_addc_u32 s29, s31, 0
	v_lshl_add_u64 v[196:197], s[24:25], 0, v[168:169]
	s_add_i32 m0, s33, 0xc000
	s_nop 0
	global_load_lds_dwordx4 v[196:197], off
	v_lshl_add_u64 v[196:197], s[24:25], 0, v[170:171]
	s_add_i32 m0, s33, 0xe000
	s_nop 0
	global_load_lds_dwordx4 v[196:197], off
	s_waitcnt lgkmcnt(0)
	s_barrier
	v_mfma_f32_16x16x32_bf16 v[124:127], v[128:131], v[144:147], v[124:127]
	v_mfma_f32_16x16x32_bf16 v[120:123], v[136:139], v[144:147], v[120:123]
	v_mfma_f32_16x16x32_bf16 v[108:111], v[128:131], v[172:175], v[108:111]
	v_mfma_f32_16x16x32_bf16 v[104:107], v[136:139], v[172:175], v[104:107]
	v_mfma_f32_16x16x32_bf16 v[92:95], v[128:131], v[180:183], v[92:95]
	v_mfma_f32_16x16x32_bf16 v[88:91], v[136:139], v[180:183], v[88:91]
	v_mfma_f32_16x16x32_bf16 v[76:79], v[128:131], v[188:191], v[76:79]
	v_mfma_f32_16x16x32_bf16 v[72:75], v[136:139], v[188:191], v[72:75]
	v_mfma_f32_16x16x32_bf16 v[124:127], v[132:135], v[148:151], v[124:127]
	v_mfma_f32_16x16x32_bf16 v[120:123], v[140:143], v[148:151], v[120:123]
	v_mfma_f32_16x16x32_bf16 v[108:111], v[132:135], v[176:179], v[108:111]
	v_mfma_f32_16x16x32_bf16 v[104:107], v[140:143], v[176:179], v[104:107]
	v_mfma_f32_16x16x32_bf16 v[92:95], v[132:135], v[184:187], v[92:95]
	v_mfma_f32_16x16x32_bf16 v[88:91], v[140:143], v[184:187], v[88:91]
	v_mfma_f32_16x16x32_bf16 v[76:79], v[132:135], v[192:195], v[76:79]
	v_mfma_f32_16x16x32_bf16 v[72:75], v[140:143], v[192:195], v[72:75]
	s_barrier
	s_add_i32 s50, s44, s13
	v_lshl_add_u64 v[200:201], s[26:27], 0, v[156:157]
	s_mov_b32 m0, s50
	ds_read_b128 v[196:199], v205
	ds_read_b128 v[208:211], v205 offset:1024
	ds_read_b128 v[212:215], v205 offset:2048
	ds_read_b128 v[216:219], v205 offset:3072
	global_load_lds_dwordx4 v[200:201], off
	v_lshl_add_u64 v[200:201], s[26:27], 0, v[152:153]
	s_add_i32 m0, s50, 0x2000
	s_nop 0
	global_load_lds_dwordx4 v[200:201], off
	s_barrier
	s_waitcnt lgkmcnt(0)
	v_mfma_f32_16x16x32_bf16 v[116:119], v[196:199], v[144:147], v[116:119]
	v_mfma_f32_16x16x32_bf16 v[112:115], v[212:215], v[144:147], v[112:115]
	v_mfma_f32_16x16x32_bf16 v[100:103], v[196:199], v[172:175], v[100:103]
	v_mfma_f32_16x16x32_bf16 v[96:99], v[212:215], v[172:175], v[96:99]
	v_mfma_f32_16x16x32_bf16 v[84:87], v[196:199], v[180:183], v[84:87]
	v_mfma_f32_16x16x32_bf16 v[80:83], v[212:215], v[180:183], v[80:83]
	v_mfma_f32_16x16x32_bf16 v[68:71], v[196:199], v[188:191], v[68:71]
	v_mfma_f32_16x16x32_bf16 v[64:67], v[212:215], v[188:191], v[64:67]
	v_mfma_f32_16x16x32_bf16 v[116:119], v[208:211], v[148:151], v[116:119]
	v_mfma_f32_16x16x32_bf16 v[112:115], v[216:219], v[148:151], v[112:115]
	v_mfma_f32_16x16x32_bf16 v[100:103], v[208:211], v[176:179], v[100:103]
	v_mfma_f32_16x16x32_bf16 v[96:99], v[216:219], v[176:179], v[96:99]
	v_mfma_f32_16x16x32_bf16 v[84:87], v[208:211], v[184:187], v[84:87]
	v_mfma_f32_16x16x32_bf16 v[80:83], v[216:219], v[184:187], v[80:83]
	v_mfma_f32_16x16x32_bf16 v[68:71], v[208:211], v[192:195], v[68:71]
	v_mfma_f32_16x16x32_bf16 v[64:67], v[216:219], v[192:195], v[64:67]
	s_barrier
	s_mov_b32 m0, s33
	v_lshl_add_u64 v[200:201], s[30:31], 0, v[158:159]
	ds_read_b128 v[144:147], v204 offset:16384
	ds_read_b128 v[148:151], v204 offset:17408
	ds_read_b128 v[172:175], v204 offset:18432
	ds_read_b128 v[176:179], v204 offset:19456
	ds_read_b128 v[180:183], v204 offset:20480
	ds_read_b128 v[184:187], v204 offset:21504
	ds_read_b128 v[188:191], v204 offset:22528
	ds_read_b128 v[192:195], v204 offset:23552
	global_load_lds_dwordx4 v[200:201], off
	v_lshl_add_u64 v[200:201], s[30:31], 0, v[154:155]
	s_mov_b32 m0, s35
	s_nop 0
	global_load_lds_dwordx4 v[200:201], off
	s_barrier
	s_waitcnt lgkmcnt(0)
	v_mfma_f32_16x16x32_bf16 v[60:63], v[128:131], v[144:147], v[60:63]
	v_mfma_f32_16x16x32_bf16 v[56:59], v[136:139], v[144:147], v[56:59]
	v_mfma_f32_16x16x32_bf16 v[44:47], v[128:131], v[172:175], v[44:47]
	v_mfma_f32_16x16x32_bf16 v[40:43], v[136:139], v[172:175], v[40:43]
	v_mfma_f32_16x16x32_bf16 v[28:31], v[128:131], v[180:183], v[28:31]
	v_mfma_f32_16x16x32_bf16 v[24:27], v[136:139], v[180:183], v[24:27]
	v_mfma_f32_16x16x32_bf16 v[12:15], v[128:131], v[188:191], v[12:15]
	v_mfma_f32_16x16x32_bf16 v[8:11], v[136:139], v[188:191], v[8:11]
	v_mfma_f32_16x16x32_bf16 v[60:63], v[132:135], v[148:151], v[60:63]
	v_mfma_f32_16x16x32_bf16 v[56:59], v[140:143], v[148:151], v[56:59]
	v_mfma_f32_16x16x32_bf16 v[44:47], v[132:135], v[176:179], v[44:47]
	v_mfma_f32_16x16x32_bf16 v[40:43], v[140:143], v[176:179], v[40:43]
	v_mfma_f32_16x16x32_bf16 v[28:31], v[132:135], v[184:187], v[28:31]
	v_mfma_f32_16x16x32_bf16 v[24:27], v[140:143], v[184:187], v[24:27]
	v_mfma_f32_16x16x32_bf16 v[12:15], v[132:135], v[192:195], v[12:15]
	v_mfma_f32_16x16x32_bf16 v[8:11], v[140:143], v[192:195], v[8:11]
	s_barrier
	s_add_u32 s50, s26, 0x4000
	s_addc_u32 s51, s27, 0
	s_add_i32 s52, s45, s13
	v_lshl_add_u64 v[128:129], s[50:51], 0, v[156:157]
	s_mov_b32 m0, s52
	s_nop 0
	global_load_lds_dwordx4 v[128:129], off
	v_lshl_add_u64 v[128:129], s[50:51], 0, v[152:153]
	s_add_i32 m0, s52, 0x2000
	s_nop 0
	global_load_lds_dwordx4 v[128:129], off
	s_waitcnt vmcnt(6)
	s_barrier
	v_mfma_f32_16x16x32_bf16 v[52:55], v[196:199], v[144:147], v[52:55]
	v_mfma_f32_16x16x32_bf16 v[48:51], v[212:215], v[144:147], v[48:51]
	v_mfma_f32_16x16x32_bf16 v[36:39], v[196:199], v[172:175], v[36:39]
	v_mfma_f32_16x16x32_bf16 v[32:35], v[212:215], v[172:175], v[32:35]
	v_mfma_f32_16x16x32_bf16 v[20:23], v[196:199], v[180:183], v[20:23]
	v_mfma_f32_16x16x32_bf16 v[16:19], v[212:215], v[180:183], v[16:19]
	v_mfma_f32_16x16x32_bf16 v[4:7], v[196:199], v[188:191], v[4:7]
	v_mfma_f32_16x16x32_bf16 v[0:3], v[212:215], v[188:191], v[0:3]
	v_mfma_f32_16x16x32_bf16 v[52:55], v[208:211], v[148:151], v[52:55]
	v_mfma_f32_16x16x32_bf16 v[48:51], v[216:219], v[148:151], v[48:51]
	v_mfma_f32_16x16x32_bf16 v[36:39], v[208:211], v[176:179], v[36:39]
	v_mfma_f32_16x16x32_bf16 v[32:35], v[216:219], v[176:179], v[32:35]
	v_mfma_f32_16x16x32_bf16 v[20:23], v[208:211], v[184:187], v[20:23]
	v_mfma_f32_16x16x32_bf16 v[16:19], v[216:219], v[184:187], v[16:19]
	v_mfma_f32_16x16x32_bf16 v[4:7], v[208:211], v[192:195], v[4:7]
	v_mfma_f32_16x16x32_bf16 v[0:3], v[216:219], v[192:195], v[0:3]
	s_barrier
	s_add_i32 s50, 0, 0x18000
	v_add_u32_e32 v140, s50, v202
	ds_read_b128 v[144:147], v204 offset:32768
	ds_read_b128 v[148:151], v204 offset:33792
	ds_read_b128 v[172:175], v204 offset:34816
	ds_read_b128 v[176:179], v204 offset:35840
	ds_read_b128 v[180:183], v204 offset:36864
	ds_read_b128 v[184:187], v204 offset:37888
	ds_read_b128 v[188:191], v204 offset:38912
	ds_read_b128 v[192:195], v204 offset:39936
	ds_read_b128 v[128:131], v140
	ds_read_b128 v[132:135], v140 offset:1024
	ds_read_b128 v[136:139], v140 offset:2048
	ds_read_b128 v[140:143], v140 offset:3072
	s_add_u32 s30, s30, 0x4000
	s_addc_u32 s31, s31, 0
	s_mov_b32 m0, s36
	v_lshl_add_u64 v[196:197], s[30:31], 0, v[158:159]
	global_load_lds_dwordx4 v[196:197], off
	v_lshl_add_u64 v[196:197], s[30:31], 0, v[154:155]
	s_mov_b32 m0, s37
	s_nop 0
	global_load_lds_dwordx4 v[196:197], off
	s_waitcnt lgkmcnt(0)
	s_barrier
	v_mfma_f32_16x16x32_bf16 v[124:127], v[128:131], v[144:147], v[124:127]
	v_mfma_f32_16x16x32_bf16 v[120:123], v[136:139], v[144:147], v[120:123]
	v_mfma_f32_16x16x32_bf16 v[108:111], v[128:131], v[172:175], v[108:111]
	v_mfma_f32_16x16x32_bf16 v[104:107], v[136:139], v[172:175], v[104:107]
	v_mfma_f32_16x16x32_bf16 v[92:95], v[128:131], v[180:183], v[92:95]
	v_mfma_f32_16x16x32_bf16 v[88:91], v[136:139], v[180:183], v[88:91]
	v_mfma_f32_16x16x32_bf16 v[76:79], v[128:131], v[188:191], v[76:79]
	v_mfma_f32_16x16x32_bf16 v[72:75], v[136:139], v[188:191], v[72:75]
	v_mfma_f32_16x16x32_bf16 v[124:127], v[132:135], v[148:151], v[124:127]
	v_mfma_f32_16x16x32_bf16 v[120:123], v[140:143], v[148:151], v[120:123]
	v_mfma_f32_16x16x32_bf16 v[108:111], v[132:135], v[176:179], v[108:111]
	v_mfma_f32_16x16x32_bf16 v[104:107], v[140:143], v[176:179], v[104:107]
	v_mfma_f32_16x16x32_bf16 v[92:95], v[132:135], v[184:187], v[92:95]
	v_mfma_f32_16x16x32_bf16 v[88:91], v[140:143], v[184:187], v[88:91]
	v_mfma_f32_16x16x32_bf16 v[76:79], v[132:135], v[192:195], v[76:79]
	v_mfma_f32_16x16x32_bf16 v[72:75], v[140:143], v[192:195], v[72:75]
	s_barrier
	s_add_i32 s51, 0, 0x1c000
	s_add_u32 s30, s26, 0x20000
	v_add_u32_e32 v200, s51, v202
	s_addc_u32 s31, s27, 0
	s_add_i32 s50, s50, s13
	ds_read_b128 v[196:199], v200
	ds_read_b128 v[208:211], v200 offset:1024
	ds_read_b128 v[212:215], v200 offset:2048
	ds_read_b128 v[216:219], v200 offset:3072
	v_lshl_add_u64 v[200:201], s[30:31], 0, v[156:157]
	s_mov_b32 m0, s50
	s_nop 0
	global_load_lds_dwordx4 v[200:201], off
	v_lshl_add_u64 v[200:201], s[30:31], 0, v[152:153]
	s_add_i32 m0, s50, 0x2000
	s_nop 0
	global_load_lds_dwordx4 v[200:201], off
	s_barrier
	s_waitcnt lgkmcnt(0)
	v_mfma_f32_16x16x32_bf16 v[116:119], v[196:199], v[144:147], v[116:119]
	v_mfma_f32_16x16x32_bf16 v[112:115], v[212:215], v[144:147], v[112:115]
	v_mfma_f32_16x16x32_bf16 v[100:103], v[196:199], v[172:175], v[100:103]
	v_mfma_f32_16x16x32_bf16 v[96:99], v[212:215], v[172:175], v[96:99]
	v_mfma_f32_16x16x32_bf16 v[84:87], v[196:199], v[180:183], v[84:87]
	v_mfma_f32_16x16x32_bf16 v[80:83], v[212:215], v[180:183], v[80:83]
	v_mfma_f32_16x16x32_bf16 v[68:71], v[196:199], v[188:191], v[68:71]
	v_mfma_f32_16x16x32_bf16 v[64:67], v[212:215], v[188:191], v[64:67]
	v_mfma_f32_16x16x32_bf16 v[116:119], v[208:211], v[148:151], v[116:119]
	v_mfma_f32_16x16x32_bf16 v[112:115], v[216:219], v[148:151], v[112:115]
	v_mfma_f32_16x16x32_bf16 v[100:103], v[208:211], v[176:179], v[100:103]
	v_mfma_f32_16x16x32_bf16 v[96:99], v[216:219], v[176:179], v[96:99]
	v_mfma_f32_16x16x32_bf16 v[84:87], v[208:211], v[184:187], v[84:87]
	v_mfma_f32_16x16x32_bf16 v[80:83], v[216:219], v[184:187], v[80:83]
	v_mfma_f32_16x16x32_bf16 v[68:71], v[208:211], v[192:195], v[68:71]
	v_mfma_f32_16x16x32_bf16 v[64:67], v[216:219], v[192:195], v[64:67]
	s_barrier
	s_mov_b32 m0, s41
	v_lshl_add_u64 v[200:201], s[28:29], 0, v[158:159]
	ds_read_b128 v[144:147], v204 offset:49152
	ds_read_b128 v[148:151], v204 offset:50176
	ds_read_b128 v[172:175], v204 offset:51200
	ds_read_b128 v[176:179], v204 offset:52224
	ds_read_b128 v[180:183], v204 offset:53248
	ds_read_b128 v[184:187], v204 offset:54272
	ds_read_b128 v[188:191], v204 offset:55296
	ds_read_b128 v[192:195], v204 offset:56320
	global_load_lds_dwordx4 v[200:201], off
	v_lshl_add_u64 v[200:201], s[28:29], 0, v[154:155]
	s_mov_b32 m0, s42
	s_nop 0
	global_load_lds_dwordx4 v[200:201], off
	s_barrier
	s_waitcnt lgkmcnt(0)
	v_mfma_f32_16x16x32_bf16 v[60:63], v[128:131], v[144:147], v[60:63]
	v_mfma_f32_16x16x32_bf16 v[56:59], v[136:139], v[144:147], v[56:59]
	v_mfma_f32_16x16x32_bf16 v[44:47], v[128:131], v[172:175], v[44:47]
	v_mfma_f32_16x16x32_bf16 v[40:43], v[136:139], v[172:175], v[40:43]
	v_mfma_f32_16x16x32_bf16 v[28:31], v[128:131], v[180:183], v[28:31]
	v_mfma_f32_16x16x32_bf16 v[24:27], v[136:139], v[180:183], v[24:27]
	v_mfma_f32_16x16x32_bf16 v[12:15], v[128:131], v[188:191], v[12:15]
	v_mfma_f32_16x16x32_bf16 v[8:11], v[136:139], v[188:191], v[8:11]
	v_mfma_f32_16x16x32_bf16 v[60:63], v[132:135], v[148:151], v[60:63]
	v_mfma_f32_16x16x32_bf16 v[56:59], v[140:143], v[148:151], v[56:59]
	v_mfma_f32_16x16x32_bf16 v[44:47], v[132:135], v[176:179], v[44:47]
	v_mfma_f32_16x16x32_bf16 v[40:43], v[140:143], v[176:179], v[40:43]
	v_mfma_f32_16x16x32_bf16 v[28:31], v[132:135], v[184:187], v[28:31]
	v_mfma_f32_16x16x32_bf16 v[24:27], v[140:143], v[184:187], v[24:27]
	v_mfma_f32_16x16x32_bf16 v[12:15], v[132:135], v[192:195], v[12:15]
	v_mfma_f32_16x16x32_bf16 v[8:11], v[140:143], v[192:195], v[8:11]
	s_barrier
	s_add_u32 s26, s26, 0x24000
	s_addc_u32 s27, s27, 0
	s_add_i32 s28, s51, s13
	v_lshl_add_u64 v[128:129], s[26:27], 0, v[156:157]
	s_mov_b32 m0, s28
	s_nop 0
	global_load_lds_dwordx4 v[128:129], off
	v_lshl_add_u64 v[128:129], s[26:27], 0, v[152:153]
	s_add_i32 m0, s28, 0x2000
	s_nop 0
	global_load_lds_dwordx4 v[128:129], off
	s_waitcnt vmcnt(6)
	s_barrier
	v_mfma_f32_16x16x32_bf16 v[52:55], v[196:199], v[144:147], v[52:55]
	v_mfma_f32_16x16x32_bf16 v[48:51], v[212:215], v[144:147], v[48:51]
	v_mfma_f32_16x16x32_bf16 v[36:39], v[196:199], v[172:175], v[36:39]
	v_mfma_f32_16x16x32_bf16 v[32:35], v[212:215], v[172:175], v[32:35]
	v_mfma_f32_16x16x32_bf16 v[20:23], v[196:199], v[180:183], v[20:23]
	v_mfma_f32_16x16x32_bf16 v[16:19], v[212:215], v[180:183], v[16:19]
	v_mfma_f32_16x16x32_bf16 v[4:7], v[196:199], v[188:191], v[4:7]
	v_mfma_f32_16x16x32_bf16 v[0:3], v[212:215], v[188:191], v[0:3]
	v_mfma_f32_16x16x32_bf16 v[52:55], v[208:211], v[148:151], v[52:55]
	v_mfma_f32_16x16x32_bf16 v[48:51], v[216:219], v[148:151], v[48:51]
	v_mfma_f32_16x16x32_bf16 v[36:39], v[208:211], v[176:179], v[36:39]
	v_mfma_f32_16x16x32_bf16 v[32:35], v[216:219], v[176:179], v[32:35]
	v_mfma_f32_16x16x32_bf16 v[20:23], v[208:211], v[184:187], v[20:23]
	v_mfma_f32_16x16x32_bf16 v[16:19], v[216:219], v[184:187], v[16:19]
	v_mfma_f32_16x16x32_bf16 v[4:7], v[208:211], v[192:195], v[4:7]
	v_mfma_f32_16x16x32_bf16 v[0:3], v[216:219], v[192:195], v[0:3]
	s_barrier
	s_add_i32 s49, s49, 2
	s_add_u32 s17, s17, 0x40000
	s_addc_u32 s48, s48, 0
	s_add_u32 s24, s24, 0x800000
	s_addc_u32 s25, s25, 0
	s_cmp_gt_u32 s49, 61
	s_cbranch_scc0 .LBB0_1512
	s_nop 0
	s_lshl_b32 s24, s4, 8
	v_readlane_b32 s68, v253, 38
	v_readlane_b32 s69, v253, 39
	s_ashr_i32 s25, s24, 31
	s_lshl_b32 s4, s4, 2
	v_readlane_b32 s70, v253, 40
	v_readlane_b32 s71, v253, 41
	s_mov_b64 s[48:49], s[68:69]
	v_lshl_add_u32 v178, s6, 8, v163
	s_ashr_i32 s5, s4, 31
	s_lshl_b64 s[26:27], s[24:25], 1
	s_mov_b64 s[50:51], s[70:71]
	s_add_u32 s26, s50, s26
	v_ashrrev_i32_e32 v179, 31, v178
	s_addc_u32 s27, s51, s27
	v_lshlrev_b64 v[128:129], 11, v[178:179]
	v_lshl_add_u64 v[128:129], s[26:27], 0, v[128:129]
	v_lshl_add_u64 v[128:129], v[128:129], 0, v[160:161]
	global_load_dwordx4 v[180:183], v[128:129], off
	global_load_dwordx4 v[184:187], v[128:129], off offset:256
	v_or_b32_e32 v176, 16, v178
	v_or_b32_e32 v174, 32, v178
	v_or_b32_e32 v172, 48, v178
	v_ashrrev_i32_e32 v177, 31, v176
	v_ashrrev_i32_e32 v175, 31, v174
	v_ashrrev_i32_e32 v173, 31, v172
	v_lshlrev_b64 v[128:129], 11, v[176:177]
	v_lshlrev_b64 v[130:131], 11, v[174:175]
	v_lshlrev_b64 v[132:133], 11, v[172:173]
	v_lshl_add_u64 v[128:129], s[26:27], 0, v[128:129]
	v_lshl_add_u64 v[130:131], s[26:27], 0, v[130:131]
	v_lshl_add_u64 v[132:133], s[26:27], 0, v[132:133]
	v_lshl_add_u64 v[128:129], v[128:129], 0, v[160:161]
	v_lshl_add_u64 v[130:131], v[130:131], 0, v[160:161]
	v_lshl_add_u64 v[188:189], v[132:133], 0, v[160:161]
	global_load_dwordx4 v[148:151], v[128:129], off
	global_load_dwordx4 v[144:147], v[128:129], off offset:256
	global_load_dwordx4 v[140:143], v[130:131], off
	global_load_dwordx4 v[136:139], v[130:131], off offset:256
	global_load_dwordx4 v[132:135], v[188:189], off
	s_nop 0
	global_load_dwordx4 v[128:131], v[188:189], off offset:256
	v_and_b32_e32 v189, 64, v206
	v_xor_b32_e32 v188, 16, v206
	v_add_u32_e32 v196, 64, v189
	v_cmp_lt_i32_e32 vcc, v188, v196
	s_nop 1
	v_cndmask_b32_e32 v188, v206, v188, vcc
	v_lshlrev_b32_e32 v207, 2, v188
	s_nop 7
	s_nop 0
	s_waitcnt vmcnt(0)
	v_lshlrev_b32_e32 v190, 16, v182
	v_and_b32_e32 v191, 0xffff0000, v182
	v_lshlrev_b32_e32 v188, 16, v180
	v_and_b32_e32 v189, 0xffff0000, v180
	v_lshlrev_b32_e32 v180, 16, v181
	v_and_b32_e32 v181, 0xffff0000, v181
	v_lshlrev_b32_e32 v182, 16, v183
	v_and_b32_e32 v183, 0xffff0000, v183
	v_pk_add_f32 v[120:121], v[120:121], v[190:191]
	v_pk_add_f32 v[126:127], v[126:127], v[180:181]
	v_pk_add_f32 v[124:125], v[124:125], v[188:189]
	v_pk_add_f32 v[122:123], v[122:123], v[182:183]
	v_mul_f32_e32 v180, v120, v120
	v_mul_f32_e32 v181, v121, v121
	v_lshlrev_b32_e32 v194, 16, v186
	v_and_b32_e32 v195, 0xffff0000, v186
	v_mul_f32_e32 v182, v122, v122
	v_fmac_f32_e32 v180, v124, v124
	v_fmac_f32_e32 v181, v125, v125
	v_lshlrev_b32_e32 v192, 16, v184
	v_and_b32_e32 v193, 0xffff0000, v184
	v_lshlrev_b32_e32 v184, 16, v185
	v_and_b32_e32 v185, 0xffff0000, v185
	v_pk_add_f32 v[112:113], v[112:113], v[194:195]
	v_mul_f32_e32 v183, v123, v123
	v_fmac_f32_e32 v182, v126, v126
	v_add_f32_e32 v180, v180, v181
	v_lshlrev_b32_e32 v186, 16, v187
	v_and_b32_e32 v187, 0xffff0000, v187
	v_pk_add_f32 v[118:119], v[118:119], v[184:185]
	v_pk_add_f32 v[116:117], v[116:117], v[192:193]
	v_mul_f32_e32 v184, v112, v112
	v_fmac_f32_e32 v183, v127, v127
	v_add_f32_e32 v180, v182, v180
	v_pk_add_f32 v[114:115], v[114:115], v[186:187]
	v_mul_f32_e32 v185, v113, v113
	v_fmac_f32_e32 v184, v116, v116
	v_add_f32_e32 v180, v183, v180
	v_mul_f32_e32 v186, v114, v114
	v_fmac_f32_e32 v185, v117, v117
	v_add_f32_e32 v180, v184, v180
	v_mul_f32_e32 v187, v115, v115
	v_fmac_f32_e32 v186, v118, v118
	v_add_f32_e32 v180, v185, v180
	v_add_f32_e32 v180, v186, v180
	v_fmac_f32_e32 v187, v119, v119
	v_add_f32_e32 v180, v187, v180
	ds_bpermute_b32 v181, v207, v180
	v_xor_b32_e32 v182, 32, v206
	v_cmp_lt_i32_e32 vcc, v182, v196
	v_lshlrev_b64 v[188:189], 6, v[178:179]
	s_waitcnt lgkmcnt(0)
	v_add_f32_e32 v180, v180, v181
	v_cndmask_b32_e32 v182, v206, v182, vcc
	v_lshlrev_b32_e32 v208, 2, v182
	ds_bpermute_b32 v181, v208, v180
	s_and_saveexec_b64 s[28:29], s[0:1]
	s_cbranch_execz .LBB0_1515
	s_waitcnt lgkmcnt(0)
	v_add_f32_e32 v182, v180, v181
	v_lshl_add_u64 v[180:181], s[88:89], 0, v[188:189]
	v_lshl_add_u64 v[180:181], s[4:5], 2, v[180:181]
	s_lshl_b32 s8, s40, 2
	v_lshl_add_u64 v[180:181], v[180:181], 0, s[8:9]
	global_store_dword v[180:181], v182, off sc1
